# v45 + residual epilogue address setup and first 8 residual loads hoisted above the half-alignment barrier at K-loop exit
# speedup vs baseline: 1.0016x; 1.0016x over previous
.LBB0_995:
	ds_read_b128 v[146:149], v164
	ds_read_b128 v[150:153], v164 offset:1024
	ds_read_b128 v[154:157], v164 offset:2048
	ds_read_b128 v[158:161], v164 offset:3072
	ds_read_b128 v[168:171], v165
	ds_read_b128 v[172:175], v165 offset:1024
	ds_read_b128 v[176:179], v165 offset:2048
	ds_read_b128 v[180:183], v165 offset:3072
	s_add_u32 s34, s88, 0xfff80080
	s_addc_u32 s35, s89, -1
	s_cmp_eq_u32 s81, 28
	s_cselect_b32 s91, s0, s35
	s_cselect_b32 s90, s1, s34
	s_cselect_b32 s35, s52, s77
	s_cselect_b32 s34, s74, s75
	v_lshl_add_u64 v[218:219], s[88:89], 0, v[138:139]
	s_add_i32 m0, s33, 0xc000
	ds_read_b128 v[184:187], v166
	ds_read_b128 v[188:191], v166 offset:1024
	ds_read_b128 v[192:195], v166 offset:2048
	ds_read_b128 v[196:199], v166 offset:3072
	ds_read_b128 v[200:203], v166 offset:4096
	ds_read_b128 v[204:207], v166 offset:5120
	ds_read_b128 v[208:211], v166 offset:6144
	ds_read_b128 v[212:215], v166 offset:7168
	global_load_lds_dwordx4 v[218:219], off
	v_lshl_add_u64 v[218:219], s[88:89], 0, v[140:141]
	s_add_i32 m0, s33, 0xe000
	s_nop 0
	global_load_lds_dwordx4 v[218:219], off
	s_waitcnt vmcnt(8)
	s_waitcnt lgkmcnt(0)
	s_barrier
	s_setprio 1
	s_waitcnt lgkmcnt(0)
	v_mfma_f32_16x16x32_bf16 v[126:129], v[146:149], v[184:187], v[126:129]
	v_mfma_f32_16x16x32_bf16 v[122:125], v[154:157], v[184:187], v[122:125]
	v_mfma_f32_16x16x32_bf16 v[110:113], v[146:149], v[192:195], v[110:113]
	v_mfma_f32_16x16x32_bf16 v[106:109], v[154:157], v[192:195], v[106:109]
	v_mfma_f32_16x16x32_bf16 v[94:97], v[146:149], v[200:203], v[94:97]
	v_mfma_f32_16x16x32_bf16 v[90:93], v[154:157], v[200:203], v[90:93]
	v_mfma_f32_16x16x32_bf16 v[78:81], v[146:149], v[208:211], v[78:81]
	v_mfma_f32_16x16x32_bf16 v[74:77], v[154:157], v[208:211], v[74:77]
	v_mfma_f32_16x16x32_bf16 v[126:129], v[150:153], v[188:191], v[126:129]
	v_mfma_f32_16x16x32_bf16 v[122:125], v[158:161], v[188:191], v[122:125]
	v_mfma_f32_16x16x32_bf16 v[110:113], v[150:153], v[196:199], v[110:113]
	v_mfma_f32_16x16x32_bf16 v[106:109], v[158:161], v[196:199], v[106:109]
	v_mfma_f32_16x16x32_bf16 v[94:97], v[150:153], v[204:207], v[94:97]
	v_mfma_f32_16x16x32_bf16 v[90:93], v[158:161], v[204:207], v[90:93]
	v_mfma_f32_16x16x32_bf16 v[78:81], v[150:153], v[212:215], v[78:81]
	v_mfma_f32_16x16x32_bf16 v[74:77], v[158:161], v[212:215], v[74:77]
	s_setprio 0
	s_setprio 1
	v_mfma_f32_16x16x32_bf16 v[118:121], v[168:171], v[184:187], v[118:121]
	v_mfma_f32_16x16x32_bf16 v[114:117], v[176:179], v[184:187], v[114:117]
	v_mfma_f32_16x16x32_bf16 v[102:105], v[168:171], v[192:195], v[102:105]
	v_mfma_f32_16x16x32_bf16 v[98:101], v[176:179], v[192:195], v[98:101]
	v_mfma_f32_16x16x32_bf16 v[86:89], v[168:171], v[200:203], v[86:89]
	v_mfma_f32_16x16x32_bf16 v[82:85], v[176:179], v[200:203], v[82:85]
	v_mfma_f32_16x16x32_bf16 v[70:73], v[168:171], v[208:211], v[70:73]
	v_mfma_f32_16x16x32_bf16 v[66:69], v[176:179], v[208:211], v[66:69]
	v_mfma_f32_16x16x32_bf16 v[118:121], v[172:175], v[188:191], v[118:121]
	v_mfma_f32_16x16x32_bf16 v[114:117], v[180:183], v[188:191], v[114:117]
	v_mfma_f32_16x16x32_bf16 v[102:105], v[172:175], v[196:199], v[102:105]
	v_mfma_f32_16x16x32_bf16 v[98:101], v[180:183], v[196:199], v[98:101]
	v_mfma_f32_16x16x32_bf16 v[86:89], v[172:175], v[204:207], v[86:89]
	v_mfma_f32_16x16x32_bf16 v[82:85], v[180:183], v[204:207], v[82:85]
	v_mfma_f32_16x16x32_bf16 v[70:73], v[172:175], v[212:215], v[70:73]
	v_mfma_f32_16x16x32_bf16 v[66:69], v[180:183], v[212:215], v[66:69]
	s_setprio 0
	s_barrier
	s_add_i32 s53, s71, s31
	v_lshl_add_u64 v[218:219], s[34:35], 0, v[132:133]
	s_mov_b32 m0, s53
	ds_read_b128 v[184:187], v166 offset:16384
	ds_read_b128 v[188:191], v166 offset:17408
	ds_read_b128 v[192:195], v166 offset:18432
	ds_read_b128 v[196:199], v166 offset:19456
	ds_read_b128 v[200:203], v166 offset:20480
	ds_read_b128 v[204:207], v166 offset:21504
	ds_read_b128 v[208:211], v166 offset:22528
	ds_read_b128 v[212:215], v166 offset:23552
	global_load_lds_dwordx4 v[218:219], off
	s_add_i32 m0, s53, 0x2000
	s_add_u32 s54, s34, 0x80000
	v_lshl_add_u64 v[220:221], s[34:35], 0, v[136:137]
	s_addc_u32 s55, s35, 0
	s_add_i32 s53, s72, s31
	global_load_lds_dwordx4 v[220:221], off
	v_lshl_add_u64 v[222:223], s[54:55], 0, v[132:133]
	s_mov_b32 m0, s53
	v_lshl_add_u64 v[224:225], s[90:91], 0, v[134:135]
	global_load_lds_dwordx4 v[222:223], off
	v_lshl_add_u64 v[222:223], s[54:55], 0, v[136:137]
	s_add_i32 m0, s53, 0x2000
	s_nop 0
	global_load_lds_dwordx4 v[222:223], off
	v_lshl_add_u64 v[222:223], s[90:91], 0, v[130:131]
	s_mov_b32 m0, s33
	s_nop 0
	global_load_lds_dwordx4 v[222:223], off
	s_mov_b32 m0, s56
	s_nop 0
	global_load_lds_dwordx4 v[224:225], off
	s_waitcnt vmcnt(8)
	s_waitcnt lgkmcnt(0)
	s_barrier
	s_setprio 1
	s_waitcnt lgkmcnt(0)
	v_mfma_f32_16x16x32_bf16 v[62:65], v[146:149], v[184:187], v[62:65]
	v_mfma_f32_16x16x32_bf16 v[58:61], v[154:157], v[184:187], v[58:61]
	v_mfma_f32_16x16x32_bf16 v[46:49], v[146:149], v[192:195], v[46:49]
	v_mfma_f32_16x16x32_bf16 v[42:45], v[154:157], v[192:195], v[42:45]
	v_mfma_f32_16x16x32_bf16 v[30:33], v[146:149], v[200:203], v[30:33]
	v_mfma_f32_16x16x32_bf16 v[26:29], v[154:157], v[200:203], v[26:29]
	v_mfma_f32_16x16x32_bf16 v[14:17], v[146:149], v[208:211], v[14:17]
	v_mfma_f32_16x16x32_bf16 v[10:13], v[154:157], v[208:211], v[10:13]
	v_mfma_f32_16x16x32_bf16 v[62:65], v[150:153], v[188:191], v[62:65]
	v_mfma_f32_16x16x32_bf16 v[58:61], v[158:161], v[188:191], v[58:61]
	v_mfma_f32_16x16x32_bf16 v[46:49], v[150:153], v[196:199], v[46:49]
	v_mfma_f32_16x16x32_bf16 v[42:45], v[158:161], v[196:199], v[42:45]
	v_mfma_f32_16x16x32_bf16 v[30:33], v[150:153], v[204:207], v[30:33]
	v_mfma_f32_16x16x32_bf16 v[26:29], v[158:161], v[204:207], v[26:29]
	v_mfma_f32_16x16x32_bf16 v[14:17], v[150:153], v[212:215], v[14:17]
	v_mfma_f32_16x16x32_bf16 v[10:13], v[158:161], v[212:215], v[10:13]
	s_setprio 0
	s_setprio 1
	v_mfma_f32_16x16x32_bf16 v[54:57], v[168:171], v[184:187], v[54:57]
	v_mfma_f32_16x16x32_bf16 v[50:53], v[176:179], v[184:187], v[50:53]
	v_mfma_f32_16x16x32_bf16 v[38:41], v[168:171], v[192:195], v[38:41]
	v_mfma_f32_16x16x32_bf16 v[34:37], v[176:179], v[192:195], v[34:37]
	v_mfma_f32_16x16x32_bf16 v[22:25], v[168:171], v[200:203], v[22:25]
	v_mfma_f32_16x16x32_bf16 v[18:21], v[176:179], v[200:203], v[18:21]
	v_mfma_f32_16x16x32_bf16 v[6:9], v[168:171], v[208:211], v[6:9]
	v_mfma_f32_16x16x32_bf16 v[2:5], v[176:179], v[208:211], v[2:5]
	v_mfma_f32_16x16x32_bf16 v[54:57], v[172:175], v[188:191], v[54:57]
	v_mfma_f32_16x16x32_bf16 v[50:53], v[180:183], v[188:191], v[50:53]
	v_mfma_f32_16x16x32_bf16 v[38:41], v[172:175], v[196:199], v[38:41]
	v_mfma_f32_16x16x32_bf16 v[34:37], v[180:183], v[196:199], v[34:37]
	v_mfma_f32_16x16x32_bf16 v[22:25], v[172:175], v[204:207], v[22:25]
	v_mfma_f32_16x16x32_bf16 v[18:21], v[180:183], v[204:207], v[18:21]
	v_mfma_f32_16x16x32_bf16 v[6:9], v[172:175], v[212:215], v[6:9]
	v_mfma_f32_16x16x32_bf16 v[2:5], v[180:183], v[212:215], v[2:5]
	s_setprio 0
	s_barrier
	s_add_i32 s53, 0, 0x18000
	s_add_i32 s62, 0, 0x1c000
	v_add_u32_e32 v158, s53, v162
	v_add_u32_e32 v167, 0x19000, v162
	ds_read_b128 v[146:149], v158
	ds_read_b128 v[150:153], v158 offset:1024
	ds_read_b128 v[154:157], v158 offset:2048
	ds_read_b128 v[158:161], v158 offset:3072
	ds_read_b128 v[168:171], v167
	ds_read_b128 v[172:175], v167 offset:1024
	ds_read_b128 v[176:179], v167 offset:2048
	ds_read_b128 v[180:183], v167 offset:3072
	s_add_u32 s54, s90, 0x80000
	s_addc_u32 s55, s91, 0
	s_mov_b32 m0, s57
	v_lshl_add_u64 v[226:227], s[54:55], 0, v[130:131]
	ds_read_b128 v[184:187], v166 offset:32768
	ds_read_b128 v[188:191], v166 offset:33792
	ds_read_b128 v[192:195], v166 offset:34816
	ds_read_b128 v[196:199], v166 offset:35840
	ds_read_b128 v[200:203], v166 offset:36864
	ds_read_b128 v[204:207], v166 offset:37888
	ds_read_b128 v[208:211], v166 offset:38912
	ds_read_b128 v[212:215], v166 offset:39936
	global_load_lds_dwordx4 v[226:227], off
	v_lshl_add_u64 v[226:227], s[54:55], 0, v[134:135]
	s_mov_b32 m0, s58
	s_nop 0
	global_load_lds_dwordx4 v[226:227], off
	s_waitcnt vmcnt(8)
	s_waitcnt lgkmcnt(0)
	s_barrier
	s_setprio 1
	s_waitcnt lgkmcnt(0)
	v_mfma_f32_16x16x32_bf16 v[126:129], v[146:149], v[184:187], v[126:129]
	v_mfma_f32_16x16x32_bf16 v[122:125], v[154:157], v[184:187], v[122:125]
	v_mfma_f32_16x16x32_bf16 v[110:113], v[146:149], v[192:195], v[110:113]
	v_mfma_f32_16x16x32_bf16 v[106:109], v[154:157], v[192:195], v[106:109]
	v_mfma_f32_16x16x32_bf16 v[94:97], v[146:149], v[200:203], v[94:97]
	v_mfma_f32_16x16x32_bf16 v[90:93], v[154:157], v[200:203], v[90:93]
	v_mfma_f32_16x16x32_bf16 v[78:81], v[146:149], v[208:211], v[78:81]
	v_mfma_f32_16x16x32_bf16 v[74:77], v[154:157], v[208:211], v[74:77]
	v_mfma_f32_16x16x32_bf16 v[126:129], v[150:153], v[188:191], v[126:129]
	v_mfma_f32_16x16x32_bf16 v[122:125], v[158:161], v[188:191], v[122:125]
	v_mfma_f32_16x16x32_bf16 v[110:113], v[150:153], v[196:199], v[110:113]
	v_mfma_f32_16x16x32_bf16 v[106:109], v[158:161], v[196:199], v[106:109]
	v_mfma_f32_16x16x32_bf16 v[94:97], v[150:153], v[204:207], v[94:97]
	v_mfma_f32_16x16x32_bf16 v[90:93], v[158:161], v[204:207], v[90:93]
	v_mfma_f32_16x16x32_bf16 v[78:81], v[150:153], v[212:215], v[78:81]
	v_mfma_f32_16x16x32_bf16 v[74:77], v[158:161], v[212:215], v[74:77]
	s_setprio 0
	s_setprio 1
	v_mfma_f32_16x16x32_bf16 v[118:121], v[168:171], v[184:187], v[118:121]
	v_mfma_f32_16x16x32_bf16 v[114:117], v[176:179], v[184:187], v[114:117]
	v_mfma_f32_16x16x32_bf16 v[102:105], v[168:171], v[192:195], v[102:105]
	v_mfma_f32_16x16x32_bf16 v[98:101], v[176:179], v[192:195], v[98:101]
	v_mfma_f32_16x16x32_bf16 v[86:89], v[168:171], v[200:203], v[86:89]
	v_mfma_f32_16x16x32_bf16 v[82:85], v[176:179], v[200:203], v[82:85]
	v_mfma_f32_16x16x32_bf16 v[70:73], v[168:171], v[208:211], v[70:73]
	v_mfma_f32_16x16x32_bf16 v[66:69], v[176:179], v[208:211], v[66:69]
	v_mfma_f32_16x16x32_bf16 v[118:121], v[172:175], v[188:191], v[118:121]
	v_mfma_f32_16x16x32_bf16 v[114:117], v[180:183], v[188:191], v[114:117]
	v_mfma_f32_16x16x32_bf16 v[102:105], v[172:175], v[196:199], v[102:105]
	v_mfma_f32_16x16x32_bf16 v[98:101], v[180:183], v[196:199], v[98:101]
	v_mfma_f32_16x16x32_bf16 v[86:89], v[172:175], v[204:207], v[86:89]
	v_mfma_f32_16x16x32_bf16 v[82:85], v[180:183], v[204:207], v[82:85]
	v_mfma_f32_16x16x32_bf16 v[70:73], v[172:175], v[212:215], v[70:73]
	v_mfma_f32_16x16x32_bf16 v[66:69], v[180:183], v[212:215], v[66:69]
	s_setprio 0
	s_barrier
	s_add_i32 s53, s53, s31
	v_lshl_add_u64 v[218:219], v[218:219], 0, s[8:9]
	s_mov_b32 m0, s53
	ds_read_b128 v[184:187], v166 offset:49152
	ds_read_b128 v[188:191], v166 offset:50176
	ds_read_b128 v[192:195], v166 offset:51200
	ds_read_b128 v[196:199], v166 offset:52224
	ds_read_b128 v[200:203], v166 offset:53248
	ds_read_b128 v[204:207], v166 offset:54272
	ds_read_b128 v[208:211], v166 offset:55296
	ds_read_b128 v[212:215], v166 offset:56320
	global_load_lds_dwordx4 v[218:219], off
	s_add_i32 m0, s53, 0x2000
	s_add_u32 s34, s34, 0x80080
	v_lshl_add_u64 v[218:219], v[220:221], 0, s[8:9]
	s_addc_u32 s35, s35, 0
	s_add_i32 s53, s62, s31
	global_load_lds_dwordx4 v[218:219], off
	v_lshl_add_u64 v[218:219], s[34:35], 0, v[132:133]
	s_mov_b32 m0, s53
	s_nop 0
	global_load_lds_dwordx4 v[218:219], off
	v_lshl_add_u64 v[218:219], s[34:35], 0, v[136:137]
	s_add_i32 m0, s53, 0x2000
	s_nop 0
	global_load_lds_dwordx4 v[218:219], off
	v_lshl_add_u64 v[218:219], v[222:223], 0, s[8:9]
	s_mov_b32 m0, s60
	s_nop 0
	global_load_lds_dwordx4 v[218:219], off
	v_lshl_add_u64 v[218:219], v[224:225], 0, s[8:9]
	s_mov_b32 m0, s61
	s_nop 0
	global_load_lds_dwordx4 v[218:219], off
	s_waitcnt vmcnt(8)
	s_waitcnt lgkmcnt(0)
	s_barrier
	s_setprio 1
	s_waitcnt lgkmcnt(0)
	v_mfma_f32_16x16x32_bf16 v[62:65], v[146:149], v[184:187], v[62:65]
	v_mfma_f32_16x16x32_bf16 v[58:61], v[154:157], v[184:187], v[58:61]
	v_mfma_f32_16x16x32_bf16 v[46:49], v[146:149], v[192:195], v[46:49]
	v_mfma_f32_16x16x32_bf16 v[42:45], v[154:157], v[192:195], v[42:45]
	v_mfma_f32_16x16x32_bf16 v[30:33], v[146:149], v[200:203], v[30:33]
	v_mfma_f32_16x16x32_bf16 v[26:29], v[154:157], v[200:203], v[26:29]
	v_mfma_f32_16x16x32_bf16 v[14:17], v[146:149], v[208:211], v[14:17]
	v_mfma_f32_16x16x32_bf16 v[10:13], v[154:157], v[208:211], v[10:13]
	v_mfma_f32_16x16x32_bf16 v[62:65], v[150:153], v[188:191], v[62:65]
	v_mfma_f32_16x16x32_bf16 v[58:61], v[158:161], v[188:191], v[58:61]
	v_mfma_f32_16x16x32_bf16 v[46:49], v[150:153], v[196:199], v[46:49]
	v_mfma_f32_16x16x32_bf16 v[42:45], v[158:161], v[196:199], v[42:45]
	v_mfma_f32_16x16x32_bf16 v[30:33], v[150:153], v[204:207], v[30:33]
	v_mfma_f32_16x16x32_bf16 v[26:29], v[158:161], v[204:207], v[26:29]
	v_mfma_f32_16x16x32_bf16 v[14:17], v[150:153], v[212:215], v[14:17]
	v_mfma_f32_16x16x32_bf16 v[10:13], v[158:161], v[212:215], v[10:13]
	s_setprio 0
	s_setprio 1
	v_mfma_f32_16x16x32_bf16 v[54:57], v[168:171], v[184:187], v[54:57]
	v_mfma_f32_16x16x32_bf16 v[50:53], v[176:179], v[184:187], v[50:53]
	v_mfma_f32_16x16x32_bf16 v[38:41], v[168:171], v[192:195], v[38:41]
	v_mfma_f32_16x16x32_bf16 v[34:37], v[176:179], v[192:195], v[34:37]
	v_mfma_f32_16x16x32_bf16 v[22:25], v[168:171], v[200:203], v[22:25]
	v_mfma_f32_16x16x32_bf16 v[18:21], v[176:179], v[200:203], v[18:21]
	v_mfma_f32_16x16x32_bf16 v[6:9], v[168:171], v[208:211], v[6:9]
	v_mfma_f32_16x16x32_bf16 v[2:5], v[176:179], v[208:211], v[2:5]
	v_mfma_f32_16x16x32_bf16 v[54:57], v[172:175], v[188:191], v[54:57]
	v_mfma_f32_16x16x32_bf16 v[50:53], v[180:183], v[188:191], v[50:53]
	v_mfma_f32_16x16x32_bf16 v[38:41], v[172:175], v[196:199], v[38:41]
	v_mfma_f32_16x16x32_bf16 v[34:37], v[180:183], v[196:199], v[34:37]
	v_mfma_f32_16x16x32_bf16 v[22:25], v[172:175], v[204:207], v[22:25]
	v_mfma_f32_16x16x32_bf16 v[18:21], v[180:183], v[204:207], v[18:21]
	v_mfma_f32_16x16x32_bf16 v[6:9], v[172:175], v[212:215], v[6:9]
	v_mfma_f32_16x16x32_bf16 v[2:5], v[180:183], v[212:215], v[2:5]
	s_setprio 0
	s_barrier
	s_add_i32 s81, s81, 2
	s_add_u32 s88, s88, 0x100
	s_addc_u32 s89, s89, 0
	s_add_u32 s75, s75, 0x100
	s_addc_u32 s77, s77, 0
	s_cmp_gt_u32 s81, 29
	s_cbranch_scc0 .LBB0_995
	v_lshl_add_u32 v146, s76, 8, v1
	v_lshl_or_b32 v148, s73, 8, v163
	v_ashrrev_i32_e32 v147, 31, v146
	v_ashrrev_i32_e32 v149, 31, v148
	v_lshlrev_b64 v[150:151], 12, v[146:147]
	v_lshl_add_u64 v[150:151], s[64:65], 0, v[150:151]
	v_lshlrev_b64 v[148:149], 1, v[148:149]
	v_lshl_add_u64 v[150:151], v[150:151], 0, v[148:149]
	v_mov_b32_e32 v245, 0
	v_mov_b32_e32 v244, 0x10000
	v_lshl_add_u64 v[230:231], v[244:245], 0, v[150:151]
	v_mov_b32_e32 v244, 0x20000
	v_lshl_add_u64 v[232:233], v[244:245], 0, v[150:151]
	v_mov_b32_e32 v244, 0x30000
	v_lshl_add_u64 v[234:235], v[244:245], 0, v[150:151]
	v_mov_b32_e32 v244, 0x80000
	v_lshl_add_u64 v[236:237], v[244:245], 0, v[150:151]
	v_mov_b32_e32 v244, 0x90000
	v_lshl_add_u64 v[238:239], v[244:245], 0, v[150:151]
	v_mov_b32_e32 v244, 0xa0000
	v_lshl_add_u64 v[240:241], v[244:245], 0, v[150:151]
	v_mov_b32_e32 v244, 0xb0000
	v_lshl_add_u64 v[242:243], v[244:245], 0, v[150:151]
	global_load_dwordx4 v[146:149], v[150:151], off
	global_load_dwordx4 v[152:155], v[150:151], off offset:64
	global_load_dwordx4 v[156:159], v[230:231], off
	global_load_dwordx4 v[168:171], v[230:231], off offset:64
	global_load_dwordx4 v[172:175], v[232:233], off
	global_load_dwordx4 v[176:179], v[232:233], off offset:64
	global_load_dwordx4 v[180:183], v[234:235], off
	global_load_dwordx4 v[184:187], v[234:235], off offset:64
	s_and_b64 vcc, exec, s[78:79]
	s_cbranch_vccz .LBB0_998
	s_barrier
.LBB0_998:
	s_waitcnt vmcnt(7)
	v_cvt_f32_f16_e32 v160, v146
	v_cvt_f32_f16_sdwa v161, v146 dst_sel:DWORD dst_unused:UNUSED_PAD src0_sel:WORD_1
	v_cvt_f32_f16_e32 v188, v147
	v_cvt_f32_f16_sdwa v189, v147 dst_sel:DWORD dst_unused:UNUSED_PAD src0_sel:WORD_1
	v_cvt_f32_f16_e32 v190, v148
	v_cvt_f32_f16_sdwa v191, v148 dst_sel:DWORD dst_unused:UNUSED_PAD src0_sel:WORD_1
	v_cvt_f32_f16_e32 v228, v149
	v_cvt_f32_f16_sdwa v229, v149 dst_sel:DWORD dst_unused:UNUSED_PAD src0_sel:WORD_1
	global_load_dwordx4 v[146:149], v[236:237], off
	v_pk_add_f32 v[126:127], v[160:161], v[126:127]
	v_pk_add_f32 v[128:129], v[188:189], v[128:129]
	v_pk_add_f32 v[122:123], v[190:191], v[122:123]
	v_pk_add_f32 v[124:125], v[228:229], v[124:125]
	v_cvt_pk_f16_f32 v125, v124, v125
	v_cvt_pk_f16_f32 v124, v122, v123
	v_cvt_pk_f16_f32 v123, v128, v129
	v_cvt_pk_f16_f32 v122, v126, v127
	global_store_dwordx4 v[150:151], v[122:125], off
	s_waitcnt vmcnt(8)
	v_cvt_f32_f16_e32 v160, v152
	v_cvt_f32_f16_sdwa v161, v152 dst_sel:DWORD dst_unused:UNUSED_PAD src0_sel:WORD_1
	v_cvt_f32_f16_e32 v188, v153
	v_cvt_f32_f16_sdwa v189, v153 dst_sel:DWORD dst_unused:UNUSED_PAD src0_sel:WORD_1
	v_cvt_f32_f16_e32 v190, v154
	v_cvt_f32_f16_sdwa v191, v154 dst_sel:DWORD dst_unused:UNUSED_PAD src0_sel:WORD_1
	v_cvt_f32_f16_e32 v228, v155
	v_cvt_f32_f16_sdwa v229, v155 dst_sel:DWORD dst_unused:UNUSED_PAD src0_sel:WORD_1
	global_load_dwordx4 v[152:155], v[236:237], off offset:64
	v_pk_add_f32 v[118:119], v[160:161], v[118:119]
	v_pk_add_f32 v[120:121], v[188:189], v[120:121]
	v_pk_add_f32 v[114:115], v[190:191], v[114:115]
	v_pk_add_f32 v[116:117], v[228:229], v[116:117]
	v_cvt_pk_f16_f32 v117, v116, v117
	v_cvt_pk_f16_f32 v116, v114, v115
	v_cvt_pk_f16_f32 v115, v120, v121
	v_cvt_pk_f16_f32 v114, v118, v119
	global_store_dwordx4 v[150:151], v[114:117], off offset:64
	s_waitcnt vmcnt(9)
	v_cvt_f32_f16_e32 v160, v156
	v_cvt_f32_f16_sdwa v161, v156 dst_sel:DWORD dst_unused:UNUSED_PAD src0_sel:WORD_1
	v_cvt_f32_f16_e32 v188, v157
	v_cvt_f32_f16_sdwa v189, v157 dst_sel:DWORD dst_unused:UNUSED_PAD src0_sel:WORD_1
	v_cvt_f32_f16_e32 v190, v158
	v_cvt_f32_f16_sdwa v191, v158 dst_sel:DWORD dst_unused:UNUSED_PAD src0_sel:WORD_1
	v_cvt_f32_f16_e32 v228, v159
	v_cvt_f32_f16_sdwa v229, v159 dst_sel:DWORD dst_unused:UNUSED_PAD src0_sel:WORD_1
	global_load_dwordx4 v[156:159], v[238:239], off
	v_pk_add_f32 v[110:111], v[160:161], v[110:111]
	v_pk_add_f32 v[112:113], v[188:189], v[112:113]
	v_pk_add_f32 v[106:107], v[190:191], v[106:107]
	v_pk_add_f32 v[108:109], v[228:229], v[108:109]
	v_cvt_pk_f16_f32 v109, v108, v109
	v_cvt_pk_f16_f32 v108, v106, v107
	v_cvt_pk_f16_f32 v107, v112, v113
	v_cvt_pk_f16_f32 v106, v110, v111
	global_store_dwordx4 v[230:231], v[106:109], off
	s_waitcnt vmcnt(10)
	v_cvt_f32_f16_e32 v160, v168
	v_cvt_f32_f16_sdwa v161, v168 dst_sel:DWORD dst_unused:UNUSED_PAD src0_sel:WORD_1
	v_cvt_f32_f16_e32 v188, v169
	v_cvt_f32_f16_sdwa v189, v169 dst_sel:DWORD dst_unused:UNUSED_PAD src0_sel:WORD_1
	v_cvt_f32_f16_e32 v190, v170
	v_cvt_f32_f16_sdwa v191, v170 dst_sel:DWORD dst_unused:UNUSED_PAD src0_sel:WORD_1
	v_cvt_f32_f16_e32 v228, v171
	v_cvt_f32_f16_sdwa v229, v171 dst_sel:DWORD dst_unused:UNUSED_PAD src0_sel:WORD_1
	global_load_dwordx4 v[168:171], v[238:239], off offset:64
	v_pk_add_f32 v[102:103], v[160:161], v[102:103]
	v_pk_add_f32 v[104:105], v[188:189], v[104:105]
	v_pk_add_f32 v[98:99], v[190:191], v[98:99]
	v_pk_add_f32 v[100:101], v[228:229], v[100:101]
	v_cvt_pk_f16_f32 v101, v100, v101
	v_cvt_pk_f16_f32 v100, v98, v99
	v_cvt_pk_f16_f32 v99, v104, v105
	v_cvt_pk_f16_f32 v98, v102, v103
	global_store_dwordx4 v[230:231], v[98:101], off offset:64
	s_waitcnt vmcnt(11)
	v_cvt_f32_f16_e32 v160, v172
	v_cvt_f32_f16_sdwa v161, v172 dst_sel:DWORD dst_unused:UNUSED_PAD src0_sel:WORD_1
	v_cvt_f32_f16_e32 v188, v173
	v_cvt_f32_f16_sdwa v189, v173 dst_sel:DWORD dst_unused:UNUSED_PAD src0_sel:WORD_1
	v_cvt_f32_f16_e32 v190, v174
	v_cvt_f32_f16_sdwa v191, v174 dst_sel:DWORD dst_unused:UNUSED_PAD src0_sel:WORD_1
	v_cvt_f32_f16_e32 v228, v175
	v_cvt_f32_f16_sdwa v229, v175 dst_sel:DWORD dst_unused:UNUSED_PAD src0_sel:WORD_1
	global_load_dwordx4 v[172:175], v[240:241], off
	v_pk_add_f32 v[94:95], v[160:161], v[94:95]
	v_pk_add_f32 v[96:97], v[188:189], v[96:97]
	v_pk_add_f32 v[90:91], v[190:191], v[90:91]
	v_pk_add_f32 v[92:93], v[228:229], v[92:93]
	v_cvt_pk_f16_f32 v93, v92, v93
	v_cvt_pk_f16_f32 v92, v90, v91
	v_cvt_pk_f16_f32 v91, v96, v97
	v_cvt_pk_f16_f32 v90, v94, v95
	global_store_dwordx4 v[232:233], v[90:93], off
	s_waitcnt vmcnt(12)
	v_cvt_f32_f16_e32 v160, v176
	v_cvt_f32_f16_sdwa v161, v176 dst_sel:DWORD dst_unused:UNUSED_PAD src0_sel:WORD_1
	v_cvt_f32_f16_e32 v188, v177
	v_cvt_f32_f16_sdwa v189, v177 dst_sel:DWORD dst_unused:UNUSED_PAD src0_sel:WORD_1
	v_cvt_f32_f16_e32 v190, v178
	v_cvt_f32_f16_sdwa v191, v178 dst_sel:DWORD dst_unused:UNUSED_PAD src0_sel:WORD_1
	v_cvt_f32_f16_e32 v228, v179
	v_cvt_f32_f16_sdwa v229, v179 dst_sel:DWORD dst_unused:UNUSED_PAD src0_sel:WORD_1
	global_load_dwordx4 v[176:179], v[240:241], off offset:64
	v_pk_add_f32 v[86:87], v[160:161], v[86:87]
	v_pk_add_f32 v[88:89], v[188:189], v[88:89]
	v_pk_add_f32 v[82:83], v[190:191], v[82:83]
	v_pk_add_f32 v[84:85], v[228:229], v[84:85]
	v_cvt_pk_f16_f32 v85, v84, v85
	v_cvt_pk_f16_f32 v84, v82, v83
	v_cvt_pk_f16_f32 v83, v88, v89
	v_cvt_pk_f16_f32 v82, v86, v87
	global_store_dwordx4 v[232:233], v[82:85], off offset:64
	s_waitcnt vmcnt(13)
	v_cvt_f32_f16_e32 v160, v180
	v_cvt_f32_f16_sdwa v161, v180 dst_sel:DWORD dst_unused:UNUSED_PAD src0_sel:WORD_1
	v_cvt_f32_f16_e32 v188, v181
	v_cvt_f32_f16_sdwa v189, v181 dst_sel:DWORD dst_unused:UNUSED_PAD src0_sel:WORD_1
	v_cvt_f32_f16_e32 v190, v182
	v_cvt_f32_f16_sdwa v191, v182 dst_sel:DWORD dst_unused:UNUSED_PAD src0_sel:WORD_1
	v_cvt_f32_f16_e32 v228, v183
	v_cvt_f32_f16_sdwa v229, v183 dst_sel:DWORD dst_unused:UNUSED_PAD src0_sel:WORD_1
	global_load_dwordx4 v[180:183], v[242:243], off
	v_pk_add_f32 v[78:79], v[160:161], v[78:79]
	v_pk_add_f32 v[80:81], v[188:189], v[80:81]
	v_pk_add_f32 v[74:75], v[190:191], v[74:75]
	v_pk_add_f32 v[76:77], v[228:229], v[76:77]
	v_cvt_pk_f16_f32 v77, v76, v77
	v_cvt_pk_f16_f32 v76, v74, v75
	v_cvt_pk_f16_f32 v75, v80, v81
	v_cvt_pk_f16_f32 v74, v78, v79
	global_store_dwordx4 v[234:235], v[74:77], off
	s_waitcnt vmcnt(14)
	v_cvt_f32_f16_e32 v160, v184
	v_cvt_f32_f16_sdwa v161, v184 dst_sel:DWORD dst_unused:UNUSED_PAD src0_sel:WORD_1
	v_cvt_f32_f16_e32 v188, v185
	v_cvt_f32_f16_sdwa v189, v185 dst_sel:DWORD dst_unused:UNUSED_PAD src0_sel:WORD_1
	v_cvt_f32_f16_e32 v190, v186
	v_cvt_f32_f16_sdwa v191, v186 dst_sel:DWORD dst_unused:UNUSED_PAD src0_sel:WORD_1
	v_cvt_f32_f16_e32 v228, v187
	v_cvt_f32_f16_sdwa v229, v187 dst_sel:DWORD dst_unused:UNUSED_PAD src0_sel:WORD_1
	global_load_dwordx4 v[184:187], v[242:243], off offset:64
	v_pk_add_f32 v[70:71], v[160:161], v[70:71]
	v_pk_add_f32 v[72:73], v[188:189], v[72:73]
	v_pk_add_f32 v[66:67], v[190:191], v[66:67]
	v_pk_add_f32 v[68:69], v[228:229], v[68:69]
	v_cvt_pk_f16_f32 v69, v68, v69
	v_cvt_pk_f16_f32 v68, v66, v67
	v_cvt_pk_f16_f32 v67, v72, v73
	v_cvt_pk_f16_f32 v66, v70, v71
	global_store_dwordx4 v[234:235], v[66:69], off offset:64
	s_waitcnt vmcnt(15)
	v_cvt_f32_f16_e32 v160, v146
	v_cvt_f32_f16_sdwa v161, v146 dst_sel:DWORD dst_unused:UNUSED_PAD src0_sel:WORD_1
	v_cvt_f32_f16_e32 v188, v147
	v_cvt_f32_f16_sdwa v189, v147 dst_sel:DWORD dst_unused:UNUSED_PAD src0_sel:WORD_1
	v_cvt_f32_f16_e32 v190, v148
	v_cvt_f32_f16_sdwa v191, v148 dst_sel:DWORD dst_unused:UNUSED_PAD src0_sel:WORD_1
	v_cvt_f32_f16_e32 v228, v149
	v_cvt_f32_f16_sdwa v229, v149 dst_sel:DWORD dst_unused:UNUSED_PAD src0_sel:WORD_1
	v_pk_add_f32 v[62:63], v[160:161], v[62:63]
	v_pk_add_f32 v[64:65], v[188:189], v[64:65]
	v_pk_add_f32 v[58:59], v[190:191], v[58:59]
	v_pk_add_f32 v[60:61], v[228:229], v[60:61]
	v_cvt_pk_f16_f32 v61, v60, v61
	v_cvt_pk_f16_f32 v60, v58, v59
	v_cvt_pk_f16_f32 v59, v64, v65
	v_cvt_pk_f16_f32 v58, v62, v63
	global_store_dwordx4 v[236:237], v[58:61], off
	s_waitcnt vmcnt(14)
	v_cvt_f32_f16_e32 v160, v152
	v_cvt_f32_f16_sdwa v161, v152 dst_sel:DWORD dst_unused:UNUSED_PAD src0_sel:WORD_1
	v_cvt_f32_f16_e32 v188, v153
	v_cvt_f32_f16_sdwa v189, v153 dst_sel:DWORD dst_unused:UNUSED_PAD src0_sel:WORD_1
	v_cvt_f32_f16_e32 v190, v154
	v_cvt_f32_f16_sdwa v191, v154 dst_sel:DWORD dst_unused:UNUSED_PAD src0_sel:WORD_1
	v_cvt_f32_f16_e32 v228, v155
	v_cvt_f32_f16_sdwa v229, v155 dst_sel:DWORD dst_unused:UNUSED_PAD src0_sel:WORD_1
	v_pk_add_f32 v[54:55], v[160:161], v[54:55]
	v_pk_add_f32 v[56:57], v[188:189], v[56:57]
	v_pk_add_f32 v[50:51], v[190:191], v[50:51]
	v_pk_add_f32 v[52:53], v[228:229], v[52:53]
	v_cvt_pk_f16_f32 v53, v52, v53
	v_cvt_pk_f16_f32 v52, v50, v51
	v_cvt_pk_f16_f32 v51, v56, v57
	v_cvt_pk_f16_f32 v50, v54, v55
	global_store_dwordx4 v[236:237], v[50:53], off offset:64
	s_waitcnt vmcnt(13)
	v_cvt_f32_f16_e32 v160, v156
	v_cvt_f32_f16_sdwa v161, v156 dst_sel:DWORD dst_unused:UNUSED_PAD src0_sel:WORD_1
	v_cvt_f32_f16_e32 v188, v157
	v_cvt_f32_f16_sdwa v189, v157 dst_sel:DWORD dst_unused:UNUSED_PAD src0_sel:WORD_1
	v_cvt_f32_f16_e32 v190, v158
	v_cvt_f32_f16_sdwa v191, v158 dst_sel:DWORD dst_unused:UNUSED_PAD src0_sel:WORD_1
	v_cvt_f32_f16_e32 v228, v159
	v_cvt_f32_f16_sdwa v229, v159 dst_sel:DWORD dst_unused:UNUSED_PAD src0_sel:WORD_1
	v_pk_add_f32 v[46:47], v[160:161], v[46:47]
	v_pk_add_f32 v[48:49], v[188:189], v[48:49]
	v_pk_add_f32 v[42:43], v[190:191], v[42:43]
	v_pk_add_f32 v[44:45], v[228:229], v[44:45]
	v_cvt_pk_f16_f32 v45, v44, v45
	v_cvt_pk_f16_f32 v44, v42, v43
	v_cvt_pk_f16_f32 v43, v48, v49
	v_cvt_pk_f16_f32 v42, v46, v47
	global_store_dwordx4 v[238:239], v[42:45], off
	s_waitcnt vmcnt(12)
	v_cvt_f32_f16_e32 v160, v168
	v_cvt_f32_f16_sdwa v161, v168 dst_sel:DWORD dst_unused:UNUSED_PAD src0_sel:WORD_1
	v_cvt_f32_f16_e32 v188, v169
	v_cvt_f32_f16_sdwa v189, v169 dst_sel:DWORD dst_unused:UNUSED_PAD src0_sel:WORD_1
	v_cvt_f32_f16_e32 v190, v170
	v_cvt_f32_f16_sdwa v191, v170 dst_sel:DWORD dst_unused:UNUSED_PAD src0_sel:WORD_1
	v_cvt_f32_f16_e32 v228, v171
	v_cvt_f32_f16_sdwa v229, v171 dst_sel:DWORD dst_unused:UNUSED_PAD src0_sel:WORD_1
	v_pk_add_f32 v[38:39], v[160:161], v[38:39]
	v_pk_add_f32 v[40:41], v[188:189], v[40:41]
	v_pk_add_f32 v[34:35], v[190:191], v[34:35]
	v_pk_add_f32 v[36:37], v[228:229], v[36:37]
	v_cvt_pk_f16_f32 v37, v36, v37
	v_cvt_pk_f16_f32 v36, v34, v35
	v_cvt_pk_f16_f32 v35, v40, v41
	v_cvt_pk_f16_f32 v34, v38, v39
	global_store_dwordx4 v[238:239], v[34:37], off offset:64
	s_waitcnt vmcnt(11)
	v_cvt_f32_f16_e32 v160, v172
	v_cvt_f32_f16_sdwa v161, v172 dst_sel:DWORD dst_unused:UNUSED_PAD src0_sel:WORD_1
	v_cvt_f32_f16_e32 v188, v173
	v_cvt_f32_f16_sdwa v189, v173 dst_sel:DWORD dst_unused:UNUSED_PAD src0_sel:WORD_1
	v_cvt_f32_f16_e32 v190, v174
	v_cvt_f32_f16_sdwa v191, v174 dst_sel:DWORD dst_unused:UNUSED_PAD src0_sel:WORD_1
	v_cvt_f32_f16_e32 v228, v175
	v_cvt_f32_f16_sdwa v229, v175 dst_sel:DWORD dst_unused:UNUSED_PAD src0_sel:WORD_1
	v_pk_add_f32 v[30:31], v[160:161], v[30:31]
	v_pk_add_f32 v[32:33], v[188:189], v[32:33]
	v_pk_add_f32 v[26:27], v[190:191], v[26:27]
	v_pk_add_f32 v[28:29], v[228:229], v[28:29]
	v_cvt_pk_f16_f32 v29, v28, v29
	v_cvt_pk_f16_f32 v28, v26, v27
	v_cvt_pk_f16_f32 v27, v32, v33
	v_cvt_pk_f16_f32 v26, v30, v31
	global_store_dwordx4 v[240:241], v[26:29], off
	s_waitcnt vmcnt(10)
	v_cvt_f32_f16_e32 v160, v176
	v_cvt_f32_f16_sdwa v161, v176 dst_sel:DWORD dst_unused:UNUSED_PAD src0_sel:WORD_1
	v_cvt_f32_f16_e32 v188, v177
	v_cvt_f32_f16_sdwa v189, v177 dst_sel:DWORD dst_unused:UNUSED_PAD src0_sel:WORD_1
	v_cvt_f32_f16_e32 v190, v178
	v_cvt_f32_f16_sdwa v191, v178 dst_sel:DWORD dst_unused:UNUSED_PAD src0_sel:WORD_1
	v_cvt_f32_f16_e32 v228, v179
	v_cvt_f32_f16_sdwa v229, v179 dst_sel:DWORD dst_unused:UNUSED_PAD src0_sel:WORD_1
	v_pk_add_f32 v[22:23], v[160:161], v[22:23]
	v_pk_add_f32 v[24:25], v[188:189], v[24:25]
	v_pk_add_f32 v[18:19], v[190:191], v[18:19]
	v_pk_add_f32 v[20:21], v[228:229], v[20:21]
	v_cvt_pk_f16_f32 v21, v20, v21
	v_cvt_pk_f16_f32 v20, v18, v19
	v_cvt_pk_f16_f32 v19, v24, v25
	v_cvt_pk_f16_f32 v18, v22, v23
	global_store_dwordx4 v[240:241], v[18:21], off offset:64
	s_waitcnt vmcnt(9)
	v_cvt_f32_f16_e32 v160, v180
	v_cvt_f32_f16_sdwa v161, v180 dst_sel:DWORD dst_unused:UNUSED_PAD src0_sel:WORD_1
	v_cvt_f32_f16_e32 v188, v181
	v_cvt_f32_f16_sdwa v189, v181 dst_sel:DWORD dst_unused:UNUSED_PAD src0_sel:WORD_1
	v_cvt_f32_f16_e32 v190, v182
	v_cvt_f32_f16_sdwa v191, v182 dst_sel:DWORD dst_unused:UNUSED_PAD src0_sel:WORD_1
	v_cvt_f32_f16_e32 v228, v183
	v_cvt_f32_f16_sdwa v229, v183 dst_sel:DWORD dst_unused:UNUSED_PAD src0_sel:WORD_1
	v_pk_add_f32 v[14:15], v[160:161], v[14:15]
	v_pk_add_f32 v[16:17], v[188:189], v[16:17]
	v_pk_add_f32 v[10:11], v[190:191], v[10:11]
	v_pk_add_f32 v[12:13], v[228:229], v[12:13]
	v_cvt_pk_f16_f32 v13, v12, v13
	v_cvt_pk_f16_f32 v12, v10, v11
	v_cvt_pk_f16_f32 v11, v16, v17
	v_cvt_pk_f16_f32 v10, v14, v15
	global_store_dwordx4 v[242:243], v[10:13], off
	s_waitcnt vmcnt(8)
	v_cvt_f32_f16_e32 v160, v184
	v_cvt_f32_f16_sdwa v161, v184 dst_sel:DWORD dst_unused:UNUSED_PAD src0_sel:WORD_1
	v_cvt_f32_f16_e32 v188, v185
	v_cvt_f32_f16_sdwa v189, v185 dst_sel:DWORD dst_unused:UNUSED_PAD src0_sel:WORD_1
	v_cvt_f32_f16_e32 v190, v186
	v_cvt_f32_f16_sdwa v191, v186 dst_sel:DWORD dst_unused:UNUSED_PAD src0_sel:WORD_1
	v_cvt_f32_f16_e32 v228, v187
	v_cvt_f32_f16_sdwa v229, v187 dst_sel:DWORD dst_unused:UNUSED_PAD src0_sel:WORD_1
	v_pk_add_f32 v[6:7], v[160:161], v[6:7]
	v_pk_add_f32 v[8:9], v[188:189], v[8:9]
	v_pk_add_f32 v[2:3], v[190:191], v[2:3]
	v_pk_add_f32 v[4:5], v[228:229], v[4:5]
	v_cvt_pk_f16_f32 v5, v4, v5
	v_cvt_pk_f16_f32 v4, v2, v3
	v_cvt_pk_f16_f32 v3, v8, v9
	v_cvt_pk_f16_f32 v2, v6, v7
	global_store_dwordx4 v[242:243], v[2:5], off offset:64
	s_mov_b64 s[0:1], -1
	s_andn2_b64 vcc, exec, s[2:3]
	s_cbranch_vccnz .LBB0_987
	s_andn2_b64 vcc, exec, s[6:7]
	s_cbranch_vccnz .LBB0_986
	s_barrier
	s_branch .LBB0_986

.LBB0_1237:
	ds_read_b128 v[146:149], v164
	ds_read_b128 v[150:153], v164 offset:1024
	ds_read_b128 v[154:157], v164 offset:2048
	ds_read_b128 v[158:161], v164 offset:3072
	ds_read_b128 v[168:171], v165
	ds_read_b128 v[172:175], v165 offset:1024
	ds_read_b128 v[176:179], v165 offset:2048
	ds_read_b128 v[180:183], v165 offset:3072
	s_add_u32 s34, s76, 0xffea0080
	s_addc_u32 s35, s77, -1
	s_cmpk_eq_i32 s52, 0x54
	s_cselect_b32 s85, s5, s35
	s_cselect_b32 s84, s4, s34
	s_cselect_b32 s35, s83, s1
	s_cselect_b32 s34, s82, s0
	v_lshl_add_u64 v[218:219], s[76:77], 0, v[138:139]
	s_add_i32 m0, s33, 0xc000
	ds_read_b128 v[184:187], v166
	ds_read_b128 v[188:191], v166 offset:1024
	ds_read_b128 v[192:195], v166 offset:2048
	ds_read_b128 v[196:199], v166 offset:3072
	ds_read_b128 v[200:203], v166 offset:4096
	ds_read_b128 v[204:207], v166 offset:5120
	ds_read_b128 v[208:211], v166 offset:6144
	ds_read_b128 v[212:215], v166 offset:7168
	global_load_lds_dwordx4 v[218:219], off
	v_lshl_add_u64 v[218:219], s[76:77], 0, v[140:141]
	s_add_i32 m0, s33, 0xe000
	s_nop 0
	global_load_lds_dwordx4 v[218:219], off
	s_waitcnt vmcnt(8)
	s_waitcnt lgkmcnt(0)
	s_barrier
	s_setprio 1
	s_waitcnt lgkmcnt(0)
	v_mfma_f32_16x16x32_bf16 v[126:129], v[146:149], v[184:187], v[126:129]
	v_mfma_f32_16x16x32_bf16 v[122:125], v[154:157], v[184:187], v[122:125]
	v_mfma_f32_16x16x32_bf16 v[110:113], v[146:149], v[192:195], v[110:113]
	v_mfma_f32_16x16x32_bf16 v[106:109], v[154:157], v[192:195], v[106:109]
	v_mfma_f32_16x16x32_bf16 v[94:97], v[146:149], v[200:203], v[94:97]
	v_mfma_f32_16x16x32_bf16 v[90:93], v[154:157], v[200:203], v[90:93]
	v_mfma_f32_16x16x32_bf16 v[78:81], v[146:149], v[208:211], v[78:81]
	v_mfma_f32_16x16x32_bf16 v[74:77], v[154:157], v[208:211], v[74:77]
	v_mfma_f32_16x16x32_bf16 v[126:129], v[150:153], v[188:191], v[126:129]
	v_mfma_f32_16x16x32_bf16 v[122:125], v[158:161], v[188:191], v[122:125]
	v_mfma_f32_16x16x32_bf16 v[110:113], v[150:153], v[196:199], v[110:113]
	v_mfma_f32_16x16x32_bf16 v[106:109], v[158:161], v[196:199], v[106:109]
	v_mfma_f32_16x16x32_bf16 v[94:97], v[150:153], v[204:207], v[94:97]
	v_mfma_f32_16x16x32_bf16 v[90:93], v[158:161], v[204:207], v[90:93]
	v_mfma_f32_16x16x32_bf16 v[78:81], v[150:153], v[212:215], v[78:81]
	v_mfma_f32_16x16x32_bf16 v[74:77], v[158:161], v[212:215], v[74:77]
	s_setprio 0
	s_setprio 1
	v_mfma_f32_16x16x32_bf16 v[118:121], v[168:171], v[184:187], v[118:121]
	v_mfma_f32_16x16x32_bf16 v[114:117], v[176:179], v[184:187], v[114:117]
	v_mfma_f32_16x16x32_bf16 v[102:105], v[168:171], v[192:195], v[102:105]
	v_mfma_f32_16x16x32_bf16 v[98:101], v[176:179], v[192:195], v[98:101]
	v_mfma_f32_16x16x32_bf16 v[86:89], v[168:171], v[200:203], v[86:89]
	v_mfma_f32_16x16x32_bf16 v[82:85], v[176:179], v[200:203], v[82:85]
	v_mfma_f32_16x16x32_bf16 v[70:73], v[168:171], v[208:211], v[70:73]
	v_mfma_f32_16x16x32_bf16 v[66:69], v[176:179], v[208:211], v[66:69]
	v_mfma_f32_16x16x32_bf16 v[118:121], v[172:175], v[188:191], v[118:121]
	v_mfma_f32_16x16x32_bf16 v[114:117], v[180:183], v[188:191], v[114:117]
	v_mfma_f32_16x16x32_bf16 v[102:105], v[172:175], v[196:199], v[102:105]
	v_mfma_f32_16x16x32_bf16 v[98:101], v[180:183], v[196:199], v[98:101]
	v_mfma_f32_16x16x32_bf16 v[86:89], v[172:175], v[204:207], v[86:89]
	v_mfma_f32_16x16x32_bf16 v[82:85], v[180:183], v[204:207], v[82:85]
	v_mfma_f32_16x16x32_bf16 v[70:73], v[172:175], v[212:215], v[70:73]
	v_mfma_f32_16x16x32_bf16 v[66:69], v[180:183], v[212:215], v[66:69]
	s_setprio 0
	s_barrier
	s_add_i32 s53, s71, s31
	v_lshl_add_u64 v[218:219], s[34:35], 0, v[132:133]
	s_mov_b32 m0, s53
	ds_read_b128 v[184:187], v166 offset:16384
	ds_read_b128 v[188:191], v166 offset:17408
	ds_read_b128 v[192:195], v166 offset:18432
	ds_read_b128 v[196:199], v166 offset:19456
	ds_read_b128 v[200:203], v166 offset:20480
	ds_read_b128 v[204:207], v166 offset:21504
	ds_read_b128 v[208:211], v166 offset:22528
	ds_read_b128 v[212:215], v166 offset:23552
	global_load_lds_dwordx4 v[218:219], off
	s_add_i32 m0, s53, 0x2000
	s_add_u32 s54, s34, 0x160000
	v_lshl_add_u64 v[220:221], s[34:35], 0, v[136:137]
	s_addc_u32 s55, s35, 0
	s_add_i32 s53, s72, s31
	global_load_lds_dwordx4 v[220:221], off
	v_lshl_add_u64 v[222:223], s[54:55], 0, v[132:133]
	s_mov_b32 m0, s53
	v_lshl_add_u64 v[224:225], s[84:85], 0, v[134:135]
	global_load_lds_dwordx4 v[222:223], off
	v_lshl_add_u64 v[222:223], s[54:55], 0, v[136:137]
	s_add_i32 m0, s53, 0x2000
	s_nop 0
	global_load_lds_dwordx4 v[222:223], off
	v_lshl_add_u64 v[222:223], s[84:85], 0, v[130:131]
	s_mov_b32 m0, s33
	s_nop 0
	global_load_lds_dwordx4 v[222:223], off
	s_mov_b32 m0, s56
	s_nop 0
	global_load_lds_dwordx4 v[224:225], off
	s_waitcnt vmcnt(8)
	s_waitcnt lgkmcnt(0)
	s_barrier
	s_setprio 1
	s_waitcnt lgkmcnt(0)
	v_mfma_f32_16x16x32_bf16 v[62:65], v[146:149], v[184:187], v[62:65]
	v_mfma_f32_16x16x32_bf16 v[58:61], v[154:157], v[184:187], v[58:61]
	v_mfma_f32_16x16x32_bf16 v[46:49], v[146:149], v[192:195], v[46:49]
	v_mfma_f32_16x16x32_bf16 v[42:45], v[154:157], v[192:195], v[42:45]
	v_mfma_f32_16x16x32_bf16 v[30:33], v[146:149], v[200:203], v[30:33]
	v_mfma_f32_16x16x32_bf16 v[26:29], v[154:157], v[200:203], v[26:29]
	v_mfma_f32_16x16x32_bf16 v[14:17], v[146:149], v[208:211], v[14:17]
	v_mfma_f32_16x16x32_bf16 v[10:13], v[154:157], v[208:211], v[10:13]
	v_mfma_f32_16x16x32_bf16 v[62:65], v[150:153], v[188:191], v[62:65]
	v_mfma_f32_16x16x32_bf16 v[58:61], v[158:161], v[188:191], v[58:61]
	v_mfma_f32_16x16x32_bf16 v[46:49], v[150:153], v[196:199], v[46:49]
	v_mfma_f32_16x16x32_bf16 v[42:45], v[158:161], v[196:199], v[42:45]
	v_mfma_f32_16x16x32_bf16 v[30:33], v[150:153], v[204:207], v[30:33]
	v_mfma_f32_16x16x32_bf16 v[26:29], v[158:161], v[204:207], v[26:29]
	v_mfma_f32_16x16x32_bf16 v[14:17], v[150:153], v[212:215], v[14:17]
	v_mfma_f32_16x16x32_bf16 v[10:13], v[158:161], v[212:215], v[10:13]
	s_setprio 0
	s_setprio 1
	v_mfma_f32_16x16x32_bf16 v[54:57], v[168:171], v[184:187], v[54:57]
	v_mfma_f32_16x16x32_bf16 v[50:53], v[176:179], v[184:187], v[50:53]
	v_mfma_f32_16x16x32_bf16 v[38:41], v[168:171], v[192:195], v[38:41]
	v_mfma_f32_16x16x32_bf16 v[34:37], v[176:179], v[192:195], v[34:37]
	v_mfma_f32_16x16x32_bf16 v[22:25], v[168:171], v[200:203], v[22:25]
	v_mfma_f32_16x16x32_bf16 v[18:21], v[176:179], v[200:203], v[18:21]
	v_mfma_f32_16x16x32_bf16 v[6:9], v[168:171], v[208:211], v[6:9]
	v_mfma_f32_16x16x32_bf16 v[2:5], v[176:179], v[208:211], v[2:5]
	v_mfma_f32_16x16x32_bf16 v[54:57], v[172:175], v[188:191], v[54:57]
	v_mfma_f32_16x16x32_bf16 v[50:53], v[180:183], v[188:191], v[50:53]
	v_mfma_f32_16x16x32_bf16 v[38:41], v[172:175], v[196:199], v[38:41]
	v_mfma_f32_16x16x32_bf16 v[34:37], v[180:183], v[196:199], v[34:37]
	v_mfma_f32_16x16x32_bf16 v[22:25], v[172:175], v[204:207], v[22:25]
	v_mfma_f32_16x16x32_bf16 v[18:21], v[180:183], v[204:207], v[18:21]
	v_mfma_f32_16x16x32_bf16 v[6:9], v[172:175], v[212:215], v[6:9]
	v_mfma_f32_16x16x32_bf16 v[2:5], v[180:183], v[212:215], v[2:5]
	s_setprio 0
	s_barrier
	s_add_i32 s53, 0, 0x18000
	s_add_i32 s62, 0, 0x1c000
	v_add_u32_e32 v158, s53, v162
	v_add_u32_e32 v167, 0x19000, v162
	ds_read_b128 v[146:149], v158
	ds_read_b128 v[150:153], v158 offset:1024
	ds_read_b128 v[154:157], v158 offset:2048
	ds_read_b128 v[158:161], v158 offset:3072
	ds_read_b128 v[168:171], v167
	ds_read_b128 v[172:175], v167 offset:1024
	ds_read_b128 v[176:179], v167 offset:2048
	ds_read_b128 v[180:183], v167 offset:3072
	s_add_u32 s54, s84, 0x160000
	s_addc_u32 s55, s85, 0
	s_mov_b32 m0, s57
	v_lshl_add_u64 v[226:227], s[54:55], 0, v[130:131]
	ds_read_b128 v[184:187], v166 offset:32768
	ds_read_b128 v[188:191], v166 offset:33792
	ds_read_b128 v[192:195], v166 offset:34816
	ds_read_b128 v[196:199], v166 offset:35840
	ds_read_b128 v[200:203], v166 offset:36864
	ds_read_b128 v[204:207], v166 offset:37888
	ds_read_b128 v[208:211], v166 offset:38912
	ds_read_b128 v[212:215], v166 offset:39936
	global_load_lds_dwordx4 v[226:227], off
	v_lshl_add_u64 v[226:227], s[54:55], 0, v[134:135]
	s_mov_b32 m0, s58
	s_nop 0
	global_load_lds_dwordx4 v[226:227], off
	s_waitcnt vmcnt(8)
	s_waitcnt lgkmcnt(0)
	s_barrier
	s_setprio 1
	s_waitcnt lgkmcnt(0)
	v_mfma_f32_16x16x32_bf16 v[126:129], v[146:149], v[184:187], v[126:129]
	v_mfma_f32_16x16x32_bf16 v[122:125], v[154:157], v[184:187], v[122:125]
	v_mfma_f32_16x16x32_bf16 v[110:113], v[146:149], v[192:195], v[110:113]
	v_mfma_f32_16x16x32_bf16 v[106:109], v[154:157], v[192:195], v[106:109]
	v_mfma_f32_16x16x32_bf16 v[94:97], v[146:149], v[200:203], v[94:97]
	v_mfma_f32_16x16x32_bf16 v[90:93], v[154:157], v[200:203], v[90:93]
	v_mfma_f32_16x16x32_bf16 v[78:81], v[146:149], v[208:211], v[78:81]
	v_mfma_f32_16x16x32_bf16 v[74:77], v[154:157], v[208:211], v[74:77]
	v_mfma_f32_16x16x32_bf16 v[126:129], v[150:153], v[188:191], v[126:129]
	v_mfma_f32_16x16x32_bf16 v[122:125], v[158:161], v[188:191], v[122:125]
	v_mfma_f32_16x16x32_bf16 v[110:113], v[150:153], v[196:199], v[110:113]
	v_mfma_f32_16x16x32_bf16 v[106:109], v[158:161], v[196:199], v[106:109]
	v_mfma_f32_16x16x32_bf16 v[94:97], v[150:153], v[204:207], v[94:97]
	v_mfma_f32_16x16x32_bf16 v[90:93], v[158:161], v[204:207], v[90:93]
	v_mfma_f32_16x16x32_bf16 v[78:81], v[150:153], v[212:215], v[78:81]
	v_mfma_f32_16x16x32_bf16 v[74:77], v[158:161], v[212:215], v[74:77]
	s_setprio 0
	s_setprio 1
	v_mfma_f32_16x16x32_bf16 v[118:121], v[168:171], v[184:187], v[118:121]
	v_mfma_f32_16x16x32_bf16 v[114:117], v[176:179], v[184:187], v[114:117]
	v_mfma_f32_16x16x32_bf16 v[102:105], v[168:171], v[192:195], v[102:105]
	v_mfma_f32_16x16x32_bf16 v[98:101], v[176:179], v[192:195], v[98:101]
	v_mfma_f32_16x16x32_bf16 v[86:89], v[168:171], v[200:203], v[86:89]
	v_mfma_f32_16x16x32_bf16 v[82:85], v[176:179], v[200:203], v[82:85]
	v_mfma_f32_16x16x32_bf16 v[70:73], v[168:171], v[208:211], v[70:73]
	v_mfma_f32_16x16x32_bf16 v[66:69], v[176:179], v[208:211], v[66:69]
	v_mfma_f32_16x16x32_bf16 v[118:121], v[172:175], v[188:191], v[118:121]
	v_mfma_f32_16x16x32_bf16 v[114:117], v[180:183], v[188:191], v[114:117]
	v_mfma_f32_16x16x32_bf16 v[102:105], v[172:175], v[196:199], v[102:105]
	v_mfma_f32_16x16x32_bf16 v[98:101], v[180:183], v[196:199], v[98:101]
	v_mfma_f32_16x16x32_bf16 v[86:89], v[172:175], v[204:207], v[86:89]
	v_mfma_f32_16x16x32_bf16 v[82:85], v[180:183], v[204:207], v[82:85]
	v_mfma_f32_16x16x32_bf16 v[70:73], v[172:175], v[212:215], v[70:73]
	v_mfma_f32_16x16x32_bf16 v[66:69], v[180:183], v[212:215], v[66:69]
	s_setprio 0
	s_barrier
	s_add_i32 s53, s53, s31
	v_lshl_add_u64 v[218:219], v[218:219], 0, s[78:79]
	s_mov_b32 m0, s53
	ds_read_b128 v[184:187], v166 offset:49152
	ds_read_b128 v[188:191], v166 offset:50176
	ds_read_b128 v[192:195], v166 offset:51200
	ds_read_b128 v[196:199], v166 offset:52224
	ds_read_b128 v[200:203], v166 offset:53248
	ds_read_b128 v[204:207], v166 offset:54272
	ds_read_b128 v[208:211], v166 offset:55296
	ds_read_b128 v[212:215], v166 offset:56320
	global_load_lds_dwordx4 v[218:219], off
	s_add_i32 m0, s53, 0x2000
	s_add_u32 s34, s34, 0x160080
	v_lshl_add_u64 v[218:219], v[220:221], 0, s[78:79]
	s_addc_u32 s35, s35, 0
	s_add_i32 s53, s62, s31
	global_load_lds_dwordx4 v[218:219], off
	v_lshl_add_u64 v[218:219], s[34:35], 0, v[132:133]
	s_mov_b32 m0, s53
	s_nop 0
	global_load_lds_dwordx4 v[218:219], off
	v_lshl_add_u64 v[218:219], s[34:35], 0, v[136:137]
	s_add_i32 m0, s53, 0x2000
	s_nop 0
	global_load_lds_dwordx4 v[218:219], off
	v_lshl_add_u64 v[218:219], v[222:223], 0, s[78:79]
	s_mov_b32 m0, s60
	s_nop 0
	global_load_lds_dwordx4 v[218:219], off
	v_lshl_add_u64 v[218:219], v[224:225], 0, s[78:79]
	s_mov_b32 m0, s61
	s_nop 0
	global_load_lds_dwordx4 v[218:219], off
	s_waitcnt vmcnt(8)
	s_waitcnt lgkmcnt(0)
	s_barrier
	s_setprio 1
	s_waitcnt lgkmcnt(0)
	v_mfma_f32_16x16x32_bf16 v[62:65], v[146:149], v[184:187], v[62:65]
	v_mfma_f32_16x16x32_bf16 v[58:61], v[154:157], v[184:187], v[58:61]
	v_mfma_f32_16x16x32_bf16 v[46:49], v[146:149], v[192:195], v[46:49]
	v_mfma_f32_16x16x32_bf16 v[42:45], v[154:157], v[192:195], v[42:45]
	v_mfma_f32_16x16x32_bf16 v[30:33], v[146:149], v[200:203], v[30:33]
	v_mfma_f32_16x16x32_bf16 v[26:29], v[154:157], v[200:203], v[26:29]
	v_mfma_f32_16x16x32_bf16 v[14:17], v[146:149], v[208:211], v[14:17]
	v_mfma_f32_16x16x32_bf16 v[10:13], v[154:157], v[208:211], v[10:13]
	v_mfma_f32_16x16x32_bf16 v[62:65], v[150:153], v[188:191], v[62:65]
	v_mfma_f32_16x16x32_bf16 v[58:61], v[158:161], v[188:191], v[58:61]
	v_mfma_f32_16x16x32_bf16 v[46:49], v[150:153], v[196:199], v[46:49]
	v_mfma_f32_16x16x32_bf16 v[42:45], v[158:161], v[196:199], v[42:45]
	v_mfma_f32_16x16x32_bf16 v[30:33], v[150:153], v[204:207], v[30:33]
	v_mfma_f32_16x16x32_bf16 v[26:29], v[158:161], v[204:207], v[26:29]
	v_mfma_f32_16x16x32_bf16 v[14:17], v[150:153], v[212:215], v[14:17]
	v_mfma_f32_16x16x32_bf16 v[10:13], v[158:161], v[212:215], v[10:13]
	s_setprio 0
	s_setprio 1
	v_mfma_f32_16x16x32_bf16 v[54:57], v[168:171], v[184:187], v[54:57]
	v_mfma_f32_16x16x32_bf16 v[50:53], v[176:179], v[184:187], v[50:53]
	v_mfma_f32_16x16x32_bf16 v[38:41], v[168:171], v[192:195], v[38:41]
	v_mfma_f32_16x16x32_bf16 v[34:37], v[176:179], v[192:195], v[34:37]
	v_mfma_f32_16x16x32_bf16 v[22:25], v[168:171], v[200:203], v[22:25]
	v_mfma_f32_16x16x32_bf16 v[18:21], v[176:179], v[200:203], v[18:21]
	v_mfma_f32_16x16x32_bf16 v[6:9], v[168:171], v[208:211], v[6:9]
	v_mfma_f32_16x16x32_bf16 v[2:5], v[176:179], v[208:211], v[2:5]
	v_mfma_f32_16x16x32_bf16 v[54:57], v[172:175], v[188:191], v[54:57]
	v_mfma_f32_16x16x32_bf16 v[50:53], v[180:183], v[188:191], v[50:53]
	v_mfma_f32_16x16x32_bf16 v[38:41], v[172:175], v[196:199], v[38:41]
	v_mfma_f32_16x16x32_bf16 v[34:37], v[180:183], v[196:199], v[34:37]
	v_mfma_f32_16x16x32_bf16 v[22:25], v[172:175], v[204:207], v[22:25]
	v_mfma_f32_16x16x32_bf16 v[18:21], v[180:183], v[204:207], v[18:21]
	v_mfma_f32_16x16x32_bf16 v[6:9], v[172:175], v[212:215], v[6:9]
	v_mfma_f32_16x16x32_bf16 v[2:5], v[180:183], v[212:215], v[2:5]
	s_setprio 0
	s_barrier
	s_add_i32 s52, s52, 2
	s_add_u32 s76, s76, 0x100
	s_addc_u32 s77, s77, 0
	s_add_u32 s0, s0, 0x100
	s_addc_u32 s1, s1, 0
	s_cmpk_gt_u32 s52, 0x55
	s_cbranch_scc0 .LBB0_1237
	v_lshl_add_u32 v146, s75, 8, v1
	v_lshl_or_b32 v148, s86, 8, v163
	v_ashrrev_i32_e32 v147, 31, v146
	v_ashrrev_i32_e32 v149, 31, v148
	v_lshlrev_b64 v[150:151], 12, v[146:147]
	v_lshl_add_u64 v[150:151], s[64:65], 0, v[150:151]
	v_lshlrev_b64 v[148:149], 1, v[148:149]
	v_lshl_add_u64 v[150:151], v[150:151], 0, v[148:149]
	v_mov_b32_e32 v245, 0
	v_mov_b32_e32 v244, 0x10000
	v_lshl_add_u64 v[230:231], v[244:245], 0, v[150:151]
	v_mov_b32_e32 v244, 0x20000
	v_lshl_add_u64 v[232:233], v[244:245], 0, v[150:151]
	v_mov_b32_e32 v244, 0x30000
	v_lshl_add_u64 v[234:235], v[244:245], 0, v[150:151]
	v_mov_b32_e32 v244, 0x80000
	v_lshl_add_u64 v[236:237], v[244:245], 0, v[150:151]
	v_mov_b32_e32 v244, 0x90000
	v_lshl_add_u64 v[238:239], v[244:245], 0, v[150:151]
	v_mov_b32_e32 v244, 0xa0000
	v_lshl_add_u64 v[240:241], v[244:245], 0, v[150:151]
	v_mov_b32_e32 v244, 0xb0000
	v_lshl_add_u64 v[242:243], v[244:245], 0, v[150:151]
	global_load_dwordx4 v[146:149], v[150:151], off
	global_load_dwordx4 v[152:155], v[150:151], off offset:64
	global_load_dwordx4 v[156:159], v[230:231], off
	global_load_dwordx4 v[168:171], v[230:231], off offset:64
	global_load_dwordx4 v[172:175], v[232:233], off
	global_load_dwordx4 v[176:179], v[232:233], off offset:64
	global_load_dwordx4 v[180:183], v[234:235], off
	global_load_dwordx4 v[184:187], v[234:235], off offset:64
	s_and_b64 vcc, exec, s[80:81]
	s_cbranch_vccz .LBB0_1240
	s_barrier
.LBB0_1240:
	s_waitcnt vmcnt(7)
	v_cvt_f32_f16_e32 v160, v146
	v_cvt_f32_f16_sdwa v161, v146 dst_sel:DWORD dst_unused:UNUSED_PAD src0_sel:WORD_1
	v_cvt_f32_f16_e32 v188, v147
	v_cvt_f32_f16_sdwa v189, v147 dst_sel:DWORD dst_unused:UNUSED_PAD src0_sel:WORD_1
	v_cvt_f32_f16_e32 v190, v148
	v_cvt_f32_f16_sdwa v191, v148 dst_sel:DWORD dst_unused:UNUSED_PAD src0_sel:WORD_1
	v_cvt_f32_f16_e32 v228, v149
	v_cvt_f32_f16_sdwa v229, v149 dst_sel:DWORD dst_unused:UNUSED_PAD src0_sel:WORD_1
	global_load_dwordx4 v[146:149], v[236:237], off
	v_pk_fma_f32 v[126:127], v[126:127], 0.5, v[160:161] op_sel_hi:[1,0,1]
	v_pk_fma_f32 v[128:129], v[128:129], 0.5, v[188:189] op_sel_hi:[1,0,1]
	v_pk_fma_f32 v[122:123], v[122:123], 0.5, v[190:191] op_sel_hi:[1,0,1]
	v_pk_fma_f32 v[124:125], v[124:125], 0.5, v[228:229] op_sel_hi:[1,0,1]
	v_cvt_pk_f16_f32 v125, v124, v125
	v_cvt_pk_f16_f32 v124, v122, v123
	v_cvt_pk_f16_f32 v123, v128, v129
	v_cvt_pk_f16_f32 v122, v126, v127
	global_store_dwordx4 v[150:151], v[122:125], off
	s_waitcnt vmcnt(8)
	v_cvt_f32_f16_e32 v160, v152
	v_cvt_f32_f16_sdwa v161, v152 dst_sel:DWORD dst_unused:UNUSED_PAD src0_sel:WORD_1
	v_cvt_f32_f16_e32 v188, v153
	v_cvt_f32_f16_sdwa v189, v153 dst_sel:DWORD dst_unused:UNUSED_PAD src0_sel:WORD_1
	v_cvt_f32_f16_e32 v190, v154
	v_cvt_f32_f16_sdwa v191, v154 dst_sel:DWORD dst_unused:UNUSED_PAD src0_sel:WORD_1
	v_cvt_f32_f16_e32 v228, v155
	v_cvt_f32_f16_sdwa v229, v155 dst_sel:DWORD dst_unused:UNUSED_PAD src0_sel:WORD_1
	global_load_dwordx4 v[152:155], v[236:237], off offset:64
	v_pk_fma_f32 v[118:119], v[118:119], 0.5, v[160:161] op_sel_hi:[1,0,1]
	v_pk_fma_f32 v[120:121], v[120:121], 0.5, v[188:189] op_sel_hi:[1,0,1]
	v_pk_fma_f32 v[114:115], v[114:115], 0.5, v[190:191] op_sel_hi:[1,0,1]
	v_pk_fma_f32 v[116:117], v[116:117], 0.5, v[228:229] op_sel_hi:[1,0,1]
	v_cvt_pk_f16_f32 v117, v116, v117
	v_cvt_pk_f16_f32 v116, v114, v115
	v_cvt_pk_f16_f32 v115, v120, v121
	v_cvt_pk_f16_f32 v114, v118, v119
	global_store_dwordx4 v[150:151], v[114:117], off offset:64
	s_waitcnt vmcnt(9)
	v_cvt_f32_f16_e32 v160, v156
	v_cvt_f32_f16_sdwa v161, v156 dst_sel:DWORD dst_unused:UNUSED_PAD src0_sel:WORD_1
	v_cvt_f32_f16_e32 v188, v157
	v_cvt_f32_f16_sdwa v189, v157 dst_sel:DWORD dst_unused:UNUSED_PAD src0_sel:WORD_1
	v_cvt_f32_f16_e32 v190, v158
	v_cvt_f32_f16_sdwa v191, v158 dst_sel:DWORD dst_unused:UNUSED_PAD src0_sel:WORD_1
	v_cvt_f32_f16_e32 v228, v159
	v_cvt_f32_f16_sdwa v229, v159 dst_sel:DWORD dst_unused:UNUSED_PAD src0_sel:WORD_1
	global_load_dwordx4 v[156:159], v[238:239], off
	v_pk_fma_f32 v[110:111], v[110:111], 0.5, v[160:161] op_sel_hi:[1,0,1]
	v_pk_fma_f32 v[112:113], v[112:113], 0.5, v[188:189] op_sel_hi:[1,0,1]
	v_pk_fma_f32 v[106:107], v[106:107], 0.5, v[190:191] op_sel_hi:[1,0,1]
	v_pk_fma_f32 v[108:109], v[108:109], 0.5, v[228:229] op_sel_hi:[1,0,1]
	v_cvt_pk_f16_f32 v109, v108, v109
	v_cvt_pk_f16_f32 v108, v106, v107
	v_cvt_pk_f16_f32 v107, v112, v113
	v_cvt_pk_f16_f32 v106, v110, v111
	global_store_dwordx4 v[230:231], v[106:109], off
	s_waitcnt vmcnt(10)
	v_cvt_f32_f16_e32 v160, v168
	v_cvt_f32_f16_sdwa v161, v168 dst_sel:DWORD dst_unused:UNUSED_PAD src0_sel:WORD_1
	v_cvt_f32_f16_e32 v188, v169
	v_cvt_f32_f16_sdwa v189, v169 dst_sel:DWORD dst_unused:UNUSED_PAD src0_sel:WORD_1
	v_cvt_f32_f16_e32 v190, v170
	v_cvt_f32_f16_sdwa v191, v170 dst_sel:DWORD dst_unused:UNUSED_PAD src0_sel:WORD_1
	v_cvt_f32_f16_e32 v228, v171
	v_cvt_f32_f16_sdwa v229, v171 dst_sel:DWORD dst_unused:UNUSED_PAD src0_sel:WORD_1
	global_load_dwordx4 v[168:171], v[238:239], off offset:64
	v_pk_fma_f32 v[102:103], v[102:103], 0.5, v[160:161] op_sel_hi:[1,0,1]
	v_pk_fma_f32 v[104:105], v[104:105], 0.5, v[188:189] op_sel_hi:[1,0,1]
	v_pk_fma_f32 v[98:99], v[98:99], 0.5, v[190:191] op_sel_hi:[1,0,1]
	v_pk_fma_f32 v[100:101], v[100:101], 0.5, v[228:229] op_sel_hi:[1,0,1]
	v_cvt_pk_f16_f32 v101, v100, v101
	v_cvt_pk_f16_f32 v100, v98, v99
	v_cvt_pk_f16_f32 v99, v104, v105
	v_cvt_pk_f16_f32 v98, v102, v103
	global_store_dwordx4 v[230:231], v[98:101], off offset:64
	s_waitcnt vmcnt(11)
	v_cvt_f32_f16_e32 v160, v172
	v_cvt_f32_f16_sdwa v161, v172 dst_sel:DWORD dst_unused:UNUSED_PAD src0_sel:WORD_1
	v_cvt_f32_f16_e32 v188, v173
	v_cvt_f32_f16_sdwa v189, v173 dst_sel:DWORD dst_unused:UNUSED_PAD src0_sel:WORD_1
	v_cvt_f32_f16_e32 v190, v174
	v_cvt_f32_f16_sdwa v191, v174 dst_sel:DWORD dst_unused:UNUSED_PAD src0_sel:WORD_1
	v_cvt_f32_f16_e32 v228, v175
	v_cvt_f32_f16_sdwa v229, v175 dst_sel:DWORD dst_unused:UNUSED_PAD src0_sel:WORD_1
	global_load_dwordx4 v[172:175], v[240:241], off
	v_pk_fma_f32 v[94:95], v[94:95], 0.5, v[160:161] op_sel_hi:[1,0,1]
	v_pk_fma_f32 v[96:97], v[96:97], 0.5, v[188:189] op_sel_hi:[1,0,1]
	v_pk_fma_f32 v[90:91], v[90:91], 0.5, v[190:191] op_sel_hi:[1,0,1]
	v_pk_fma_f32 v[92:93], v[92:93], 0.5, v[228:229] op_sel_hi:[1,0,1]
	v_cvt_pk_f16_f32 v93, v92, v93
	v_cvt_pk_f16_f32 v92, v90, v91
	v_cvt_pk_f16_f32 v91, v96, v97
	v_cvt_pk_f16_f32 v90, v94, v95
	global_store_dwordx4 v[232:233], v[90:93], off
	s_waitcnt vmcnt(12)
	v_cvt_f32_f16_e32 v160, v176
	v_cvt_f32_f16_sdwa v161, v176 dst_sel:DWORD dst_unused:UNUSED_PAD src0_sel:WORD_1
	v_cvt_f32_f16_e32 v188, v177
	v_cvt_f32_f16_sdwa v189, v177 dst_sel:DWORD dst_unused:UNUSED_PAD src0_sel:WORD_1
	v_cvt_f32_f16_e32 v190, v178
	v_cvt_f32_f16_sdwa v191, v178 dst_sel:DWORD dst_unused:UNUSED_PAD src0_sel:WORD_1
	v_cvt_f32_f16_e32 v228, v179
	v_cvt_f32_f16_sdwa v229, v179 dst_sel:DWORD dst_unused:UNUSED_PAD src0_sel:WORD_1
	global_load_dwordx4 v[176:179], v[240:241], off offset:64
	v_pk_fma_f32 v[86:87], v[86:87], 0.5, v[160:161] op_sel_hi:[1,0,1]
	v_pk_fma_f32 v[88:89], v[88:89], 0.5, v[188:189] op_sel_hi:[1,0,1]
	v_pk_fma_f32 v[82:83], v[82:83], 0.5, v[190:191] op_sel_hi:[1,0,1]
	v_pk_fma_f32 v[84:85], v[84:85], 0.5, v[228:229] op_sel_hi:[1,0,1]
	v_cvt_pk_f16_f32 v85, v84, v85
	v_cvt_pk_f16_f32 v84, v82, v83
	v_cvt_pk_f16_f32 v83, v88, v89
	v_cvt_pk_f16_f32 v82, v86, v87
	global_store_dwordx4 v[232:233], v[82:85], off offset:64
	s_waitcnt vmcnt(13)
	v_cvt_f32_f16_e32 v160, v180
	v_cvt_f32_f16_sdwa v161, v180 dst_sel:DWORD dst_unused:UNUSED_PAD src0_sel:WORD_1
	v_cvt_f32_f16_e32 v188, v181
	v_cvt_f32_f16_sdwa v189, v181 dst_sel:DWORD dst_unused:UNUSED_PAD src0_sel:WORD_1
	v_cvt_f32_f16_e32 v190, v182
	v_cvt_f32_f16_sdwa v191, v182 dst_sel:DWORD dst_unused:UNUSED_PAD src0_sel:WORD_1
	v_cvt_f32_f16_e32 v228, v183
	v_cvt_f32_f16_sdwa v229, v183 dst_sel:DWORD dst_unused:UNUSED_PAD src0_sel:WORD_1
	global_load_dwordx4 v[180:183], v[242:243], off
	v_pk_fma_f32 v[78:79], v[78:79], 0.5, v[160:161] op_sel_hi:[1,0,1]
	v_pk_fma_f32 v[80:81], v[80:81], 0.5, v[188:189] op_sel_hi:[1,0,1]
	v_pk_fma_f32 v[74:75], v[74:75], 0.5, v[190:191] op_sel_hi:[1,0,1]
	v_pk_fma_f32 v[76:77], v[76:77], 0.5, v[228:229] op_sel_hi:[1,0,1]
	v_cvt_pk_f16_f32 v77, v76, v77
	v_cvt_pk_f16_f32 v76, v74, v75
	v_cvt_pk_f16_f32 v75, v80, v81
	v_cvt_pk_f16_f32 v74, v78, v79
	global_store_dwordx4 v[234:235], v[74:77], off
	s_waitcnt vmcnt(14)
	v_cvt_f32_f16_e32 v160, v184
	v_cvt_f32_f16_sdwa v161, v184 dst_sel:DWORD dst_unused:UNUSED_PAD src0_sel:WORD_1
	v_cvt_f32_f16_e32 v188, v185
	v_cvt_f32_f16_sdwa v189, v185 dst_sel:DWORD dst_unused:UNUSED_PAD src0_sel:WORD_1
	v_cvt_f32_f16_e32 v190, v186
	v_cvt_f32_f16_sdwa v191, v186 dst_sel:DWORD dst_unused:UNUSED_PAD src0_sel:WORD_1
	v_cvt_f32_f16_e32 v228, v187
	v_cvt_f32_f16_sdwa v229, v187 dst_sel:DWORD dst_unused:UNUSED_PAD src0_sel:WORD_1
	global_load_dwordx4 v[184:187], v[242:243], off offset:64
	v_pk_fma_f32 v[70:71], v[70:71], 0.5, v[160:161] op_sel_hi:[1,0,1]
	v_pk_fma_f32 v[72:73], v[72:73], 0.5, v[188:189] op_sel_hi:[1,0,1]
	v_pk_fma_f32 v[66:67], v[66:67], 0.5, v[190:191] op_sel_hi:[1,0,1]
	v_pk_fma_f32 v[68:69], v[68:69], 0.5, v[228:229] op_sel_hi:[1,0,1]
	v_cvt_pk_f16_f32 v69, v68, v69
	v_cvt_pk_f16_f32 v68, v66, v67
	v_cvt_pk_f16_f32 v67, v72, v73
	v_cvt_pk_f16_f32 v66, v70, v71
	global_store_dwordx4 v[234:235], v[66:69], off offset:64
	s_waitcnt vmcnt(15)
	v_cvt_f32_f16_e32 v160, v146
	v_cvt_f32_f16_sdwa v161, v146 dst_sel:DWORD dst_unused:UNUSED_PAD src0_sel:WORD_1
	v_cvt_f32_f16_e32 v188, v147
	v_cvt_f32_f16_sdwa v189, v147 dst_sel:DWORD dst_unused:UNUSED_PAD src0_sel:WORD_1
	v_cvt_f32_f16_e32 v190, v148
	v_cvt_f32_f16_sdwa v191, v148 dst_sel:DWORD dst_unused:UNUSED_PAD src0_sel:WORD_1
	v_cvt_f32_f16_e32 v228, v149
	v_cvt_f32_f16_sdwa v229, v149 dst_sel:DWORD dst_unused:UNUSED_PAD src0_sel:WORD_1
	v_pk_fma_f32 v[62:63], v[62:63], 0.5, v[160:161] op_sel_hi:[1,0,1]
	v_pk_fma_f32 v[64:65], v[64:65], 0.5, v[188:189] op_sel_hi:[1,0,1]
	v_pk_fma_f32 v[58:59], v[58:59], 0.5, v[190:191] op_sel_hi:[1,0,1]
	v_pk_fma_f32 v[60:61], v[60:61], 0.5, v[228:229] op_sel_hi:[1,0,1]
	v_cvt_pk_f16_f32 v61, v60, v61
	v_cvt_pk_f16_f32 v60, v58, v59
	v_cvt_pk_f16_f32 v59, v64, v65
	v_cvt_pk_f16_f32 v58, v62, v63
	global_store_dwordx4 v[236:237], v[58:61], off
	s_waitcnt vmcnt(14)
	v_cvt_f32_f16_e32 v160, v152
	v_cvt_f32_f16_sdwa v161, v152 dst_sel:DWORD dst_unused:UNUSED_PAD src0_sel:WORD_1
	v_cvt_f32_f16_e32 v188, v153
	v_cvt_f32_f16_sdwa v189, v153 dst_sel:DWORD dst_unused:UNUSED_PAD src0_sel:WORD_1
	v_cvt_f32_f16_e32 v190, v154
	v_cvt_f32_f16_sdwa v191, v154 dst_sel:DWORD dst_unused:UNUSED_PAD src0_sel:WORD_1
	v_cvt_f32_f16_e32 v228, v155
	v_cvt_f32_f16_sdwa v229, v155 dst_sel:DWORD dst_unused:UNUSED_PAD src0_sel:WORD_1
	v_pk_fma_f32 v[54:55], v[54:55], 0.5, v[160:161] op_sel_hi:[1,0,1]
	v_pk_fma_f32 v[56:57], v[56:57], 0.5, v[188:189] op_sel_hi:[1,0,1]
	v_pk_fma_f32 v[50:51], v[50:51], 0.5, v[190:191] op_sel_hi:[1,0,1]
	v_pk_fma_f32 v[52:53], v[52:53], 0.5, v[228:229] op_sel_hi:[1,0,1]
	v_cvt_pk_f16_f32 v53, v52, v53
	v_cvt_pk_f16_f32 v52, v50, v51
	v_cvt_pk_f16_f32 v51, v56, v57
	v_cvt_pk_f16_f32 v50, v54, v55
	global_store_dwordx4 v[236:237], v[50:53], off offset:64
	s_waitcnt vmcnt(13)
	v_cvt_f32_f16_e32 v160, v156
	v_cvt_f32_f16_sdwa v161, v156 dst_sel:DWORD dst_unused:UNUSED_PAD src0_sel:WORD_1
	v_cvt_f32_f16_e32 v188, v157
	v_cvt_f32_f16_sdwa v189, v157 dst_sel:DWORD dst_unused:UNUSED_PAD src0_sel:WORD_1
	v_cvt_f32_f16_e32 v190, v158
	v_cvt_f32_f16_sdwa v191, v158 dst_sel:DWORD dst_unused:UNUSED_PAD src0_sel:WORD_1
	v_cvt_f32_f16_e32 v228, v159
	v_cvt_f32_f16_sdwa v229, v159 dst_sel:DWORD dst_unused:UNUSED_PAD src0_sel:WORD_1
	v_pk_fma_f32 v[46:47], v[46:47], 0.5, v[160:161] op_sel_hi:[1,0,1]
	v_pk_fma_f32 v[48:49], v[48:49], 0.5, v[188:189] op_sel_hi:[1,0,1]
	v_pk_fma_f32 v[42:43], v[42:43], 0.5, v[190:191] op_sel_hi:[1,0,1]
	v_pk_fma_f32 v[44:45], v[44:45], 0.5, v[228:229] op_sel_hi:[1,0,1]
	v_cvt_pk_f16_f32 v45, v44, v45
	v_cvt_pk_f16_f32 v44, v42, v43
	v_cvt_pk_f16_f32 v43, v48, v49
	v_cvt_pk_f16_f32 v42, v46, v47
	global_store_dwordx4 v[238:239], v[42:45], off
	s_waitcnt vmcnt(12)
	v_cvt_f32_f16_e32 v160, v168
	v_cvt_f32_f16_sdwa v161, v168 dst_sel:DWORD dst_unused:UNUSED_PAD src0_sel:WORD_1
	v_cvt_f32_f16_e32 v188, v169
	v_cvt_f32_f16_sdwa v189, v169 dst_sel:DWORD dst_unused:UNUSED_PAD src0_sel:WORD_1
	v_cvt_f32_f16_e32 v190, v170
	v_cvt_f32_f16_sdwa v191, v170 dst_sel:DWORD dst_unused:UNUSED_PAD src0_sel:WORD_1
	v_cvt_f32_f16_e32 v228, v171
	v_cvt_f32_f16_sdwa v229, v171 dst_sel:DWORD dst_unused:UNUSED_PAD src0_sel:WORD_1
	v_pk_fma_f32 v[38:39], v[38:39], 0.5, v[160:161] op_sel_hi:[1,0,1]
	v_pk_fma_f32 v[40:41], v[40:41], 0.5, v[188:189] op_sel_hi:[1,0,1]
	v_pk_fma_f32 v[34:35], v[34:35], 0.5, v[190:191] op_sel_hi:[1,0,1]
	v_pk_fma_f32 v[36:37], v[36:37], 0.5, v[228:229] op_sel_hi:[1,0,1]
	v_cvt_pk_f16_f32 v37, v36, v37
	v_cvt_pk_f16_f32 v36, v34, v35
	v_cvt_pk_f16_f32 v35, v40, v41
	v_cvt_pk_f16_f32 v34, v38, v39
	global_store_dwordx4 v[238:239], v[34:37], off offset:64
	s_waitcnt vmcnt(11)
	v_cvt_f32_f16_e32 v160, v172
	v_cvt_f32_f16_sdwa v161, v172 dst_sel:DWORD dst_unused:UNUSED_PAD src0_sel:WORD_1
	v_cvt_f32_f16_e32 v188, v173
	v_cvt_f32_f16_sdwa v189, v173 dst_sel:DWORD dst_unused:UNUSED_PAD src0_sel:WORD_1
	v_cvt_f32_f16_e32 v190, v174
	v_cvt_f32_f16_sdwa v191, v174 dst_sel:DWORD dst_unused:UNUSED_PAD src0_sel:WORD_1
	v_cvt_f32_f16_e32 v228, v175
	v_cvt_f32_f16_sdwa v229, v175 dst_sel:DWORD dst_unused:UNUSED_PAD src0_sel:WORD_1
	v_pk_fma_f32 v[30:31], v[30:31], 0.5, v[160:161] op_sel_hi:[1,0,1]
	v_pk_fma_f32 v[32:33], v[32:33], 0.5, v[188:189] op_sel_hi:[1,0,1]
	v_pk_fma_f32 v[26:27], v[26:27], 0.5, v[190:191] op_sel_hi:[1,0,1]
	v_pk_fma_f32 v[28:29], v[28:29], 0.5, v[228:229] op_sel_hi:[1,0,1]
	v_cvt_pk_f16_f32 v29, v28, v29
	v_cvt_pk_f16_f32 v28, v26, v27
	v_cvt_pk_f16_f32 v27, v32, v33
	v_cvt_pk_f16_f32 v26, v30, v31
	global_store_dwordx4 v[240:241], v[26:29], off
	s_waitcnt vmcnt(10)
	v_cvt_f32_f16_e32 v160, v176
	v_cvt_f32_f16_sdwa v161, v176 dst_sel:DWORD dst_unused:UNUSED_PAD src0_sel:WORD_1
	v_cvt_f32_f16_e32 v188, v177
	v_cvt_f32_f16_sdwa v189, v177 dst_sel:DWORD dst_unused:UNUSED_PAD src0_sel:WORD_1
	v_cvt_f32_f16_e32 v190, v178
	v_cvt_f32_f16_sdwa v191, v178 dst_sel:DWORD dst_unused:UNUSED_PAD src0_sel:WORD_1
	v_cvt_f32_f16_e32 v228, v179
	v_cvt_f32_f16_sdwa v229, v179 dst_sel:DWORD dst_unused:UNUSED_PAD src0_sel:WORD_1
	v_pk_fma_f32 v[22:23], v[22:23], 0.5, v[160:161] op_sel_hi:[1,0,1]
	v_pk_fma_f32 v[24:25], v[24:25], 0.5, v[188:189] op_sel_hi:[1,0,1]
	v_pk_fma_f32 v[18:19], v[18:19], 0.5, v[190:191] op_sel_hi:[1,0,1]
	v_pk_fma_f32 v[20:21], v[20:21], 0.5, v[228:229] op_sel_hi:[1,0,1]
	v_cvt_pk_f16_f32 v21, v20, v21
	v_cvt_pk_f16_f32 v20, v18, v19
	v_cvt_pk_f16_f32 v19, v24, v25
	v_cvt_pk_f16_f32 v18, v22, v23
	global_store_dwordx4 v[240:241], v[18:21], off offset:64
	s_waitcnt vmcnt(9)
	v_cvt_f32_f16_e32 v160, v180
	v_cvt_f32_f16_sdwa v161, v180 dst_sel:DWORD dst_unused:UNUSED_PAD src0_sel:WORD_1
	v_cvt_f32_f16_e32 v188, v181
	v_cvt_f32_f16_sdwa v189, v181 dst_sel:DWORD dst_unused:UNUSED_PAD src0_sel:WORD_1
	v_cvt_f32_f16_e32 v190, v182
	v_cvt_f32_f16_sdwa v191, v182 dst_sel:DWORD dst_unused:UNUSED_PAD src0_sel:WORD_1
	v_cvt_f32_f16_e32 v228, v183
	v_cvt_f32_f16_sdwa v229, v183 dst_sel:DWORD dst_unused:UNUSED_PAD src0_sel:WORD_1
	v_pk_fma_f32 v[14:15], v[14:15], 0.5, v[160:161] op_sel_hi:[1,0,1]
	v_pk_fma_f32 v[16:17], v[16:17], 0.5, v[188:189] op_sel_hi:[1,0,1]
	v_pk_fma_f32 v[10:11], v[10:11], 0.5, v[190:191] op_sel_hi:[1,0,1]
	v_pk_fma_f32 v[12:13], v[12:13], 0.5, v[228:229] op_sel_hi:[1,0,1]
	v_cvt_pk_f16_f32 v13, v12, v13
	v_cvt_pk_f16_f32 v12, v10, v11
	v_cvt_pk_f16_f32 v11, v16, v17
	v_cvt_pk_f16_f32 v10, v14, v15
	global_store_dwordx4 v[242:243], v[10:13], off
	s_waitcnt vmcnt(8)
	v_cvt_f32_f16_e32 v160, v184
	v_cvt_f32_f16_sdwa v161, v184 dst_sel:DWORD dst_unused:UNUSED_PAD src0_sel:WORD_1
	v_cvt_f32_f16_e32 v188, v185
	v_cvt_f32_f16_sdwa v189, v185 dst_sel:DWORD dst_unused:UNUSED_PAD src0_sel:WORD_1
	v_cvt_f32_f16_e32 v190, v186
	v_cvt_f32_f16_sdwa v191, v186 dst_sel:DWORD dst_unused:UNUSED_PAD src0_sel:WORD_1
	v_cvt_f32_f16_e32 v228, v187
	v_cvt_f32_f16_sdwa v229, v187 dst_sel:DWORD dst_unused:UNUSED_PAD src0_sel:WORD_1
	v_pk_fma_f32 v[6:7], v[6:7], 0.5, v[160:161] op_sel_hi:[1,0,1]
	v_pk_fma_f32 v[8:9], v[8:9], 0.5, v[188:189] op_sel_hi:[1,0,1]
	v_pk_fma_f32 v[2:3], v[2:3], 0.5, v[190:191] op_sel_hi:[1,0,1]
	v_pk_fma_f32 v[4:5], v[4:5], 0.5, v[228:229] op_sel_hi:[1,0,1]
	v_cvt_pk_f16_f32 v5, v4, v5
	v_cvt_pk_f16_f32 v4, v2, v3
	v_cvt_pk_f16_f32 v3, v8, v9
	v_cvt_pk_f16_f32 v2, v6, v7
	global_store_dwordx4 v[242:243], v[2:5], off offset:64
	s_mov_b64 s[0:1], -1
	s_and_b64 vcc, exec, s[2:3]
	s_cbranch_vccnz .LBB0_1225
	s_andn2_b64 vcc, exec, s[8:9]
	s_cbranch_vccnz .LBB0_1224
	s_barrier
	s_branch .LBB0_1224

.LBB0_2089:
	ds_read_b128 v[130:133], v178
	ds_read_b128 v[134:137], v178 offset:1024
	ds_read_b128 v[138:141], v178 offset:2048
	ds_read_b128 v[142:145], v178 offset:3072
	ds_read_b128 v[162:165], v179
	ds_read_b128 v[166:169], v179 offset:1024
	ds_read_b128 v[170:173], v179 offset:2048
	ds_read_b128 v[182:185], v179 offset:3072
	s_add_u32 s34, s38, 0xffea0080
	s_addc_u32 s35, s39, -1
	s_cmpk_eq_i32 s52, 0x54
	s_cselect_b32 s41, s5, s35
	s_cselect_b32 s40, s4, s34
	s_cselect_b32 s35, s37, s1
	s_cselect_b32 s34, s36, s0
	v_lshl_add_u64 v[174:175], s[38:39], 0, v[154:155]
	s_add_i32 m0, s33, 0xc000
	ds_read_b128 v[186:189], v180
	ds_read_b128 v[190:193], v180 offset:1024
	ds_read_b128 v[194:197], v180 offset:2048
	ds_read_b128 v[198:201], v180 offset:3072
	ds_read_b128 v[202:205], v180 offset:4096
	ds_read_b128 v[206:209], v180 offset:5120
	ds_read_b128 v[210:213], v180 offset:6144
	ds_read_b128 v[218:221], v180 offset:7168
	global_load_lds_dwordx4 v[174:175], off
	v_lshl_add_u64 v[174:175], s[38:39], 0, v[156:157]
	s_add_i32 m0, s33, 0xe000
	s_nop 0
	global_load_lds_dwordx4 v[174:175], off
	s_waitcnt vmcnt(8)
	s_waitcnt lgkmcnt(0)
	s_barrier
	s_setprio 1
	s_waitcnt lgkmcnt(0)
	v_mfma_f32_16x16x32_bf16 v[126:129], v[130:133], v[186:189], v[126:129]
	v_mfma_f32_16x16x32_bf16 v[122:125], v[138:141], v[186:189], v[122:125]
	v_mfma_f32_16x16x32_bf16 v[110:113], v[130:133], v[194:197], v[110:113]
	v_mfma_f32_16x16x32_bf16 v[106:109], v[138:141], v[194:197], v[106:109]
	v_mfma_f32_16x16x32_bf16 v[94:97], v[130:133], v[202:205], v[94:97]
	v_mfma_f32_16x16x32_bf16 v[90:93], v[138:141], v[202:205], v[90:93]
	v_mfma_f32_16x16x32_bf16 v[78:81], v[130:133], v[210:213], v[78:81]
	v_mfma_f32_16x16x32_bf16 v[74:77], v[138:141], v[210:213], v[74:77]
	v_mfma_f32_16x16x32_bf16 v[126:129], v[134:137], v[190:193], v[126:129]
	v_mfma_f32_16x16x32_bf16 v[122:125], v[142:145], v[190:193], v[122:125]
	v_mfma_f32_16x16x32_bf16 v[110:113], v[134:137], v[198:201], v[110:113]
	v_mfma_f32_16x16x32_bf16 v[106:109], v[142:145], v[198:201], v[106:109]
	v_mfma_f32_16x16x32_bf16 v[94:97], v[134:137], v[206:209], v[94:97]
	v_mfma_f32_16x16x32_bf16 v[90:93], v[142:145], v[206:209], v[90:93]
	v_mfma_f32_16x16x32_bf16 v[78:81], v[134:137], v[218:221], v[78:81]
	v_mfma_f32_16x16x32_bf16 v[74:77], v[142:145], v[218:221], v[74:77]
	s_setprio 0
	s_setprio 1
	v_mfma_f32_16x16x32_bf16 v[118:121], v[162:165], v[186:189], v[118:121]
	v_mfma_f32_16x16x32_bf16 v[114:117], v[170:173], v[186:189], v[114:117]
	v_mfma_f32_16x16x32_bf16 v[102:105], v[162:165], v[194:197], v[102:105]
	v_mfma_f32_16x16x32_bf16 v[98:101], v[170:173], v[194:197], v[98:101]
	v_mfma_f32_16x16x32_bf16 v[86:89], v[162:165], v[202:205], v[86:89]
	v_mfma_f32_16x16x32_bf16 v[82:85], v[170:173], v[202:205], v[82:85]
	v_mfma_f32_16x16x32_bf16 v[70:73], v[162:165], v[210:213], v[70:73]
	v_mfma_f32_16x16x32_bf16 v[66:69], v[170:173], v[210:213], v[66:69]
	v_mfma_f32_16x16x32_bf16 v[118:121], v[166:169], v[190:193], v[118:121]
	v_mfma_f32_16x16x32_bf16 v[114:117], v[182:185], v[190:193], v[114:117]
	v_mfma_f32_16x16x32_bf16 v[102:105], v[166:169], v[198:201], v[102:105]
	v_mfma_f32_16x16x32_bf16 v[98:101], v[182:185], v[198:201], v[98:101]
	v_mfma_f32_16x16x32_bf16 v[86:89], v[166:169], v[206:209], v[86:89]
	v_mfma_f32_16x16x32_bf16 v[82:85], v[182:185], v[206:209], v[82:85]
	v_mfma_f32_16x16x32_bf16 v[70:73], v[166:169], v[218:221], v[70:73]
	v_mfma_f32_16x16x32_bf16 v[66:69], v[182:185], v[218:221], v[66:69]
	s_setprio 0
	s_barrier
	s_add_i32 s53, s61, s31
	v_lshl_add_u64 v[174:175], s[34:35], 0, v[148:149]
	s_mov_b32 m0, s53
	ds_read_b128 v[186:189], v180 offset:16384
	ds_read_b128 v[190:193], v180 offset:17408
	ds_read_b128 v[194:197], v180 offset:18432
	ds_read_b128 v[198:201], v180 offset:19456
	ds_read_b128 v[202:205], v180 offset:20480
	ds_read_b128 v[206:209], v180 offset:21504
	ds_read_b128 v[210:213], v180 offset:22528
	ds_read_b128 v[218:221], v180 offset:23552
	global_load_lds_dwordx4 v[174:175], off
	s_add_i32 m0, s53, 0x2000
	s_add_u32 s54, s34, 0x160000
	v_lshl_add_u64 v[214:215], s[34:35], 0, v[152:153]
	s_addc_u32 s55, s35, 0
	s_add_i32 s53, s70, s31
	global_load_lds_dwordx4 v[214:215], off
	v_lshl_add_u64 v[222:223], s[54:55], 0, v[148:149]
	s_mov_b32 m0, s53
	v_lshl_add_u64 v[224:225], s[40:41], 0, v[150:151]
	global_load_lds_dwordx4 v[222:223], off
	v_lshl_add_u64 v[222:223], s[54:55], 0, v[152:153]
	s_add_i32 m0, s53, 0x2000
	s_nop 0
	global_load_lds_dwordx4 v[222:223], off
	v_lshl_add_u64 v[222:223], s[40:41], 0, v[146:147]
	s_mov_b32 m0, s33
	s_nop 0
	global_load_lds_dwordx4 v[222:223], off
	s_mov_b32 m0, s46
	s_nop 0
	global_load_lds_dwordx4 v[224:225], off
	s_waitcnt vmcnt(8)
	s_waitcnt lgkmcnt(0)
	s_barrier
	s_setprio 1
	s_waitcnt lgkmcnt(0)
	v_mfma_f32_16x16x32_bf16 v[62:65], v[130:133], v[186:189], v[62:65]
	v_mfma_f32_16x16x32_bf16 v[58:61], v[138:141], v[186:189], v[58:61]
	v_mfma_f32_16x16x32_bf16 v[50:53], v[130:133], v[194:197], v[50:53]
	v_mfma_f32_16x16x32_bf16 v[42:45], v[138:141], v[194:197], v[42:45]
	v_mfma_f32_16x16x32_bf16 v[38:41], v[130:133], v[202:205], v[38:41]
	v_mfma_f32_16x16x32_bf16 v[34:37], v[138:141], v[202:205], v[34:37]
	v_mfma_f32_16x16x32_bf16 v[14:17], v[130:133], v[210:213], v[14:17]
	v_mfma_f32_16x16x32_bf16 v[10:13], v[138:141], v[210:213], v[10:13]
	v_mfma_f32_16x16x32_bf16 v[62:65], v[134:137], v[190:193], v[62:65]
	v_mfma_f32_16x16x32_bf16 v[58:61], v[142:145], v[190:193], v[58:61]
	v_mfma_f32_16x16x32_bf16 v[50:53], v[134:137], v[198:201], v[50:53]
	v_mfma_f32_16x16x32_bf16 v[42:45], v[142:145], v[198:201], v[42:45]
	v_mfma_f32_16x16x32_bf16 v[38:41], v[134:137], v[206:209], v[38:41]
	v_mfma_f32_16x16x32_bf16 v[34:37], v[142:145], v[206:209], v[34:37]
	v_mfma_f32_16x16x32_bf16 v[14:17], v[134:137], v[218:221], v[14:17]
	v_mfma_f32_16x16x32_bf16 v[10:13], v[142:145], v[218:221], v[10:13]
	s_setprio 0
	s_setprio 1
	v_mfma_f32_16x16x32_bf16 v[54:57], v[162:165], v[186:189], v[54:57]
	v_mfma_f32_16x16x32_bf16 v[46:49], v[170:173], v[186:189], v[46:49]
	v_mfma_f32_16x16x32_bf16 v[30:33], v[162:165], v[194:197], v[30:33]
	v_mfma_f32_16x16x32_bf16 v[26:29], v[170:173], v[194:197], v[26:29]
	v_mfma_f32_16x16x32_bf16 v[22:25], v[162:165], v[202:205], v[22:25]
	v_mfma_f32_16x16x32_bf16 v[18:21], v[170:173], v[202:205], v[18:21]
	v_mfma_f32_16x16x32_bf16 v[6:9], v[162:165], v[210:213], v[6:9]
	v_mfma_f32_16x16x32_bf16 v[2:5], v[170:173], v[210:213], v[2:5]
	v_mfma_f32_16x16x32_bf16 v[54:57], v[166:169], v[190:193], v[54:57]
	v_mfma_f32_16x16x32_bf16 v[46:49], v[182:185], v[190:193], v[46:49]
	v_mfma_f32_16x16x32_bf16 v[30:33], v[166:169], v[198:201], v[30:33]
	v_mfma_f32_16x16x32_bf16 v[26:29], v[182:185], v[198:201], v[26:29]
	v_mfma_f32_16x16x32_bf16 v[22:25], v[166:169], v[206:209], v[22:25]
	v_mfma_f32_16x16x32_bf16 v[18:21], v[182:185], v[206:209], v[18:21]
	v_mfma_f32_16x16x32_bf16 v[6:9], v[166:169], v[218:221], v[6:9]
	v_mfma_f32_16x16x32_bf16 v[2:5], v[182:185], v[218:221], v[2:5]
	s_setprio 0
	s_barrier
	s_add_i32 s53, 0, 0x18000
	s_add_i32 s54, 0, 0x1c000
	v_add_u32_e32 v142, s53, v176
	v_add_u32_e32 v181, 0x19000, v176
	ds_read_b128 v[130:133], v142
	ds_read_b128 v[134:137], v142 offset:1024
	ds_read_b128 v[138:141], v142 offset:2048
	ds_read_b128 v[142:145], v142 offset:3072
	ds_read_b128 v[162:165], v181
	ds_read_b128 v[166:169], v181 offset:1024
	ds_read_b128 v[170:173], v181 offset:2048
	ds_read_b128 v[182:185], v181 offset:3072
	s_add_u32 s40, s40, 0x160000
	s_addc_u32 s41, s41, 0
	s_mov_b32 m0, s47
	v_lshl_add_u64 v[226:227], s[40:41], 0, v[146:147]
	ds_read_b128 v[186:189], v180 offset:32768
	ds_read_b128 v[190:193], v180 offset:33792
	ds_read_b128 v[194:197], v180 offset:34816
	ds_read_b128 v[198:201], v180 offset:35840
	ds_read_b128 v[202:205], v180 offset:36864
	ds_read_b128 v[206:209], v180 offset:37888
	ds_read_b128 v[210:213], v180 offset:38912
	ds_read_b128 v[218:221], v180 offset:39936
	global_load_lds_dwordx4 v[226:227], off
	v_lshl_add_u64 v[226:227], s[40:41], 0, v[150:151]
	s_mov_b32 m0, s56
	s_nop 0
	global_load_lds_dwordx4 v[226:227], off
	s_waitcnt vmcnt(8)
	s_waitcnt lgkmcnt(0)
	s_barrier
	s_setprio 1
	s_waitcnt lgkmcnt(0)
	v_mfma_f32_16x16x32_bf16 v[126:129], v[130:133], v[186:189], v[126:129]
	v_mfma_f32_16x16x32_bf16 v[122:125], v[138:141], v[186:189], v[122:125]
	v_mfma_f32_16x16x32_bf16 v[110:113], v[130:133], v[194:197], v[110:113]
	v_mfma_f32_16x16x32_bf16 v[106:109], v[138:141], v[194:197], v[106:109]
	v_mfma_f32_16x16x32_bf16 v[94:97], v[130:133], v[202:205], v[94:97]
	v_mfma_f32_16x16x32_bf16 v[90:93], v[138:141], v[202:205], v[90:93]
	v_mfma_f32_16x16x32_bf16 v[78:81], v[130:133], v[210:213], v[78:81]
	v_mfma_f32_16x16x32_bf16 v[74:77], v[138:141], v[210:213], v[74:77]
	v_mfma_f32_16x16x32_bf16 v[126:129], v[134:137], v[190:193], v[126:129]
	v_mfma_f32_16x16x32_bf16 v[122:125], v[142:145], v[190:193], v[122:125]
	v_mfma_f32_16x16x32_bf16 v[110:113], v[134:137], v[198:201], v[110:113]
	v_mfma_f32_16x16x32_bf16 v[106:109], v[142:145], v[198:201], v[106:109]
	v_mfma_f32_16x16x32_bf16 v[94:97], v[134:137], v[206:209], v[94:97]
	v_mfma_f32_16x16x32_bf16 v[90:93], v[142:145], v[206:209], v[90:93]
	v_mfma_f32_16x16x32_bf16 v[78:81], v[134:137], v[218:221], v[78:81]
	v_mfma_f32_16x16x32_bf16 v[74:77], v[142:145], v[218:221], v[74:77]
	s_setprio 0
	s_setprio 1
	v_mfma_f32_16x16x32_bf16 v[118:121], v[162:165], v[186:189], v[118:121]
	v_mfma_f32_16x16x32_bf16 v[114:117], v[170:173], v[186:189], v[114:117]
	v_mfma_f32_16x16x32_bf16 v[102:105], v[162:165], v[194:197], v[102:105]
	v_mfma_f32_16x16x32_bf16 v[98:101], v[170:173], v[194:197], v[98:101]
	v_mfma_f32_16x16x32_bf16 v[86:89], v[162:165], v[202:205], v[86:89]
	v_mfma_f32_16x16x32_bf16 v[82:85], v[170:173], v[202:205], v[82:85]
	v_mfma_f32_16x16x32_bf16 v[70:73], v[162:165], v[210:213], v[70:73]
	v_mfma_f32_16x16x32_bf16 v[66:69], v[170:173], v[210:213], v[66:69]
	v_mfma_f32_16x16x32_bf16 v[118:121], v[166:169], v[190:193], v[118:121]
	v_mfma_f32_16x16x32_bf16 v[114:117], v[182:185], v[190:193], v[114:117]
	v_mfma_f32_16x16x32_bf16 v[102:105], v[166:169], v[198:201], v[102:105]
	v_mfma_f32_16x16x32_bf16 v[98:101], v[182:185], v[198:201], v[98:101]
	v_mfma_f32_16x16x32_bf16 v[86:89], v[166:169], v[206:209], v[86:89]
	v_mfma_f32_16x16x32_bf16 v[82:85], v[182:185], v[206:209], v[82:85]
	v_mfma_f32_16x16x32_bf16 v[70:73], v[166:169], v[218:221], v[70:73]
	v_mfma_f32_16x16x32_bf16 v[66:69], v[182:185], v[218:221], v[66:69]
	s_setprio 0
	s_barrier
	s_add_i32 s40, s53, s31
	v_lshl_add_u64 v[174:175], v[174:175], 0, s[24:25]
	s_mov_b32 m0, s40
	ds_read_b128 v[186:189], v180 offset:49152
	ds_read_b128 v[190:193], v180 offset:50176
	ds_read_b128 v[194:197], v180 offset:51200
	ds_read_b128 v[198:201], v180 offset:52224
	ds_read_b128 v[202:205], v180 offset:53248
	ds_read_b128 v[206:209], v180 offset:54272
	ds_read_b128 v[210:213], v180 offset:55296
	ds_read_b128 v[218:221], v180 offset:56320
	global_load_lds_dwordx4 v[174:175], off
	s_add_i32 m0, s40, 0x2000
	s_add_u32 s34, s34, 0x160080
	v_lshl_add_u64 v[174:175], v[214:215], 0, s[24:25]
	s_addc_u32 s35, s35, 0
	s_add_i32 s40, s54, s31
	global_load_lds_dwordx4 v[174:175], off
	v_lshl_add_u64 v[174:175], s[34:35], 0, v[148:149]
	s_mov_b32 m0, s40
	s_nop 0
	global_load_lds_dwordx4 v[174:175], off
	v_lshl_add_u64 v[174:175], s[34:35], 0, v[152:153]
	s_add_i32 m0, s40, 0x2000
	s_nop 0
	global_load_lds_dwordx4 v[174:175], off
	v_lshl_add_u64 v[174:175], v[222:223], 0, s[24:25]
	s_mov_b32 m0, s58
	s_nop 0
	global_load_lds_dwordx4 v[174:175], off
	v_lshl_add_u64 v[174:175], v[224:225], 0, s[24:25]
	s_mov_b32 m0, s59
	s_nop 0
	global_load_lds_dwordx4 v[174:175], off
	s_waitcnt vmcnt(8)
	s_waitcnt lgkmcnt(0)
	s_barrier
	s_setprio 1
	s_waitcnt lgkmcnt(0)
	v_mfma_f32_16x16x32_bf16 v[62:65], v[130:133], v[186:189], v[62:65]
	v_mfma_f32_16x16x32_bf16 v[58:61], v[138:141], v[186:189], v[58:61]
	v_mfma_f32_16x16x32_bf16 v[50:53], v[130:133], v[194:197], v[50:53]
	v_mfma_f32_16x16x32_bf16 v[42:45], v[138:141], v[194:197], v[42:45]
	v_mfma_f32_16x16x32_bf16 v[38:41], v[130:133], v[202:205], v[38:41]
	v_mfma_f32_16x16x32_bf16 v[34:37], v[138:141], v[202:205], v[34:37]
	v_mfma_f32_16x16x32_bf16 v[14:17], v[130:133], v[210:213], v[14:17]
	v_mfma_f32_16x16x32_bf16 v[10:13], v[138:141], v[210:213], v[10:13]
	v_mfma_f32_16x16x32_bf16 v[62:65], v[134:137], v[190:193], v[62:65]
	v_mfma_f32_16x16x32_bf16 v[58:61], v[142:145], v[190:193], v[58:61]
	v_mfma_f32_16x16x32_bf16 v[50:53], v[134:137], v[198:201], v[50:53]
	v_mfma_f32_16x16x32_bf16 v[42:45], v[142:145], v[198:201], v[42:45]
	v_mfma_f32_16x16x32_bf16 v[38:41], v[134:137], v[206:209], v[38:41]
	v_mfma_f32_16x16x32_bf16 v[34:37], v[142:145], v[206:209], v[34:37]
	v_mfma_f32_16x16x32_bf16 v[14:17], v[134:137], v[218:221], v[14:17]
	v_mfma_f32_16x16x32_bf16 v[10:13], v[142:145], v[218:221], v[10:13]
	s_setprio 0
	s_setprio 1
	v_mfma_f32_16x16x32_bf16 v[54:57], v[162:165], v[186:189], v[54:57]
	v_mfma_f32_16x16x32_bf16 v[46:49], v[170:173], v[186:189], v[46:49]
	v_mfma_f32_16x16x32_bf16 v[30:33], v[162:165], v[194:197], v[30:33]
	v_mfma_f32_16x16x32_bf16 v[26:29], v[170:173], v[194:197], v[26:29]
	v_mfma_f32_16x16x32_bf16 v[22:25], v[162:165], v[202:205], v[22:25]
	v_mfma_f32_16x16x32_bf16 v[18:21], v[170:173], v[202:205], v[18:21]
	v_mfma_f32_16x16x32_bf16 v[6:9], v[162:165], v[210:213], v[6:9]
	v_mfma_f32_16x16x32_bf16 v[2:5], v[170:173], v[210:213], v[2:5]
	v_mfma_f32_16x16x32_bf16 v[54:57], v[166:169], v[190:193], v[54:57]
	v_mfma_f32_16x16x32_bf16 v[46:49], v[182:185], v[190:193], v[46:49]
	v_mfma_f32_16x16x32_bf16 v[30:33], v[166:169], v[198:201], v[30:33]
	v_mfma_f32_16x16x32_bf16 v[26:29], v[182:185], v[198:201], v[26:29]
	v_mfma_f32_16x16x32_bf16 v[22:25], v[166:169], v[206:209], v[22:25]
	v_mfma_f32_16x16x32_bf16 v[18:21], v[182:185], v[206:209], v[18:21]
	v_mfma_f32_16x16x32_bf16 v[6:9], v[166:169], v[218:221], v[6:9]
	v_mfma_f32_16x16x32_bf16 v[2:5], v[182:185], v[218:221], v[2:5]
	s_setprio 0
	s_barrier
	s_add_i32 s52, s52, 2
	s_add_u32 s38, s38, 0x100
	s_addc_u32 s39, s39, 0
	s_add_u32 s0, s0, 0x100
	s_addc_u32 s1, s1, 0
	s_cmpk_gt_u32 s52, 0x55
	s_cbranch_scc0 .LBB0_2089
	v_lshl_or_b32 v130, s74, 8, v177
	v_lshl_add_u32 v162, s73, 8, v1
	v_ashrrev_i32_e32 v131, 31, v130
	v_lshlrev_b64 v[164:165], 1, v[130:131]
	v_or_b32_e32 v130, 16, v162
	v_ashrrev_i32_e32 v163, 31, v162
	v_ashrrev_i32_e32 v131, 31, v130
	v_lshlrev_b64 v[132:133], 12, v[162:163]
	v_lshlrev_b64 v[130:131], 12, v[130:131]
	v_lshl_add_u64 v[132:133], s[64:65], 0, v[132:133]
	v_lshl_add_u64 v[130:131], s[64:65], 0, v[130:131]
	v_lshl_add_u64 v[174:175], v[132:133], 0, v[164:165]
	v_lshl_add_u64 v[172:173], v[130:131], 0, v[164:165]
	v_mov_b32_e32 v209, 0
	v_mov_b32_e32 v208, 0x10000
	v_lshl_add_u64 v[194:195], v[208:209], 0, v[174:175]
	v_mov_b32_e32 v208, 0x20000
	v_lshl_add_u64 v[196:197], v[208:209], 0, v[174:175]
	v_mov_b32_e32 v208, 0x30000
	v_lshl_add_u64 v[198:199], v[208:209], 0, v[174:175]
	v_mov_b32_e32 v208, 0x80000
	v_lshl_add_u64 v[200:201], v[208:209], 0, v[174:175]
	v_mov_b32_e32 v208, 0x90000
	v_lshl_add_u64 v[202:203], v[208:209], 0, v[174:175]
	v_mov_b32_e32 v208, 0xa0000
	v_lshl_add_u64 v[204:205], v[208:209], 0, v[174:175]
	v_mov_b32_e32 v208, 0xb0000
	v_lshl_add_u64 v[206:207], v[208:209], 0, v[174:175]
	global_load_dwordx4 v[130:133], v[174:175], off
	global_load_dwordx4 v[134:137], v[174:175], off offset:64
	global_load_dwordx4 v[138:141], v[194:195], off
	global_load_dwordx4 v[142:145], v[194:195], off offset:64
	global_load_dwordx4 v[162:165], v[196:197], off
	global_load_dwordx4 v[166:169], v[196:197], off offset:64
	global_load_dwordx4 v[170:173], v[198:199], off
	global_load_dwordx4 v[182:185], v[198:199], off offset:64
	s_and_b64 vcc, exec, s[26:27]
	s_cbranch_vccz .LBB0_2092
	s_barrier
.LBB0_2092:
	s_waitcnt vmcnt(7)
	v_cvt_f32_f16_e32 v186, v130
	v_cvt_f32_f16_sdwa v187, v130 dst_sel:DWORD dst_unused:UNUSED_PAD src0_sel:WORD_1
	v_cvt_f32_f16_e32 v188, v131
	v_cvt_f32_f16_sdwa v189, v131 dst_sel:DWORD dst_unused:UNUSED_PAD src0_sel:WORD_1
	v_cvt_f32_f16_e32 v190, v132
	v_cvt_f32_f16_sdwa v191, v132 dst_sel:DWORD dst_unused:UNUSED_PAD src0_sel:WORD_1
	v_cvt_f32_f16_e32 v192, v133
	v_cvt_f32_f16_sdwa v193, v133 dst_sel:DWORD dst_unused:UNUSED_PAD src0_sel:WORD_1
	global_load_dwordx4 v[130:133], v[200:201], off
	v_pk_fma_f32 v[126:127], v[126:127], 0.5, v[186:187] op_sel_hi:[1,0,1]
	v_pk_fma_f32 v[128:129], v[128:129], 0.5, v[188:189] op_sel_hi:[1,0,1]
	v_pk_fma_f32 v[122:123], v[122:123], 0.5, v[190:191] op_sel_hi:[1,0,1]
	v_pk_fma_f32 v[124:125], v[124:125], 0.5, v[192:193] op_sel_hi:[1,0,1]
	v_cvt_pk_f16_f32 v125, v124, v125
	v_cvt_pk_f16_f32 v124, v122, v123
	v_cvt_pk_f16_f32 v123, v128, v129
	v_cvt_pk_f16_f32 v122, v126, v127
	global_store_dwordx4 v[174:175], v[122:125], off
	s_waitcnt vmcnt(8)
	v_cvt_f32_f16_e32 v186, v134
	v_cvt_f32_f16_sdwa v187, v134 dst_sel:DWORD dst_unused:UNUSED_PAD src0_sel:WORD_1
	v_cvt_f32_f16_e32 v188, v135
	v_cvt_f32_f16_sdwa v189, v135 dst_sel:DWORD dst_unused:UNUSED_PAD src0_sel:WORD_1
	v_cvt_f32_f16_e32 v190, v136
	v_cvt_f32_f16_sdwa v191, v136 dst_sel:DWORD dst_unused:UNUSED_PAD src0_sel:WORD_1
	v_cvt_f32_f16_e32 v192, v137
	v_cvt_f32_f16_sdwa v193, v137 dst_sel:DWORD dst_unused:UNUSED_PAD src0_sel:WORD_1
	global_load_dwordx4 v[134:137], v[200:201], off offset:64
	v_pk_fma_f32 v[118:119], v[118:119], 0.5, v[186:187] op_sel_hi:[1,0,1]
	v_pk_fma_f32 v[120:121], v[120:121], 0.5, v[188:189] op_sel_hi:[1,0,1]
	v_pk_fma_f32 v[114:115], v[114:115], 0.5, v[190:191] op_sel_hi:[1,0,1]
	v_pk_fma_f32 v[116:117], v[116:117], 0.5, v[192:193] op_sel_hi:[1,0,1]
	v_cvt_pk_f16_f32 v117, v116, v117
	v_cvt_pk_f16_f32 v116, v114, v115
	v_cvt_pk_f16_f32 v115, v120, v121
	v_cvt_pk_f16_f32 v114, v118, v119
	global_store_dwordx4 v[174:175], v[114:117], off offset:64
	s_waitcnt vmcnt(9)
	v_cvt_f32_f16_e32 v186, v138
	v_cvt_f32_f16_sdwa v187, v138 dst_sel:DWORD dst_unused:UNUSED_PAD src0_sel:WORD_1
	v_cvt_f32_f16_e32 v188, v139
	v_cvt_f32_f16_sdwa v189, v139 dst_sel:DWORD dst_unused:UNUSED_PAD src0_sel:WORD_1
	v_cvt_f32_f16_e32 v190, v140
	v_cvt_f32_f16_sdwa v191, v140 dst_sel:DWORD dst_unused:UNUSED_PAD src0_sel:WORD_1
	v_cvt_f32_f16_e32 v192, v141
	v_cvt_f32_f16_sdwa v193, v141 dst_sel:DWORD dst_unused:UNUSED_PAD src0_sel:WORD_1
	global_load_dwordx4 v[138:141], v[202:203], off
	v_pk_fma_f32 v[110:111], v[110:111], 0.5, v[186:187] op_sel_hi:[1,0,1]
	v_pk_fma_f32 v[112:113], v[112:113], 0.5, v[188:189] op_sel_hi:[1,0,1]
	v_pk_fma_f32 v[106:107], v[106:107], 0.5, v[190:191] op_sel_hi:[1,0,1]
	v_pk_fma_f32 v[108:109], v[108:109], 0.5, v[192:193] op_sel_hi:[1,0,1]
	v_cvt_pk_f16_f32 v109, v108, v109
	v_cvt_pk_f16_f32 v108, v106, v107
	v_cvt_pk_f16_f32 v107, v112, v113
	v_cvt_pk_f16_f32 v106, v110, v111
	global_store_dwordx4 v[194:195], v[106:109], off
	s_waitcnt vmcnt(10)
	v_cvt_f32_f16_e32 v186, v142
	v_cvt_f32_f16_sdwa v187, v142 dst_sel:DWORD dst_unused:UNUSED_PAD src0_sel:WORD_1
	v_cvt_f32_f16_e32 v188, v143
	v_cvt_f32_f16_sdwa v189, v143 dst_sel:DWORD dst_unused:UNUSED_PAD src0_sel:WORD_1
	v_cvt_f32_f16_e32 v190, v144
	v_cvt_f32_f16_sdwa v191, v144 dst_sel:DWORD dst_unused:UNUSED_PAD src0_sel:WORD_1
	v_cvt_f32_f16_e32 v192, v145
	v_cvt_f32_f16_sdwa v193, v145 dst_sel:DWORD dst_unused:UNUSED_PAD src0_sel:WORD_1
	global_load_dwordx4 v[142:145], v[202:203], off offset:64
	v_pk_fma_f32 v[102:103], v[102:103], 0.5, v[186:187] op_sel_hi:[1,0,1]
	v_pk_fma_f32 v[104:105], v[104:105], 0.5, v[188:189] op_sel_hi:[1,0,1]
	v_pk_fma_f32 v[98:99], v[98:99], 0.5, v[190:191] op_sel_hi:[1,0,1]
	v_pk_fma_f32 v[100:101], v[100:101], 0.5, v[192:193] op_sel_hi:[1,0,1]
	v_cvt_pk_f16_f32 v101, v100, v101
	v_cvt_pk_f16_f32 v100, v98, v99
	v_cvt_pk_f16_f32 v99, v104, v105
	v_cvt_pk_f16_f32 v98, v102, v103
	global_store_dwordx4 v[194:195], v[98:101], off offset:64
	s_waitcnt vmcnt(11)
	v_cvt_f32_f16_e32 v186, v162
	v_cvt_f32_f16_sdwa v187, v162 dst_sel:DWORD dst_unused:UNUSED_PAD src0_sel:WORD_1
	v_cvt_f32_f16_e32 v188, v163
	v_cvt_f32_f16_sdwa v189, v163 dst_sel:DWORD dst_unused:UNUSED_PAD src0_sel:WORD_1
	v_cvt_f32_f16_e32 v190, v164
	v_cvt_f32_f16_sdwa v191, v164 dst_sel:DWORD dst_unused:UNUSED_PAD src0_sel:WORD_1
	v_cvt_f32_f16_e32 v192, v165
	v_cvt_f32_f16_sdwa v193, v165 dst_sel:DWORD dst_unused:UNUSED_PAD src0_sel:WORD_1
	global_load_dwordx4 v[162:165], v[204:205], off
	v_pk_fma_f32 v[94:95], v[94:95], 0.5, v[186:187] op_sel_hi:[1,0,1]
	v_pk_fma_f32 v[96:97], v[96:97], 0.5, v[188:189] op_sel_hi:[1,0,1]
	v_pk_fma_f32 v[90:91], v[90:91], 0.5, v[190:191] op_sel_hi:[1,0,1]
	v_pk_fma_f32 v[92:93], v[92:93], 0.5, v[192:193] op_sel_hi:[1,0,1]
	v_cvt_pk_f16_f32 v93, v92, v93
	v_cvt_pk_f16_f32 v92, v90, v91
	v_cvt_pk_f16_f32 v91, v96, v97
	v_cvt_pk_f16_f32 v90, v94, v95
	global_store_dwordx4 v[196:197], v[90:93], off
	s_waitcnt vmcnt(12)
	v_cvt_f32_f16_e32 v186, v166
	v_cvt_f32_f16_sdwa v187, v166 dst_sel:DWORD dst_unused:UNUSED_PAD src0_sel:WORD_1
	v_cvt_f32_f16_e32 v188, v167
	v_cvt_f32_f16_sdwa v189, v167 dst_sel:DWORD dst_unused:UNUSED_PAD src0_sel:WORD_1
	v_cvt_f32_f16_e32 v190, v168
	v_cvt_f32_f16_sdwa v191, v168 dst_sel:DWORD dst_unused:UNUSED_PAD src0_sel:WORD_1
	v_cvt_f32_f16_e32 v192, v169
	v_cvt_f32_f16_sdwa v193, v169 dst_sel:DWORD dst_unused:UNUSED_PAD src0_sel:WORD_1
	global_load_dwordx4 v[166:169], v[204:205], off offset:64
	v_pk_fma_f32 v[86:87], v[86:87], 0.5, v[186:187] op_sel_hi:[1,0,1]
	v_pk_fma_f32 v[88:89], v[88:89], 0.5, v[188:189] op_sel_hi:[1,0,1]
	v_pk_fma_f32 v[82:83], v[82:83], 0.5, v[190:191] op_sel_hi:[1,0,1]
	v_pk_fma_f32 v[84:85], v[84:85], 0.5, v[192:193] op_sel_hi:[1,0,1]
	v_cvt_pk_f16_f32 v85, v84, v85
	v_cvt_pk_f16_f32 v84, v82, v83
	v_cvt_pk_f16_f32 v83, v88, v89
	v_cvt_pk_f16_f32 v82, v86, v87
	global_store_dwordx4 v[196:197], v[82:85], off offset:64
	s_waitcnt vmcnt(13)
	v_cvt_f32_f16_e32 v186, v170
	v_cvt_f32_f16_sdwa v187, v170 dst_sel:DWORD dst_unused:UNUSED_PAD src0_sel:WORD_1
	v_cvt_f32_f16_e32 v188, v171
	v_cvt_f32_f16_sdwa v189, v171 dst_sel:DWORD dst_unused:UNUSED_PAD src0_sel:WORD_1
	v_cvt_f32_f16_e32 v190, v172
	v_cvt_f32_f16_sdwa v191, v172 dst_sel:DWORD dst_unused:UNUSED_PAD src0_sel:WORD_1
	v_cvt_f32_f16_e32 v192, v173
	v_cvt_f32_f16_sdwa v193, v173 dst_sel:DWORD dst_unused:UNUSED_PAD src0_sel:WORD_1
	global_load_dwordx4 v[170:173], v[206:207], off
	v_pk_fma_f32 v[78:79], v[78:79], 0.5, v[186:187] op_sel_hi:[1,0,1]
	v_pk_fma_f32 v[80:81], v[80:81], 0.5, v[188:189] op_sel_hi:[1,0,1]
	v_pk_fma_f32 v[74:75], v[74:75], 0.5, v[190:191] op_sel_hi:[1,0,1]
	v_pk_fma_f32 v[76:77], v[76:77], 0.5, v[192:193] op_sel_hi:[1,0,1]
	v_cvt_pk_f16_f32 v77, v76, v77
	v_cvt_pk_f16_f32 v76, v74, v75
	v_cvt_pk_f16_f32 v75, v80, v81
	v_cvt_pk_f16_f32 v74, v78, v79
	global_store_dwordx4 v[198:199], v[74:77], off
	s_waitcnt vmcnt(14)
	v_cvt_f32_f16_e32 v186, v182
	v_cvt_f32_f16_sdwa v187, v182 dst_sel:DWORD dst_unused:UNUSED_PAD src0_sel:WORD_1
	v_cvt_f32_f16_e32 v188, v183
	v_cvt_f32_f16_sdwa v189, v183 dst_sel:DWORD dst_unused:UNUSED_PAD src0_sel:WORD_1
	v_cvt_f32_f16_e32 v190, v184
	v_cvt_f32_f16_sdwa v191, v184 dst_sel:DWORD dst_unused:UNUSED_PAD src0_sel:WORD_1
	v_cvt_f32_f16_e32 v192, v185
	v_cvt_f32_f16_sdwa v193, v185 dst_sel:DWORD dst_unused:UNUSED_PAD src0_sel:WORD_1
	global_load_dwordx4 v[182:185], v[206:207], off offset:64
	v_pk_fma_f32 v[70:71], v[70:71], 0.5, v[186:187] op_sel_hi:[1,0,1]
	v_pk_fma_f32 v[72:73], v[72:73], 0.5, v[188:189] op_sel_hi:[1,0,1]
	v_pk_fma_f32 v[66:67], v[66:67], 0.5, v[190:191] op_sel_hi:[1,0,1]
	v_pk_fma_f32 v[68:69], v[68:69], 0.5, v[192:193] op_sel_hi:[1,0,1]
	v_cvt_pk_f16_f32 v69, v68, v69
	v_cvt_pk_f16_f32 v68, v66, v67
	v_cvt_pk_f16_f32 v67, v72, v73
	v_cvt_pk_f16_f32 v66, v70, v71
	global_store_dwordx4 v[198:199], v[66:69], off offset:64
	s_waitcnt vmcnt(15)
	v_cvt_f32_f16_e32 v186, v130
	v_cvt_f32_f16_sdwa v187, v130 dst_sel:DWORD dst_unused:UNUSED_PAD src0_sel:WORD_1
	v_cvt_f32_f16_e32 v188, v131
	v_cvt_f32_f16_sdwa v189, v131 dst_sel:DWORD dst_unused:UNUSED_PAD src0_sel:WORD_1
	v_cvt_f32_f16_e32 v190, v132
	v_cvt_f32_f16_sdwa v191, v132 dst_sel:DWORD dst_unused:UNUSED_PAD src0_sel:WORD_1
	v_cvt_f32_f16_e32 v192, v133
	v_cvt_f32_f16_sdwa v193, v133 dst_sel:DWORD dst_unused:UNUSED_PAD src0_sel:WORD_1
	v_pk_fma_f32 v[62:63], v[62:63], 0.5, v[186:187] op_sel_hi:[1,0,1]
	v_pk_fma_f32 v[64:65], v[64:65], 0.5, v[188:189] op_sel_hi:[1,0,1]
	v_pk_fma_f32 v[58:59], v[58:59], 0.5, v[190:191] op_sel_hi:[1,0,1]
	v_pk_fma_f32 v[60:61], v[60:61], 0.5, v[192:193] op_sel_hi:[1,0,1]
	v_cvt_pk_f16_f32 v61, v60, v61
	v_cvt_pk_f16_f32 v60, v58, v59
	v_cvt_pk_f16_f32 v59, v64, v65
	v_cvt_pk_f16_f32 v58, v62, v63
	global_store_dwordx4 v[200:201], v[58:61], off
	s_waitcnt vmcnt(14)
	v_cvt_f32_f16_e32 v186, v134
	v_cvt_f32_f16_sdwa v187, v134 dst_sel:DWORD dst_unused:UNUSED_PAD src0_sel:WORD_1
	v_cvt_f32_f16_e32 v188, v135
	v_cvt_f32_f16_sdwa v189, v135 dst_sel:DWORD dst_unused:UNUSED_PAD src0_sel:WORD_1
	v_cvt_f32_f16_e32 v190, v136
	v_cvt_f32_f16_sdwa v191, v136 dst_sel:DWORD dst_unused:UNUSED_PAD src0_sel:WORD_1
	v_cvt_f32_f16_e32 v192, v137
	v_cvt_f32_f16_sdwa v193, v137 dst_sel:DWORD dst_unused:UNUSED_PAD src0_sel:WORD_1
	v_pk_fma_f32 v[54:55], v[54:55], 0.5, v[186:187] op_sel_hi:[1,0,1]
	v_pk_fma_f32 v[56:57], v[56:57], 0.5, v[188:189] op_sel_hi:[1,0,1]
	v_pk_fma_f32 v[46:47], v[46:47], 0.5, v[190:191] op_sel_hi:[1,0,1]
	v_pk_fma_f32 v[48:49], v[48:49], 0.5, v[192:193] op_sel_hi:[1,0,1]
	v_cvt_pk_f16_f32 v49, v48, v49
	v_cvt_pk_f16_f32 v48, v46, v47
	v_cvt_pk_f16_f32 v47, v56, v57
	v_cvt_pk_f16_f32 v46, v54, v55
	global_store_dwordx4 v[200:201], v[46:49], off offset:64
	s_waitcnt vmcnt(13)
	v_cvt_f32_f16_e32 v186, v138
	v_cvt_f32_f16_sdwa v187, v138 dst_sel:DWORD dst_unused:UNUSED_PAD src0_sel:WORD_1
	v_cvt_f32_f16_e32 v188, v139
	v_cvt_f32_f16_sdwa v189, v139 dst_sel:DWORD dst_unused:UNUSED_PAD src0_sel:WORD_1
	v_cvt_f32_f16_e32 v190, v140
	v_cvt_f32_f16_sdwa v191, v140 dst_sel:DWORD dst_unused:UNUSED_PAD src0_sel:WORD_1
	v_cvt_f32_f16_e32 v192, v141
	v_cvt_f32_f16_sdwa v193, v141 dst_sel:DWORD dst_unused:UNUSED_PAD src0_sel:WORD_1
	v_pk_fma_f32 v[50:51], v[50:51], 0.5, v[186:187] op_sel_hi:[1,0,1]
	v_pk_fma_f32 v[52:53], v[52:53], 0.5, v[188:189] op_sel_hi:[1,0,1]
	v_pk_fma_f32 v[42:43], v[42:43], 0.5, v[190:191] op_sel_hi:[1,0,1]
	v_pk_fma_f32 v[44:45], v[44:45], 0.5, v[192:193] op_sel_hi:[1,0,1]
	v_cvt_pk_f16_f32 v45, v44, v45
	v_cvt_pk_f16_f32 v44, v42, v43
	v_cvt_pk_f16_f32 v43, v52, v53
	v_cvt_pk_f16_f32 v42, v50, v51
	global_store_dwordx4 v[202:203], v[42:45], off
	s_waitcnt vmcnt(12)
	v_cvt_f32_f16_e32 v186, v142
	v_cvt_f32_f16_sdwa v187, v142 dst_sel:DWORD dst_unused:UNUSED_PAD src0_sel:WORD_1
	v_cvt_f32_f16_e32 v188, v143
	v_cvt_f32_f16_sdwa v189, v143 dst_sel:DWORD dst_unused:UNUSED_PAD src0_sel:WORD_1
	v_cvt_f32_f16_e32 v190, v144
	v_cvt_f32_f16_sdwa v191, v144 dst_sel:DWORD dst_unused:UNUSED_PAD src0_sel:WORD_1
	v_cvt_f32_f16_e32 v192, v145
	v_cvt_f32_f16_sdwa v193, v145 dst_sel:DWORD dst_unused:UNUSED_PAD src0_sel:WORD_1
	v_pk_fma_f32 v[30:31], v[30:31], 0.5, v[186:187] op_sel_hi:[1,0,1]
	v_pk_fma_f32 v[32:33], v[32:33], 0.5, v[188:189] op_sel_hi:[1,0,1]
	v_pk_fma_f32 v[26:27], v[26:27], 0.5, v[190:191] op_sel_hi:[1,0,1]
	v_pk_fma_f32 v[28:29], v[28:29], 0.5, v[192:193] op_sel_hi:[1,0,1]
	v_cvt_pk_f16_f32 v29, v28, v29
	v_cvt_pk_f16_f32 v28, v26, v27
	v_cvt_pk_f16_f32 v27, v32, v33
	v_cvt_pk_f16_f32 v26, v30, v31
	global_store_dwordx4 v[202:203], v[26:29], off offset:64
	s_waitcnt vmcnt(11)
	v_cvt_f32_f16_e32 v186, v162
	v_cvt_f32_f16_sdwa v187, v162 dst_sel:DWORD dst_unused:UNUSED_PAD src0_sel:WORD_1
	v_cvt_f32_f16_e32 v188, v163
	v_cvt_f32_f16_sdwa v189, v163 dst_sel:DWORD dst_unused:UNUSED_PAD src0_sel:WORD_1
	v_cvt_f32_f16_e32 v190, v164
	v_cvt_f32_f16_sdwa v191, v164 dst_sel:DWORD dst_unused:UNUSED_PAD src0_sel:WORD_1
	v_cvt_f32_f16_e32 v192, v165
	v_cvt_f32_f16_sdwa v193, v165 dst_sel:DWORD dst_unused:UNUSED_PAD src0_sel:WORD_1
	v_pk_fma_f32 v[38:39], v[38:39], 0.5, v[186:187] op_sel_hi:[1,0,1]
	v_pk_fma_f32 v[40:41], v[40:41], 0.5, v[188:189] op_sel_hi:[1,0,1]
	v_pk_fma_f32 v[34:35], v[34:35], 0.5, v[190:191] op_sel_hi:[1,0,1]
	v_pk_fma_f32 v[36:37], v[36:37], 0.5, v[192:193] op_sel_hi:[1,0,1]
	v_cvt_pk_f16_f32 v37, v36, v37
	v_cvt_pk_f16_f32 v36, v34, v35
	v_cvt_pk_f16_f32 v35, v40, v41
	v_cvt_pk_f16_f32 v34, v38, v39
	global_store_dwordx4 v[204:205], v[34:37], off
	s_waitcnt vmcnt(10)
	v_cvt_f32_f16_e32 v186, v166
	v_cvt_f32_f16_sdwa v187, v166 dst_sel:DWORD dst_unused:UNUSED_PAD src0_sel:WORD_1
	v_cvt_f32_f16_e32 v188, v167
	v_cvt_f32_f16_sdwa v189, v167 dst_sel:DWORD dst_unused:UNUSED_PAD src0_sel:WORD_1
	v_cvt_f32_f16_e32 v190, v168
	v_cvt_f32_f16_sdwa v191, v168 dst_sel:DWORD dst_unused:UNUSED_PAD src0_sel:WORD_1
	v_cvt_f32_f16_e32 v192, v169
	v_cvt_f32_f16_sdwa v193, v169 dst_sel:DWORD dst_unused:UNUSED_PAD src0_sel:WORD_1
	v_pk_fma_f32 v[22:23], v[22:23], 0.5, v[186:187] op_sel_hi:[1,0,1]
	v_pk_fma_f32 v[24:25], v[24:25], 0.5, v[188:189] op_sel_hi:[1,0,1]
	v_pk_fma_f32 v[18:19], v[18:19], 0.5, v[190:191] op_sel_hi:[1,0,1]
	v_pk_fma_f32 v[20:21], v[20:21], 0.5, v[192:193] op_sel_hi:[1,0,1]
	v_cvt_pk_f16_f32 v21, v20, v21
	v_cvt_pk_f16_f32 v20, v18, v19
	v_cvt_pk_f16_f32 v19, v24, v25
	v_cvt_pk_f16_f32 v18, v22, v23
	global_store_dwordx4 v[204:205], v[18:21], off offset:64
	s_waitcnt vmcnt(9)
	v_cvt_f32_f16_e32 v186, v170
	v_cvt_f32_f16_sdwa v187, v170 dst_sel:DWORD dst_unused:UNUSED_PAD src0_sel:WORD_1
	v_cvt_f32_f16_e32 v188, v171
	v_cvt_f32_f16_sdwa v189, v171 dst_sel:DWORD dst_unused:UNUSED_PAD src0_sel:WORD_1
	v_cvt_f32_f16_e32 v190, v172
	v_cvt_f32_f16_sdwa v191, v172 dst_sel:DWORD dst_unused:UNUSED_PAD src0_sel:WORD_1
	v_cvt_f32_f16_e32 v192, v173
	v_cvt_f32_f16_sdwa v193, v173 dst_sel:DWORD dst_unused:UNUSED_PAD src0_sel:WORD_1
	v_pk_fma_f32 v[14:15], v[14:15], 0.5, v[186:187] op_sel_hi:[1,0,1]
	v_pk_fma_f32 v[16:17], v[16:17], 0.5, v[188:189] op_sel_hi:[1,0,1]
	v_pk_fma_f32 v[10:11], v[10:11], 0.5, v[190:191] op_sel_hi:[1,0,1]
	v_pk_fma_f32 v[12:13], v[12:13], 0.5, v[192:193] op_sel_hi:[1,0,1]
	v_cvt_pk_f16_f32 v13, v12, v13
	v_cvt_pk_f16_f32 v12, v10, v11
	v_cvt_pk_f16_f32 v11, v16, v17
	v_cvt_pk_f16_f32 v10, v14, v15
	global_store_dwordx4 v[206:207], v[10:13], off
	s_waitcnt vmcnt(8)
	v_cvt_f32_f16_e32 v186, v182
	v_cvt_f32_f16_sdwa v187, v182 dst_sel:DWORD dst_unused:UNUSED_PAD src0_sel:WORD_1
	v_cvt_f32_f16_e32 v188, v183
	v_cvt_f32_f16_sdwa v189, v183 dst_sel:DWORD dst_unused:UNUSED_PAD src0_sel:WORD_1
	v_cvt_f32_f16_e32 v190, v184
	v_cvt_f32_f16_sdwa v191, v184 dst_sel:DWORD dst_unused:UNUSED_PAD src0_sel:WORD_1
	v_cvt_f32_f16_e32 v192, v185
	v_cvt_f32_f16_sdwa v193, v185 dst_sel:DWORD dst_unused:UNUSED_PAD src0_sel:WORD_1
	v_pk_fma_f32 v[6:7], v[6:7], 0.5, v[186:187] op_sel_hi:[1,0,1]
	v_pk_fma_f32 v[8:9], v[8:9], 0.5, v[188:189] op_sel_hi:[1,0,1]
	v_pk_fma_f32 v[2:3], v[2:3], 0.5, v[190:191] op_sel_hi:[1,0,1]
	v_pk_fma_f32 v[4:5], v[4:5], 0.5, v[192:193] op_sel_hi:[1,0,1]
	v_cvt_pk_f16_f32 v5, v4, v5
	v_cvt_pk_f16_f32 v4, v2, v3
	v_cvt_pk_f16_f32 v3, v8, v9
	v_cvt_pk_f16_f32 v2, v6, v7
	global_store_dwordx4 v[206:207], v[2:5], off offset:64
	s_and_b64 vcc, exec, s[2:3]
	s_mov_b64 s[0:1], -1
	s_cbranch_vccnz .LBB0_2077
	s_andn2_b64 vcc, exec, s[8:9]
	s_cbranch_vccnz .LBB0_2076
	s_barrier
	s_branch .LBB0_2076

.LBB0_2938:
	ds_read_b128 v[130:133], v174
	ds_read_b128 v[134:137], v174 offset:1024
	ds_read_b128 v[138:141], v174 offset:2048
	ds_read_b128 v[158:161], v174 offset:3072
	ds_read_b128 v[162:165], v175
	ds_read_b128 v[166:169], v175 offset:1024
	ds_read_b128 v[178:181], v175 offset:2048
	ds_read_b128 v[182:185], v175 offset:3072
	s_add_u32 s34, s46, 0xfff80080
	s_addc_u32 s35, s47, -1
	s_cmp_eq_u32 s72, 28
	s_cselect_b32 s69, s0, s35
	s_cselect_b32 s68, s1, s34
	s_cselect_b32 s35, s37, s71
	s_cselect_b32 s34, s39, s70
	v_lshl_add_u64 v[170:171], s[46:47], 0, v[150:151]
	s_add_i32 m0, s33, 0xc000
	ds_read_b128 v[186:189], v176
	ds_read_b128 v[190:193], v176 offset:1024
	ds_read_b128 v[194:197], v176 offset:2048
	ds_read_b128 v[198:201], v176 offset:3072
	ds_read_b128 v[202:205], v176 offset:4096
	ds_read_b128 v[206:209], v176 offset:5120
	ds_read_b128 v[210:213], v176 offset:6144
	ds_read_b128 v[218:221], v176 offset:7168
	global_load_lds_dwordx4 v[170:171], off
	v_lshl_add_u64 v[170:171], s[46:47], 0, v[152:153]
	s_add_i32 m0, s33, 0xe000
	s_nop 0
	global_load_lds_dwordx4 v[170:171], off
	s_waitcnt vmcnt(8)
	s_waitcnt lgkmcnt(0)
	s_barrier
	s_setprio 1
	s_waitcnt lgkmcnt(0)
	v_mfma_f32_16x16x32_bf16 v[126:129], v[130:133], v[186:189], v[126:129]
	v_mfma_f32_16x16x32_bf16 v[122:125], v[138:141], v[186:189], v[122:125]
	v_mfma_f32_16x16x32_bf16 v[110:113], v[130:133], v[194:197], v[110:113]
	v_mfma_f32_16x16x32_bf16 v[106:109], v[138:141], v[194:197], v[106:109]
	v_mfma_f32_16x16x32_bf16 v[94:97], v[130:133], v[202:205], v[94:97]
	v_mfma_f32_16x16x32_bf16 v[90:93], v[138:141], v[202:205], v[90:93]
	v_mfma_f32_16x16x32_bf16 v[78:81], v[130:133], v[210:213], v[78:81]
	v_mfma_f32_16x16x32_bf16 v[74:77], v[138:141], v[210:213], v[74:77]
	v_mfma_f32_16x16x32_bf16 v[126:129], v[134:137], v[190:193], v[126:129]
	v_mfma_f32_16x16x32_bf16 v[122:125], v[158:161], v[190:193], v[122:125]
	v_mfma_f32_16x16x32_bf16 v[110:113], v[134:137], v[198:201], v[110:113]
	v_mfma_f32_16x16x32_bf16 v[106:109], v[158:161], v[198:201], v[106:109]
	v_mfma_f32_16x16x32_bf16 v[94:97], v[134:137], v[206:209], v[94:97]
	v_mfma_f32_16x16x32_bf16 v[90:93], v[158:161], v[206:209], v[90:93]
	v_mfma_f32_16x16x32_bf16 v[78:81], v[134:137], v[218:221], v[78:81]
	v_mfma_f32_16x16x32_bf16 v[74:77], v[158:161], v[218:221], v[74:77]
	s_setprio 0
	s_setprio 1
	v_mfma_f32_16x16x32_bf16 v[118:121], v[162:165], v[186:189], v[118:121]
	v_mfma_f32_16x16x32_bf16 v[114:117], v[178:181], v[186:189], v[114:117]
	v_mfma_f32_16x16x32_bf16 v[102:105], v[162:165], v[194:197], v[102:105]
	v_mfma_f32_16x16x32_bf16 v[98:101], v[178:181], v[194:197], v[98:101]
	v_mfma_f32_16x16x32_bf16 v[86:89], v[162:165], v[202:205], v[86:89]
	v_mfma_f32_16x16x32_bf16 v[82:85], v[178:181], v[202:205], v[82:85]
	v_mfma_f32_16x16x32_bf16 v[70:73], v[162:165], v[210:213], v[70:73]
	v_mfma_f32_16x16x32_bf16 v[66:69], v[178:181], v[210:213], v[66:69]
	v_mfma_f32_16x16x32_bf16 v[118:121], v[166:169], v[190:193], v[118:121]
	v_mfma_f32_16x16x32_bf16 v[114:117], v[182:185], v[190:193], v[114:117]
	v_mfma_f32_16x16x32_bf16 v[102:105], v[166:169], v[198:201], v[102:105]
	v_mfma_f32_16x16x32_bf16 v[98:101], v[182:185], v[198:201], v[98:101]
	v_mfma_f32_16x16x32_bf16 v[86:89], v[166:169], v[206:209], v[86:89]
	v_mfma_f32_16x16x32_bf16 v[82:85], v[182:185], v[206:209], v[82:85]
	v_mfma_f32_16x16x32_bf16 v[70:73], v[166:169], v[218:221], v[70:73]
	v_mfma_f32_16x16x32_bf16 v[66:69], v[182:185], v[218:221], v[66:69]
	s_setprio 0
	s_barrier
	s_add_i32 s62, s58, s31
	v_lshl_add_u64 v[170:171], s[34:35], 0, v[144:145]
	s_mov_b32 m0, s62
	ds_read_b128 v[186:189], v176 offset:16384
	ds_read_b128 v[190:193], v176 offset:17408
	ds_read_b128 v[194:197], v176 offset:18432
	ds_read_b128 v[198:201], v176 offset:19456
	ds_read_b128 v[202:205], v176 offset:20480
	ds_read_b128 v[206:209], v176 offset:21504
	ds_read_b128 v[210:213], v176 offset:22528
	ds_read_b128 v[218:221], v176 offset:23552
	global_load_lds_dwordx4 v[170:171], off
	s_add_i32 m0, s62, 0x2000
	s_add_u32 s62, s34, 0x80000
	v_lshl_add_u64 v[214:215], s[34:35], 0, v[148:149]
	s_addc_u32 s63, s35, 0
	s_add_i32 s66, s59, s31
	global_load_lds_dwordx4 v[214:215], off
	v_lshl_add_u64 v[222:223], s[62:63], 0, v[144:145]
	s_mov_b32 m0, s66
	v_lshl_add_u64 v[224:225], s[68:69], 0, v[146:147]
	global_load_lds_dwordx4 v[222:223], off
	v_lshl_add_u64 v[222:223], s[62:63], 0, v[148:149]
	s_add_i32 m0, s66, 0x2000
	s_nop 0
	global_load_lds_dwordx4 v[222:223], off
	v_lshl_add_u64 v[222:223], s[68:69], 0, v[142:143]
	s_mov_b32 m0, s33
	s_nop 0
	global_load_lds_dwordx4 v[222:223], off
	s_mov_b32 m0, s45
	s_nop 0
	global_load_lds_dwordx4 v[224:225], off
	s_waitcnt vmcnt(8)
	s_waitcnt lgkmcnt(0)
	s_barrier
	s_setprio 1
	s_waitcnt lgkmcnt(0)
	v_mfma_f32_16x16x32_bf16 v[62:65], v[130:133], v[186:189], v[62:65]
	v_mfma_f32_16x16x32_bf16 v[58:61], v[138:141], v[186:189], v[58:61]
	v_mfma_f32_16x16x32_bf16 v[50:53], v[130:133], v[194:197], v[50:53]
	v_mfma_f32_16x16x32_bf16 v[42:45], v[138:141], v[194:197], v[42:45]
	v_mfma_f32_16x16x32_bf16 v[38:41], v[130:133], v[202:205], v[38:41]
	v_mfma_f32_16x16x32_bf16 v[34:37], v[138:141], v[202:205], v[34:37]
	v_mfma_f32_16x16x32_bf16 v[14:17], v[130:133], v[210:213], v[14:17]
	v_mfma_f32_16x16x32_bf16 v[10:13], v[138:141], v[210:213], v[10:13]
	v_mfma_f32_16x16x32_bf16 v[62:65], v[134:137], v[190:193], v[62:65]
	v_mfma_f32_16x16x32_bf16 v[58:61], v[158:161], v[190:193], v[58:61]
	v_mfma_f32_16x16x32_bf16 v[50:53], v[134:137], v[198:201], v[50:53]
	v_mfma_f32_16x16x32_bf16 v[42:45], v[158:161], v[198:201], v[42:45]
	v_mfma_f32_16x16x32_bf16 v[38:41], v[134:137], v[206:209], v[38:41]
	v_mfma_f32_16x16x32_bf16 v[34:37], v[158:161], v[206:209], v[34:37]
	v_mfma_f32_16x16x32_bf16 v[14:17], v[134:137], v[218:221], v[14:17]
	v_mfma_f32_16x16x32_bf16 v[10:13], v[158:161], v[218:221], v[10:13]
	s_setprio 0
	s_setprio 1
	v_mfma_f32_16x16x32_bf16 v[54:57], v[162:165], v[186:189], v[54:57]
	v_mfma_f32_16x16x32_bf16 v[46:49], v[178:181], v[186:189], v[46:49]
	v_mfma_f32_16x16x32_bf16 v[30:33], v[162:165], v[194:197], v[30:33]
	v_mfma_f32_16x16x32_bf16 v[26:29], v[178:181], v[194:197], v[26:29]
	v_mfma_f32_16x16x32_bf16 v[22:25], v[162:165], v[202:205], v[22:25]
	v_mfma_f32_16x16x32_bf16 v[18:21], v[178:181], v[202:205], v[18:21]
	v_mfma_f32_16x16x32_bf16 v[6:9], v[162:165], v[210:213], v[6:9]
	v_mfma_f32_16x16x32_bf16 v[2:5], v[178:181], v[210:213], v[2:5]
	v_mfma_f32_16x16x32_bf16 v[54:57], v[166:169], v[190:193], v[54:57]
	v_mfma_f32_16x16x32_bf16 v[46:49], v[182:185], v[190:193], v[46:49]
	v_mfma_f32_16x16x32_bf16 v[30:33], v[166:169], v[198:201], v[30:33]
	v_mfma_f32_16x16x32_bf16 v[26:29], v[182:185], v[198:201], v[26:29]
	v_mfma_f32_16x16x32_bf16 v[22:25], v[166:169], v[206:209], v[22:25]
	v_mfma_f32_16x16x32_bf16 v[18:21], v[182:185], v[206:209], v[18:21]
	v_mfma_f32_16x16x32_bf16 v[6:9], v[166:169], v[218:221], v[6:9]
	v_mfma_f32_16x16x32_bf16 v[2:5], v[182:185], v[218:221], v[2:5]
	s_setprio 0
	s_barrier
	s_add_i32 s66, 0, 0x18000
	s_add_i32 s67, 0, 0x1c000
	v_add_u32_e32 v158, s66, v172
	v_add_u32_e32 v177, 0x19000, v172
	ds_read_b128 v[130:133], v158
	ds_read_b128 v[134:137], v158 offset:1024
	ds_read_b128 v[138:141], v158 offset:2048
	ds_read_b128 v[158:161], v158 offset:3072
	ds_read_b128 v[162:165], v177
	ds_read_b128 v[166:169], v177 offset:1024
	ds_read_b128 v[178:181], v177 offset:2048
	ds_read_b128 v[182:185], v177 offset:3072
	s_add_u32 s62, s68, 0x80000
	s_addc_u32 s63, s69, 0
	s_mov_b32 m0, s52
	v_lshl_add_u64 v[226:227], s[62:63], 0, v[142:143]
	ds_read_b128 v[186:189], v176 offset:32768
	ds_read_b128 v[190:193], v176 offset:33792
	ds_read_b128 v[194:197], v176 offset:34816
	ds_read_b128 v[198:201], v176 offset:35840
	ds_read_b128 v[202:205], v176 offset:36864
	ds_read_b128 v[206:209], v176 offset:37888
	ds_read_b128 v[210:213], v176 offset:38912
	ds_read_b128 v[218:221], v176 offset:39936
	global_load_lds_dwordx4 v[226:227], off
	v_lshl_add_u64 v[226:227], s[62:63], 0, v[146:147]
	s_mov_b32 m0, s53
	s_nop 0
	global_load_lds_dwordx4 v[226:227], off
	s_waitcnt vmcnt(8)
	s_waitcnt lgkmcnt(0)
	s_barrier
	s_setprio 1
	s_waitcnt lgkmcnt(0)
	v_mfma_f32_16x16x32_bf16 v[126:129], v[130:133], v[186:189], v[126:129]
	v_mfma_f32_16x16x32_bf16 v[122:125], v[138:141], v[186:189], v[122:125]
	v_mfma_f32_16x16x32_bf16 v[110:113], v[130:133], v[194:197], v[110:113]
	v_mfma_f32_16x16x32_bf16 v[106:109], v[138:141], v[194:197], v[106:109]
	v_mfma_f32_16x16x32_bf16 v[94:97], v[130:133], v[202:205], v[94:97]
	v_mfma_f32_16x16x32_bf16 v[90:93], v[138:141], v[202:205], v[90:93]
	v_mfma_f32_16x16x32_bf16 v[78:81], v[130:133], v[210:213], v[78:81]
	v_mfma_f32_16x16x32_bf16 v[74:77], v[138:141], v[210:213], v[74:77]
	v_mfma_f32_16x16x32_bf16 v[126:129], v[134:137], v[190:193], v[126:129]
	v_mfma_f32_16x16x32_bf16 v[122:125], v[158:161], v[190:193], v[122:125]
	v_mfma_f32_16x16x32_bf16 v[110:113], v[134:137], v[198:201], v[110:113]
	v_mfma_f32_16x16x32_bf16 v[106:109], v[158:161], v[198:201], v[106:109]
	v_mfma_f32_16x16x32_bf16 v[94:97], v[134:137], v[206:209], v[94:97]
	v_mfma_f32_16x16x32_bf16 v[90:93], v[158:161], v[206:209], v[90:93]
	v_mfma_f32_16x16x32_bf16 v[78:81], v[134:137], v[218:221], v[78:81]
	v_mfma_f32_16x16x32_bf16 v[74:77], v[158:161], v[218:221], v[74:77]
	s_setprio 0
	s_setprio 1
	v_mfma_f32_16x16x32_bf16 v[118:121], v[162:165], v[186:189], v[118:121]
	v_mfma_f32_16x16x32_bf16 v[114:117], v[178:181], v[186:189], v[114:117]
	v_mfma_f32_16x16x32_bf16 v[102:105], v[162:165], v[194:197], v[102:105]
	v_mfma_f32_16x16x32_bf16 v[98:101], v[178:181], v[194:197], v[98:101]
	v_mfma_f32_16x16x32_bf16 v[86:89], v[162:165], v[202:205], v[86:89]
	v_mfma_f32_16x16x32_bf16 v[82:85], v[178:181], v[202:205], v[82:85]
	v_mfma_f32_16x16x32_bf16 v[70:73], v[162:165], v[210:213], v[70:73]
	v_mfma_f32_16x16x32_bf16 v[66:69], v[178:181], v[210:213], v[66:69]
	v_mfma_f32_16x16x32_bf16 v[118:121], v[166:169], v[190:193], v[118:121]
	v_mfma_f32_16x16x32_bf16 v[114:117], v[182:185], v[190:193], v[114:117]
	v_mfma_f32_16x16x32_bf16 v[102:105], v[166:169], v[198:201], v[102:105]
	v_mfma_f32_16x16x32_bf16 v[98:101], v[182:185], v[198:201], v[98:101]
	v_mfma_f32_16x16x32_bf16 v[86:89], v[166:169], v[206:209], v[86:89]
	v_mfma_f32_16x16x32_bf16 v[82:85], v[182:185], v[206:209], v[82:85]
	v_mfma_f32_16x16x32_bf16 v[70:73], v[166:169], v[218:221], v[70:73]
	v_mfma_f32_16x16x32_bf16 v[66:69], v[182:185], v[218:221], v[66:69]
	s_setprio 0
	s_barrier
	s_add_i32 s62, s66, s31
	v_lshl_add_u64 v[170:171], v[170:171], 0, s[24:25]
	s_mov_b32 m0, s62
	ds_read_b128 v[186:189], v176 offset:49152
	ds_read_b128 v[190:193], v176 offset:50176
	ds_read_b128 v[194:197], v176 offset:51200
	ds_read_b128 v[198:201], v176 offset:52224
	ds_read_b128 v[202:205], v176 offset:53248
	ds_read_b128 v[206:209], v176 offset:54272
	ds_read_b128 v[210:213], v176 offset:55296
	ds_read_b128 v[218:221], v176 offset:56320
	global_load_lds_dwordx4 v[170:171], off
	s_add_i32 m0, s62, 0x2000
	s_add_u32 s34, s34, 0x80080
	v_lshl_add_u64 v[170:171], v[214:215], 0, s[24:25]
	s_addc_u32 s35, s35, 0
	s_add_i32 s62, s67, s31
	global_load_lds_dwordx4 v[170:171], off
	v_lshl_add_u64 v[170:171], s[34:35], 0, v[144:145]
	s_mov_b32 m0, s62
	s_nop 0
	global_load_lds_dwordx4 v[170:171], off
	v_lshl_add_u64 v[170:171], s[34:35], 0, v[148:149]
	s_add_i32 m0, s62, 0x2000
	s_nop 0
	global_load_lds_dwordx4 v[170:171], off
	v_lshl_add_u64 v[170:171], v[222:223], 0, s[24:25]
	s_mov_b32 m0, s55
	s_nop 0
	global_load_lds_dwordx4 v[170:171], off
	v_lshl_add_u64 v[170:171], v[224:225], 0, s[24:25]
	s_mov_b32 m0, s56
	s_nop 0
	global_load_lds_dwordx4 v[170:171], off
	s_waitcnt vmcnt(8)
	s_waitcnt lgkmcnt(0)
	s_barrier
	s_setprio 1
	s_waitcnt lgkmcnt(0)
	v_mfma_f32_16x16x32_bf16 v[62:65], v[130:133], v[186:189], v[62:65]
	v_mfma_f32_16x16x32_bf16 v[58:61], v[138:141], v[186:189], v[58:61]
	v_mfma_f32_16x16x32_bf16 v[50:53], v[130:133], v[194:197], v[50:53]
	v_mfma_f32_16x16x32_bf16 v[42:45], v[138:141], v[194:197], v[42:45]
	v_mfma_f32_16x16x32_bf16 v[38:41], v[130:133], v[202:205], v[38:41]
	v_mfma_f32_16x16x32_bf16 v[34:37], v[138:141], v[202:205], v[34:37]
	v_mfma_f32_16x16x32_bf16 v[14:17], v[130:133], v[210:213], v[14:17]
	v_mfma_f32_16x16x32_bf16 v[10:13], v[138:141], v[210:213], v[10:13]
	v_mfma_f32_16x16x32_bf16 v[62:65], v[134:137], v[190:193], v[62:65]
	v_mfma_f32_16x16x32_bf16 v[58:61], v[158:161], v[190:193], v[58:61]
	v_mfma_f32_16x16x32_bf16 v[50:53], v[134:137], v[198:201], v[50:53]
	v_mfma_f32_16x16x32_bf16 v[42:45], v[158:161], v[198:201], v[42:45]
	v_mfma_f32_16x16x32_bf16 v[38:41], v[134:137], v[206:209], v[38:41]
	v_mfma_f32_16x16x32_bf16 v[34:37], v[158:161], v[206:209], v[34:37]
	v_mfma_f32_16x16x32_bf16 v[14:17], v[134:137], v[218:221], v[14:17]
	v_mfma_f32_16x16x32_bf16 v[10:13], v[158:161], v[218:221], v[10:13]
	s_setprio 0
	s_setprio 1
	v_mfma_f32_16x16x32_bf16 v[54:57], v[162:165], v[186:189], v[54:57]
	v_mfma_f32_16x16x32_bf16 v[46:49], v[178:181], v[186:189], v[46:49]
	v_mfma_f32_16x16x32_bf16 v[30:33], v[162:165], v[194:197], v[30:33]
	v_mfma_f32_16x16x32_bf16 v[26:29], v[178:181], v[194:197], v[26:29]
	v_mfma_f32_16x16x32_bf16 v[22:25], v[162:165], v[202:205], v[22:25]
	v_mfma_f32_16x16x32_bf16 v[18:21], v[178:181], v[202:205], v[18:21]
	v_mfma_f32_16x16x32_bf16 v[6:9], v[162:165], v[210:213], v[6:9]
	v_mfma_f32_16x16x32_bf16 v[2:5], v[178:181], v[210:213], v[2:5]
	v_mfma_f32_16x16x32_bf16 v[54:57], v[166:169], v[190:193], v[54:57]
	v_mfma_f32_16x16x32_bf16 v[46:49], v[182:185], v[190:193], v[46:49]
	v_mfma_f32_16x16x32_bf16 v[30:33], v[166:169], v[198:201], v[30:33]
	v_mfma_f32_16x16x32_bf16 v[26:29], v[182:185], v[198:201], v[26:29]
	v_mfma_f32_16x16x32_bf16 v[22:25], v[166:169], v[206:209], v[22:25]
	v_mfma_f32_16x16x32_bf16 v[18:21], v[182:185], v[206:209], v[18:21]
	v_mfma_f32_16x16x32_bf16 v[6:9], v[166:169], v[218:221], v[6:9]
	v_mfma_f32_16x16x32_bf16 v[2:5], v[182:185], v[218:221], v[2:5]
	s_setprio 0
	s_barrier
	s_add_i32 s72, s72, 2
	s_add_u32 s46, s46, 0x100
	s_addc_u32 s47, s47, 0
	s_add_u32 s70, s70, 0x100
	s_addc_u32 s71, s71, 0
	s_cmp_gt_u32 s72, 29
	s_cbranch_scc0 .LBB0_2938
	v_lshl_or_b32 v130, s61, 8, v173
	v_lshl_add_u32 v158, s44, 8, v1
	v_ashrrev_i32_e32 v131, 31, v130
	v_lshlrev_b64 v[160:161], 1, v[130:131]
	v_or_b32_e32 v130, 16, v158
	v_ashrrev_i32_e32 v159, 31, v158
	v_ashrrev_i32_e32 v131, 31, v130
	v_lshlrev_b64 v[132:133], 12, v[158:159]
	v_lshlrev_b64 v[130:131], 12, v[130:131]
	v_lshl_add_u64 v[132:133], s[64:65], 0, v[132:133]
	v_lshl_add_u64 v[130:131], s[64:65], 0, v[130:131]
	v_lshl_add_u64 v[170:171], v[132:133], 0, v[160:161]
	v_lshl_add_u64 v[168:169], v[130:131], 0, v[160:161]
	v_mov_b32_e32 v209, 0
	v_mov_b32_e32 v208, 0x10000
	v_lshl_add_u64 v[194:195], v[208:209], 0, v[170:171]
	v_mov_b32_e32 v208, 0x20000
	v_lshl_add_u64 v[196:197], v[208:209], 0, v[170:171]
	v_mov_b32_e32 v208, 0x30000
	v_lshl_add_u64 v[198:199], v[208:209], 0, v[170:171]
	v_mov_b32_e32 v208, 0x80000
	v_lshl_add_u64 v[200:201], v[208:209], 0, v[170:171]
	v_mov_b32_e32 v208, 0x90000
	v_lshl_add_u64 v[202:203], v[208:209], 0, v[170:171]
	v_mov_b32_e32 v208, 0xa0000
	v_lshl_add_u64 v[204:205], v[208:209], 0, v[170:171]
	v_mov_b32_e32 v208, 0xb0000
	v_lshl_add_u64 v[206:207], v[208:209], 0, v[170:171]
	global_load_dwordx4 v[130:133], v[170:171], off
	global_load_dwordx4 v[134:137], v[170:171], off offset:64
	global_load_dwordx4 v[138:141], v[194:195], off
	global_load_dwordx4 v[158:161], v[194:195], off offset:64
	global_load_dwordx4 v[162:165], v[196:197], off
	global_load_dwordx4 v[166:169], v[196:197], off offset:64
	global_load_dwordx4 v[178:181], v[198:199], off
	global_load_dwordx4 v[182:185], v[198:199], off offset:64
	s_and_b64 vcc, exec, s[26:27]
	s_cbranch_vccz .LBB0_2941
	s_barrier
.LBB0_2941:
	s_waitcnt vmcnt(7)
	v_cvt_f32_f16_e32 v186, v130
	v_cvt_f32_f16_sdwa v187, v130 dst_sel:DWORD dst_unused:UNUSED_PAD src0_sel:WORD_1
	v_cvt_f32_f16_e32 v188, v131
	v_cvt_f32_f16_sdwa v189, v131 dst_sel:DWORD dst_unused:UNUSED_PAD src0_sel:WORD_1
	v_cvt_f32_f16_e32 v190, v132
	v_cvt_f32_f16_sdwa v191, v132 dst_sel:DWORD dst_unused:UNUSED_PAD src0_sel:WORD_1
	v_cvt_f32_f16_e32 v192, v133
	v_cvt_f32_f16_sdwa v193, v133 dst_sel:DWORD dst_unused:UNUSED_PAD src0_sel:WORD_1
	global_load_dwordx4 v[130:133], v[200:201], off
	v_pk_add_f32 v[126:127], v[186:187], v[126:127]
	v_pk_add_f32 v[128:129], v[188:189], v[128:129]
	v_pk_add_f32 v[122:123], v[190:191], v[122:123]
	v_pk_add_f32 v[124:125], v[192:193], v[124:125]
	v_cvt_pk_f16_f32 v125, v124, v125
	v_cvt_pk_f16_f32 v124, v122, v123
	v_cvt_pk_f16_f32 v123, v128, v129
	v_cvt_pk_f16_f32 v122, v126, v127
	global_store_dwordx4 v[170:171], v[122:125], off
	s_waitcnt vmcnt(8)
	v_cvt_f32_f16_e32 v186, v134
	v_cvt_f32_f16_sdwa v187, v134 dst_sel:DWORD dst_unused:UNUSED_PAD src0_sel:WORD_1
	v_cvt_f32_f16_e32 v188, v135
	v_cvt_f32_f16_sdwa v189, v135 dst_sel:DWORD dst_unused:UNUSED_PAD src0_sel:WORD_1
	v_cvt_f32_f16_e32 v190, v136
	v_cvt_f32_f16_sdwa v191, v136 dst_sel:DWORD dst_unused:UNUSED_PAD src0_sel:WORD_1
	v_cvt_f32_f16_e32 v192, v137
	v_cvt_f32_f16_sdwa v193, v137 dst_sel:DWORD dst_unused:UNUSED_PAD src0_sel:WORD_1
	global_load_dwordx4 v[134:137], v[200:201], off offset:64
	v_pk_add_f32 v[118:119], v[186:187], v[118:119]
	v_pk_add_f32 v[120:121], v[188:189], v[120:121]
	v_pk_add_f32 v[114:115], v[190:191], v[114:115]
	v_pk_add_f32 v[116:117], v[192:193], v[116:117]
	v_cvt_pk_f16_f32 v117, v116, v117
	v_cvt_pk_f16_f32 v116, v114, v115
	v_cvt_pk_f16_f32 v115, v120, v121
	v_cvt_pk_f16_f32 v114, v118, v119
	global_store_dwordx4 v[170:171], v[114:117], off offset:64
	s_waitcnt vmcnt(9)
	v_cvt_f32_f16_e32 v186, v138
	v_cvt_f32_f16_sdwa v187, v138 dst_sel:DWORD dst_unused:UNUSED_PAD src0_sel:WORD_1
	v_cvt_f32_f16_e32 v188, v139
	v_cvt_f32_f16_sdwa v189, v139 dst_sel:DWORD dst_unused:UNUSED_PAD src0_sel:WORD_1
	v_cvt_f32_f16_e32 v190, v140
	v_cvt_f32_f16_sdwa v191, v140 dst_sel:DWORD dst_unused:UNUSED_PAD src0_sel:WORD_1
	v_cvt_f32_f16_e32 v192, v141
	v_cvt_f32_f16_sdwa v193, v141 dst_sel:DWORD dst_unused:UNUSED_PAD src0_sel:WORD_1
	global_load_dwordx4 v[138:141], v[202:203], off
	v_pk_add_f32 v[110:111], v[186:187], v[110:111]
	v_pk_add_f32 v[112:113], v[188:189], v[112:113]
	v_pk_add_f32 v[106:107], v[190:191], v[106:107]
	v_pk_add_f32 v[108:109], v[192:193], v[108:109]
	v_cvt_pk_f16_f32 v109, v108, v109
	v_cvt_pk_f16_f32 v108, v106, v107
	v_cvt_pk_f16_f32 v107, v112, v113
	v_cvt_pk_f16_f32 v106, v110, v111
	global_store_dwordx4 v[194:195], v[106:109], off
	s_waitcnt vmcnt(10)
	v_cvt_f32_f16_e32 v186, v158
	v_cvt_f32_f16_sdwa v187, v158 dst_sel:DWORD dst_unused:UNUSED_PAD src0_sel:WORD_1
	v_cvt_f32_f16_e32 v188, v159
	v_cvt_f32_f16_sdwa v189, v159 dst_sel:DWORD dst_unused:UNUSED_PAD src0_sel:WORD_1
	v_cvt_f32_f16_e32 v190, v160
	v_cvt_f32_f16_sdwa v191, v160 dst_sel:DWORD dst_unused:UNUSED_PAD src0_sel:WORD_1
	v_cvt_f32_f16_e32 v192, v161
	v_cvt_f32_f16_sdwa v193, v161 dst_sel:DWORD dst_unused:UNUSED_PAD src0_sel:WORD_1
	global_load_dwordx4 v[158:161], v[202:203], off offset:64
	v_pk_add_f32 v[102:103], v[186:187], v[102:103]
	v_pk_add_f32 v[104:105], v[188:189], v[104:105]
	v_pk_add_f32 v[98:99], v[190:191], v[98:99]
	v_pk_add_f32 v[100:101], v[192:193], v[100:101]
	v_cvt_pk_f16_f32 v101, v100, v101
	v_cvt_pk_f16_f32 v100, v98, v99
	v_cvt_pk_f16_f32 v99, v104, v105
	v_cvt_pk_f16_f32 v98, v102, v103
	global_store_dwordx4 v[194:195], v[98:101], off offset:64
	s_waitcnt vmcnt(11)
	v_cvt_f32_f16_e32 v186, v162
	v_cvt_f32_f16_sdwa v187, v162 dst_sel:DWORD dst_unused:UNUSED_PAD src0_sel:WORD_1
	v_cvt_f32_f16_e32 v188, v163
	v_cvt_f32_f16_sdwa v189, v163 dst_sel:DWORD dst_unused:UNUSED_PAD src0_sel:WORD_1
	v_cvt_f32_f16_e32 v190, v164
	v_cvt_f32_f16_sdwa v191, v164 dst_sel:DWORD dst_unused:UNUSED_PAD src0_sel:WORD_1
	v_cvt_f32_f16_e32 v192, v165
	v_cvt_f32_f16_sdwa v193, v165 dst_sel:DWORD dst_unused:UNUSED_PAD src0_sel:WORD_1
	global_load_dwordx4 v[162:165], v[204:205], off
	v_pk_add_f32 v[94:95], v[186:187], v[94:95]
	v_pk_add_f32 v[96:97], v[188:189], v[96:97]
	v_pk_add_f32 v[90:91], v[190:191], v[90:91]
	v_pk_add_f32 v[92:93], v[192:193], v[92:93]
	v_cvt_pk_f16_f32 v93, v92, v93
	v_cvt_pk_f16_f32 v92, v90, v91
	v_cvt_pk_f16_f32 v91, v96, v97
	v_cvt_pk_f16_f32 v90, v94, v95
	global_store_dwordx4 v[196:197], v[90:93], off
	s_waitcnt vmcnt(12)
	v_cvt_f32_f16_e32 v186, v166
	v_cvt_f32_f16_sdwa v187, v166 dst_sel:DWORD dst_unused:UNUSED_PAD src0_sel:WORD_1
	v_cvt_f32_f16_e32 v188, v167
	v_cvt_f32_f16_sdwa v189, v167 dst_sel:DWORD dst_unused:UNUSED_PAD src0_sel:WORD_1
	v_cvt_f32_f16_e32 v190, v168
	v_cvt_f32_f16_sdwa v191, v168 dst_sel:DWORD dst_unused:UNUSED_PAD src0_sel:WORD_1
	v_cvt_f32_f16_e32 v192, v169
	v_cvt_f32_f16_sdwa v193, v169 dst_sel:DWORD dst_unused:UNUSED_PAD src0_sel:WORD_1
	global_load_dwordx4 v[166:169], v[204:205], off offset:64
	v_pk_add_f32 v[86:87], v[186:187], v[86:87]
	v_pk_add_f32 v[88:89], v[188:189], v[88:89]
	v_pk_add_f32 v[82:83], v[190:191], v[82:83]
	v_pk_add_f32 v[84:85], v[192:193], v[84:85]
	v_cvt_pk_f16_f32 v85, v84, v85
	v_cvt_pk_f16_f32 v84, v82, v83
	v_cvt_pk_f16_f32 v83, v88, v89
	v_cvt_pk_f16_f32 v82, v86, v87
	global_store_dwordx4 v[196:197], v[82:85], off offset:64
	s_waitcnt vmcnt(13)
	v_cvt_f32_f16_e32 v186, v178
	v_cvt_f32_f16_sdwa v187, v178 dst_sel:DWORD dst_unused:UNUSED_PAD src0_sel:WORD_1
	v_cvt_f32_f16_e32 v188, v179
	v_cvt_f32_f16_sdwa v189, v179 dst_sel:DWORD dst_unused:UNUSED_PAD src0_sel:WORD_1
	v_cvt_f32_f16_e32 v190, v180
	v_cvt_f32_f16_sdwa v191, v180 dst_sel:DWORD dst_unused:UNUSED_PAD src0_sel:WORD_1
	v_cvt_f32_f16_e32 v192, v181
	v_cvt_f32_f16_sdwa v193, v181 dst_sel:DWORD dst_unused:UNUSED_PAD src0_sel:WORD_1
	global_load_dwordx4 v[178:181], v[206:207], off
	v_pk_add_f32 v[78:79], v[186:187], v[78:79]
	v_pk_add_f32 v[80:81], v[188:189], v[80:81]
	v_pk_add_f32 v[74:75], v[190:191], v[74:75]
	v_pk_add_f32 v[76:77], v[192:193], v[76:77]
	v_cvt_pk_f16_f32 v77, v76, v77
	v_cvt_pk_f16_f32 v76, v74, v75
	v_cvt_pk_f16_f32 v75, v80, v81
	v_cvt_pk_f16_f32 v74, v78, v79
	global_store_dwordx4 v[198:199], v[74:77], off
	s_waitcnt vmcnt(14)
	v_cvt_f32_f16_e32 v186, v182
	v_cvt_f32_f16_sdwa v187, v182 dst_sel:DWORD dst_unused:UNUSED_PAD src0_sel:WORD_1
	v_cvt_f32_f16_e32 v188, v183
	v_cvt_f32_f16_sdwa v189, v183 dst_sel:DWORD dst_unused:UNUSED_PAD src0_sel:WORD_1
	v_cvt_f32_f16_e32 v190, v184
	v_cvt_f32_f16_sdwa v191, v184 dst_sel:DWORD dst_unused:UNUSED_PAD src0_sel:WORD_1
	v_cvt_f32_f16_e32 v192, v185
	v_cvt_f32_f16_sdwa v193, v185 dst_sel:DWORD dst_unused:UNUSED_PAD src0_sel:WORD_1
	global_load_dwordx4 v[182:185], v[206:207], off offset:64
	v_pk_add_f32 v[70:71], v[186:187], v[70:71]
	v_pk_add_f32 v[72:73], v[188:189], v[72:73]
	v_pk_add_f32 v[66:67], v[190:191], v[66:67]
	v_pk_add_f32 v[68:69], v[192:193], v[68:69]
	v_cvt_pk_f16_f32 v69, v68, v69
	v_cvt_pk_f16_f32 v68, v66, v67
	v_cvt_pk_f16_f32 v67, v72, v73
	v_cvt_pk_f16_f32 v66, v70, v71
	global_store_dwordx4 v[198:199], v[66:69], off offset:64
	s_waitcnt vmcnt(15)
	v_cvt_f32_f16_e32 v186, v130
	v_cvt_f32_f16_sdwa v187, v130 dst_sel:DWORD dst_unused:UNUSED_PAD src0_sel:WORD_1
	v_cvt_f32_f16_e32 v188, v131
	v_cvt_f32_f16_sdwa v189, v131 dst_sel:DWORD dst_unused:UNUSED_PAD src0_sel:WORD_1
	v_cvt_f32_f16_e32 v190, v132
	v_cvt_f32_f16_sdwa v191, v132 dst_sel:DWORD dst_unused:UNUSED_PAD src0_sel:WORD_1
	v_cvt_f32_f16_e32 v192, v133
	v_cvt_f32_f16_sdwa v193, v133 dst_sel:DWORD dst_unused:UNUSED_PAD src0_sel:WORD_1
	v_pk_add_f32 v[62:63], v[186:187], v[62:63]
	v_pk_add_f32 v[64:65], v[188:189], v[64:65]
	v_pk_add_f32 v[58:59], v[190:191], v[58:59]
	v_pk_add_f32 v[60:61], v[192:193], v[60:61]
	v_cvt_pk_f16_f32 v61, v60, v61
	v_cvt_pk_f16_f32 v60, v58, v59
	v_cvt_pk_f16_f32 v59, v64, v65
	v_cvt_pk_f16_f32 v58, v62, v63
	global_store_dwordx4 v[200:201], v[58:61], off
	s_waitcnt vmcnt(14)
	v_cvt_f32_f16_e32 v186, v134
	v_cvt_f32_f16_sdwa v187, v134 dst_sel:DWORD dst_unused:UNUSED_PAD src0_sel:WORD_1
	v_cvt_f32_f16_e32 v188, v135
	v_cvt_f32_f16_sdwa v189, v135 dst_sel:DWORD dst_unused:UNUSED_PAD src0_sel:WORD_1
	v_cvt_f32_f16_e32 v190, v136
	v_cvt_f32_f16_sdwa v191, v136 dst_sel:DWORD dst_unused:UNUSED_PAD src0_sel:WORD_1
	v_cvt_f32_f16_e32 v192, v137
	v_cvt_f32_f16_sdwa v193, v137 dst_sel:DWORD dst_unused:UNUSED_PAD src0_sel:WORD_1
	v_pk_add_f32 v[54:55], v[186:187], v[54:55]
	v_pk_add_f32 v[56:57], v[188:189], v[56:57]
	v_pk_add_f32 v[46:47], v[190:191], v[46:47]
	v_pk_add_f32 v[48:49], v[192:193], v[48:49]
	v_cvt_pk_f16_f32 v49, v48, v49
	v_cvt_pk_f16_f32 v48, v46, v47
	v_cvt_pk_f16_f32 v47, v56, v57
	v_cvt_pk_f16_f32 v46, v54, v55
	global_store_dwordx4 v[200:201], v[46:49], off offset:64
	s_waitcnt vmcnt(13)
	v_cvt_f32_f16_e32 v186, v138
	v_cvt_f32_f16_sdwa v187, v138 dst_sel:DWORD dst_unused:UNUSED_PAD src0_sel:WORD_1
	v_cvt_f32_f16_e32 v188, v139
	v_cvt_f32_f16_sdwa v189, v139 dst_sel:DWORD dst_unused:UNUSED_PAD src0_sel:WORD_1
	v_cvt_f32_f16_e32 v190, v140
	v_cvt_f32_f16_sdwa v191, v140 dst_sel:DWORD dst_unused:UNUSED_PAD src0_sel:WORD_1
	v_cvt_f32_f16_e32 v192, v141
	v_cvt_f32_f16_sdwa v193, v141 dst_sel:DWORD dst_unused:UNUSED_PAD src0_sel:WORD_1
	v_pk_add_f32 v[50:51], v[186:187], v[50:51]
	v_pk_add_f32 v[52:53], v[188:189], v[52:53]
	v_pk_add_f32 v[42:43], v[190:191], v[42:43]
	v_pk_add_f32 v[44:45], v[192:193], v[44:45]
	v_cvt_pk_f16_f32 v45, v44, v45
	v_cvt_pk_f16_f32 v44, v42, v43
	v_cvt_pk_f16_f32 v43, v52, v53
	v_cvt_pk_f16_f32 v42, v50, v51
	global_store_dwordx4 v[202:203], v[42:45], off
	s_waitcnt vmcnt(12)
	v_cvt_f32_f16_e32 v186, v158
	v_cvt_f32_f16_sdwa v187, v158 dst_sel:DWORD dst_unused:UNUSED_PAD src0_sel:WORD_1
	v_cvt_f32_f16_e32 v188, v159
	v_cvt_f32_f16_sdwa v189, v159 dst_sel:DWORD dst_unused:UNUSED_PAD src0_sel:WORD_1
	v_cvt_f32_f16_e32 v190, v160
	v_cvt_f32_f16_sdwa v191, v160 dst_sel:DWORD dst_unused:UNUSED_PAD src0_sel:WORD_1
	v_cvt_f32_f16_e32 v192, v161
	v_cvt_f32_f16_sdwa v193, v161 dst_sel:DWORD dst_unused:UNUSED_PAD src0_sel:WORD_1
	v_pk_add_f32 v[30:31], v[186:187], v[30:31]
	v_pk_add_f32 v[32:33], v[188:189], v[32:33]
	v_pk_add_f32 v[26:27], v[190:191], v[26:27]
	v_pk_add_f32 v[28:29], v[192:193], v[28:29]
	v_cvt_pk_f16_f32 v29, v28, v29
	v_cvt_pk_f16_f32 v28, v26, v27
	v_cvt_pk_f16_f32 v27, v32, v33
	v_cvt_pk_f16_f32 v26, v30, v31
	global_store_dwordx4 v[202:203], v[26:29], off offset:64
	s_waitcnt vmcnt(11)
	v_cvt_f32_f16_e32 v186, v162
	v_cvt_f32_f16_sdwa v187, v162 dst_sel:DWORD dst_unused:UNUSED_PAD src0_sel:WORD_1
	v_cvt_f32_f16_e32 v188, v163
	v_cvt_f32_f16_sdwa v189, v163 dst_sel:DWORD dst_unused:UNUSED_PAD src0_sel:WORD_1
	v_cvt_f32_f16_e32 v190, v164
	v_cvt_f32_f16_sdwa v191, v164 dst_sel:DWORD dst_unused:UNUSED_PAD src0_sel:WORD_1
	v_cvt_f32_f16_e32 v192, v165
	v_cvt_f32_f16_sdwa v193, v165 dst_sel:DWORD dst_unused:UNUSED_PAD src0_sel:WORD_1
	v_pk_add_f32 v[38:39], v[186:187], v[38:39]
	v_pk_add_f32 v[40:41], v[188:189], v[40:41]
	v_pk_add_f32 v[34:35], v[190:191], v[34:35]
	v_pk_add_f32 v[36:37], v[192:193], v[36:37]
	v_cvt_pk_f16_f32 v37, v36, v37
	v_cvt_pk_f16_f32 v36, v34, v35
	v_cvt_pk_f16_f32 v35, v40, v41
	v_cvt_pk_f16_f32 v34, v38, v39
	global_store_dwordx4 v[204:205], v[34:37], off
	s_waitcnt vmcnt(10)
	v_cvt_f32_f16_e32 v186, v166
	v_cvt_f32_f16_sdwa v187, v166 dst_sel:DWORD dst_unused:UNUSED_PAD src0_sel:WORD_1
	v_cvt_f32_f16_e32 v188, v167
	v_cvt_f32_f16_sdwa v189, v167 dst_sel:DWORD dst_unused:UNUSED_PAD src0_sel:WORD_1
	v_cvt_f32_f16_e32 v190, v168
	v_cvt_f32_f16_sdwa v191, v168 dst_sel:DWORD dst_unused:UNUSED_PAD src0_sel:WORD_1
	v_cvt_f32_f16_e32 v192, v169
	v_cvt_f32_f16_sdwa v193, v169 dst_sel:DWORD dst_unused:UNUSED_PAD src0_sel:WORD_1
	v_pk_add_f32 v[22:23], v[186:187], v[22:23]
	v_pk_add_f32 v[24:25], v[188:189], v[24:25]
	v_pk_add_f32 v[18:19], v[190:191], v[18:19]
	v_pk_add_f32 v[20:21], v[192:193], v[20:21]
	v_cvt_pk_f16_f32 v21, v20, v21
	v_cvt_pk_f16_f32 v20, v18, v19
	v_cvt_pk_f16_f32 v19, v24, v25
	v_cvt_pk_f16_f32 v18, v22, v23
	global_store_dwordx4 v[204:205], v[18:21], off offset:64
	s_waitcnt vmcnt(9)
	v_cvt_f32_f16_e32 v186, v178
	v_cvt_f32_f16_sdwa v187, v178 dst_sel:DWORD dst_unused:UNUSED_PAD src0_sel:WORD_1
	v_cvt_f32_f16_e32 v188, v179
	v_cvt_f32_f16_sdwa v189, v179 dst_sel:DWORD dst_unused:UNUSED_PAD src0_sel:WORD_1
	v_cvt_f32_f16_e32 v190, v180
	v_cvt_f32_f16_sdwa v191, v180 dst_sel:DWORD dst_unused:UNUSED_PAD src0_sel:WORD_1
	v_cvt_f32_f16_e32 v192, v181
	v_cvt_f32_f16_sdwa v193, v181 dst_sel:DWORD dst_unused:UNUSED_PAD src0_sel:WORD_1
	v_pk_add_f32 v[14:15], v[186:187], v[14:15]
	v_pk_add_f32 v[16:17], v[188:189], v[16:17]
	v_pk_add_f32 v[10:11], v[190:191], v[10:11]
	v_pk_add_f32 v[12:13], v[192:193], v[12:13]
	v_cvt_pk_f16_f32 v13, v12, v13
	v_cvt_pk_f16_f32 v12, v10, v11
	v_cvt_pk_f16_f32 v11, v16, v17
	v_cvt_pk_f16_f32 v10, v14, v15
	global_store_dwordx4 v[206:207], v[10:13], off
	s_waitcnt vmcnt(8)
	v_cvt_f32_f16_e32 v186, v182
	v_cvt_f32_f16_sdwa v187, v182 dst_sel:DWORD dst_unused:UNUSED_PAD src0_sel:WORD_1
	v_cvt_f32_f16_e32 v188, v183
	v_cvt_f32_f16_sdwa v189, v183 dst_sel:DWORD dst_unused:UNUSED_PAD src0_sel:WORD_1
	v_cvt_f32_f16_e32 v190, v184
	v_cvt_f32_f16_sdwa v191, v184 dst_sel:DWORD dst_unused:UNUSED_PAD src0_sel:WORD_1
	v_cvt_f32_f16_e32 v192, v185
	v_cvt_f32_f16_sdwa v193, v185 dst_sel:DWORD dst_unused:UNUSED_PAD src0_sel:WORD_1
	v_pk_add_f32 v[6:7], v[186:187], v[6:7]
	v_pk_add_f32 v[8:9], v[188:189], v[8:9]
	v_pk_add_f32 v[2:3], v[190:191], v[2:3]
	v_pk_add_f32 v[4:5], v[192:193], v[4:5]
	v_cvt_pk_f16_f32 v5, v4, v5
	v_cvt_pk_f16_f32 v4, v2, v3
	v_cvt_pk_f16_f32 v3, v8, v9
	v_cvt_pk_f16_f32 v2, v6, v7
	global_store_dwordx4 v[206:207], v[2:5], off offset:64
	s_mov_b64 s[0:1], -1
	s_andn2_b64 vcc, exec, s[2:3]
	s_cbranch_vccnz .LBB0_2930
	s_andn2_b64 vcc, exec, s[8:9]
	s_cbranch_vccnz .LBB0_2929
	s_barrier
	s_branch .LBB0_2929

.LBB0_3180:
	ds_read_b128 v[130:133], v174
	ds_read_b128 v[134:137], v174 offset:1024
	ds_read_b128 v[138:141], v174 offset:2048
	ds_read_b128 v[158:161], v174 offset:3072
	ds_read_b128 v[162:165], v175
	ds_read_b128 v[166:169], v175 offset:1024
	ds_read_b128 v[178:181], v175 offset:2048
	ds_read_b128 v[182:185], v175 offset:3072
	s_add_u32 s34, s40, 0xffea0080
	s_addc_u32 s35, s41, -1
	s_cmpk_eq_i32 s60, 0x54
	s_cselect_b32 s43, s5, s35
	s_cselect_b32 s42, s4, s34
	s_cselect_b32 s35, s39, s1
	s_cselect_b32 s34, s38, s0
	v_lshl_add_u64 v[170:171], s[40:41], 0, v[150:151]
	s_add_i32 m0, s33, 0xc000
	ds_read_b128 v[186:189], v176
	ds_read_b128 v[190:193], v176 offset:1024
	ds_read_b128 v[194:197], v176 offset:2048
	ds_read_b128 v[198:201], v176 offset:3072
	ds_read_b128 v[202:205], v176 offset:4096
	ds_read_b128 v[206:209], v176 offset:5120
	ds_read_b128 v[210:213], v176 offset:6144
	ds_read_b128 v[218:221], v176 offset:7168
	global_load_lds_dwordx4 v[170:171], off
	v_lshl_add_u64 v[170:171], s[40:41], 0, v[152:153]
	s_add_i32 m0, s33, 0xe000
	s_nop 0
	global_load_lds_dwordx4 v[170:171], off
	s_waitcnt vmcnt(8)
	s_waitcnt lgkmcnt(0)
	s_barrier
	s_setprio 1
	s_waitcnt lgkmcnt(0)
	v_mfma_f32_16x16x32_bf16 v[126:129], v[130:133], v[186:189], v[126:129]
	v_mfma_f32_16x16x32_bf16 v[122:125], v[138:141], v[186:189], v[122:125]
	v_mfma_f32_16x16x32_bf16 v[110:113], v[130:133], v[194:197], v[110:113]
	v_mfma_f32_16x16x32_bf16 v[106:109], v[138:141], v[194:197], v[106:109]
	v_mfma_f32_16x16x32_bf16 v[94:97], v[130:133], v[202:205], v[94:97]
	v_mfma_f32_16x16x32_bf16 v[90:93], v[138:141], v[202:205], v[90:93]
	v_mfma_f32_16x16x32_bf16 v[78:81], v[130:133], v[210:213], v[78:81]
	v_mfma_f32_16x16x32_bf16 v[74:77], v[138:141], v[210:213], v[74:77]
	v_mfma_f32_16x16x32_bf16 v[126:129], v[134:137], v[190:193], v[126:129]
	v_mfma_f32_16x16x32_bf16 v[122:125], v[158:161], v[190:193], v[122:125]
	v_mfma_f32_16x16x32_bf16 v[110:113], v[134:137], v[198:201], v[110:113]
	v_mfma_f32_16x16x32_bf16 v[106:109], v[158:161], v[198:201], v[106:109]
	v_mfma_f32_16x16x32_bf16 v[94:97], v[134:137], v[206:209], v[94:97]
	v_mfma_f32_16x16x32_bf16 v[90:93], v[158:161], v[206:209], v[90:93]
	v_mfma_f32_16x16x32_bf16 v[78:81], v[134:137], v[218:221], v[78:81]
	v_mfma_f32_16x16x32_bf16 v[74:77], v[158:161], v[218:221], v[74:77]
	s_setprio 0
	s_setprio 1
	v_mfma_f32_16x16x32_bf16 v[118:121], v[162:165], v[186:189], v[118:121]
	v_mfma_f32_16x16x32_bf16 v[114:117], v[178:181], v[186:189], v[114:117]
	v_mfma_f32_16x16x32_bf16 v[102:105], v[162:165], v[194:197], v[102:105]
	v_mfma_f32_16x16x32_bf16 v[98:101], v[178:181], v[194:197], v[98:101]
	v_mfma_f32_16x16x32_bf16 v[86:89], v[162:165], v[202:205], v[86:89]
	v_mfma_f32_16x16x32_bf16 v[82:85], v[178:181], v[202:205], v[82:85]
	v_mfma_f32_16x16x32_bf16 v[70:73], v[162:165], v[210:213], v[70:73]
	v_mfma_f32_16x16x32_bf16 v[66:69], v[178:181], v[210:213], v[66:69]
	v_mfma_f32_16x16x32_bf16 v[118:121], v[166:169], v[190:193], v[118:121]
	v_mfma_f32_16x16x32_bf16 v[114:117], v[182:185], v[190:193], v[114:117]
	v_mfma_f32_16x16x32_bf16 v[102:105], v[166:169], v[198:201], v[102:105]
	v_mfma_f32_16x16x32_bf16 v[98:101], v[182:185], v[198:201], v[98:101]
	v_mfma_f32_16x16x32_bf16 v[86:89], v[166:169], v[206:209], v[86:89]
	v_mfma_f32_16x16x32_bf16 v[82:85], v[182:185], v[206:209], v[82:85]
	v_mfma_f32_16x16x32_bf16 v[70:73], v[166:169], v[218:221], v[70:73]
	v_mfma_f32_16x16x32_bf16 v[66:69], v[182:185], v[218:221], v[66:69]
	s_setprio 0
	s_barrier
	s_add_i32 s61, s53, s31
	v_lshl_add_u64 v[170:171], s[34:35], 0, v[144:145]
	s_mov_b32 m0, s61
	ds_read_b128 v[186:189], v176 offset:16384
	ds_read_b128 v[190:193], v176 offset:17408
	ds_read_b128 v[194:197], v176 offset:18432
	ds_read_b128 v[198:201], v176 offset:19456
	ds_read_b128 v[202:205], v176 offset:20480
	ds_read_b128 v[206:209], v176 offset:21504
	ds_read_b128 v[210:213], v176 offset:22528
	ds_read_b128 v[218:221], v176 offset:23552
	global_load_lds_dwordx4 v[170:171], off
	s_add_i32 m0, s61, 0x2000
	s_add_u32 s62, s34, 0x160000
	v_lshl_add_u64 v[214:215], s[34:35], 0, v[148:149]
	s_addc_u32 s63, s35, 0
	s_add_i32 s61, s54, s31
	global_load_lds_dwordx4 v[214:215], off
	v_lshl_add_u64 v[222:223], s[62:63], 0, v[144:145]
	s_mov_b32 m0, s61
	v_lshl_add_u64 v[224:225], s[42:43], 0, v[146:147]
	global_load_lds_dwordx4 v[222:223], off
	v_lshl_add_u64 v[222:223], s[62:63], 0, v[148:149]
	s_add_i32 m0, s61, 0x2000
	s_nop 0
	global_load_lds_dwordx4 v[222:223], off
	v_lshl_add_u64 v[222:223], s[42:43], 0, v[142:143]
	s_mov_b32 m0, s33
	s_nop 0
	global_load_lds_dwordx4 v[222:223], off
	s_mov_b32 m0, s44
	s_nop 0
	global_load_lds_dwordx4 v[224:225], off
	s_waitcnt vmcnt(8)
	s_waitcnt lgkmcnt(0)
	s_barrier
	s_setprio 1
	s_waitcnt lgkmcnt(0)
	v_mfma_f32_16x16x32_bf16 v[62:65], v[130:133], v[186:189], v[62:65]
	v_mfma_f32_16x16x32_bf16 v[58:61], v[138:141], v[186:189], v[58:61]
	v_mfma_f32_16x16x32_bf16 v[50:53], v[130:133], v[194:197], v[50:53]
	v_mfma_f32_16x16x32_bf16 v[42:45], v[138:141], v[194:197], v[42:45]
	v_mfma_f32_16x16x32_bf16 v[38:41], v[130:133], v[202:205], v[38:41]
	v_mfma_f32_16x16x32_bf16 v[34:37], v[138:141], v[202:205], v[34:37]
	v_mfma_f32_16x16x32_bf16 v[14:17], v[130:133], v[210:213], v[14:17]
	v_mfma_f32_16x16x32_bf16 v[10:13], v[138:141], v[210:213], v[10:13]
	v_mfma_f32_16x16x32_bf16 v[62:65], v[134:137], v[190:193], v[62:65]
	v_mfma_f32_16x16x32_bf16 v[58:61], v[158:161], v[190:193], v[58:61]
	v_mfma_f32_16x16x32_bf16 v[50:53], v[134:137], v[198:201], v[50:53]
	v_mfma_f32_16x16x32_bf16 v[42:45], v[158:161], v[198:201], v[42:45]
	v_mfma_f32_16x16x32_bf16 v[38:41], v[134:137], v[206:209], v[38:41]
	v_mfma_f32_16x16x32_bf16 v[34:37], v[158:161], v[206:209], v[34:37]
	v_mfma_f32_16x16x32_bf16 v[14:17], v[134:137], v[218:221], v[14:17]
	v_mfma_f32_16x16x32_bf16 v[10:13], v[158:161], v[218:221], v[10:13]
	s_setprio 0
	s_setprio 1
	v_mfma_f32_16x16x32_bf16 v[54:57], v[162:165], v[186:189], v[54:57]
	v_mfma_f32_16x16x32_bf16 v[46:49], v[178:181], v[186:189], v[46:49]
	v_mfma_f32_16x16x32_bf16 v[30:33], v[162:165], v[194:197], v[30:33]
	v_mfma_f32_16x16x32_bf16 v[26:29], v[178:181], v[194:197], v[26:29]
	v_mfma_f32_16x16x32_bf16 v[22:25], v[162:165], v[202:205], v[22:25]
	v_mfma_f32_16x16x32_bf16 v[18:21], v[178:181], v[202:205], v[18:21]
	v_mfma_f32_16x16x32_bf16 v[6:9], v[162:165], v[210:213], v[6:9]
	v_mfma_f32_16x16x32_bf16 v[2:5], v[178:181], v[210:213], v[2:5]
	v_mfma_f32_16x16x32_bf16 v[54:57], v[166:169], v[190:193], v[54:57]
	v_mfma_f32_16x16x32_bf16 v[46:49], v[182:185], v[190:193], v[46:49]
	v_mfma_f32_16x16x32_bf16 v[30:33], v[166:169], v[198:201], v[30:33]
	v_mfma_f32_16x16x32_bf16 v[26:29], v[182:185], v[198:201], v[26:29]
	v_mfma_f32_16x16x32_bf16 v[22:25], v[166:169], v[206:209], v[22:25]
	v_mfma_f32_16x16x32_bf16 v[18:21], v[182:185], v[206:209], v[18:21]
	v_mfma_f32_16x16x32_bf16 v[6:9], v[166:169], v[218:221], v[6:9]
	v_mfma_f32_16x16x32_bf16 v[2:5], v[182:185], v[218:221], v[2:5]
	s_setprio 0
	s_barrier
	s_add_i32 s61, 0, 0x18000
	s_add_i32 s62, 0, 0x1c000
	v_add_u32_e32 v158, s61, v172
	v_add_u32_e32 v177, 0x19000, v172
	ds_read_b128 v[130:133], v158
	ds_read_b128 v[134:137], v158 offset:1024
	ds_read_b128 v[138:141], v158 offset:2048
	ds_read_b128 v[158:161], v158 offset:3072
	ds_read_b128 v[162:165], v177
	ds_read_b128 v[166:169], v177 offset:1024
	ds_read_b128 v[178:181], v177 offset:2048
	ds_read_b128 v[182:185], v177 offset:3072
	s_add_u32 s42, s42, 0x160000
	s_addc_u32 s43, s43, 0
	s_mov_b32 m0, s45
	v_lshl_add_u64 v[226:227], s[42:43], 0, v[142:143]
	ds_read_b128 v[186:189], v176 offset:32768
	ds_read_b128 v[190:193], v176 offset:33792
	ds_read_b128 v[194:197], v176 offset:34816
	ds_read_b128 v[198:201], v176 offset:35840
	ds_read_b128 v[202:205], v176 offset:36864
	ds_read_b128 v[206:209], v176 offset:37888
	ds_read_b128 v[210:213], v176 offset:38912
	ds_read_b128 v[218:221], v176 offset:39936
	global_load_lds_dwordx4 v[226:227], off
	v_lshl_add_u64 v[226:227], s[42:43], 0, v[146:147]
	s_mov_b32 m0, s46
	s_nop 0
	global_load_lds_dwordx4 v[226:227], off
	s_waitcnt vmcnt(8)
	s_waitcnt lgkmcnt(0)
	s_barrier
	s_setprio 1
	s_waitcnt lgkmcnt(0)
	v_mfma_f32_16x16x32_bf16 v[126:129], v[130:133], v[186:189], v[126:129]
	v_mfma_f32_16x16x32_bf16 v[122:125], v[138:141], v[186:189], v[122:125]
	v_mfma_f32_16x16x32_bf16 v[110:113], v[130:133], v[194:197], v[110:113]
	v_mfma_f32_16x16x32_bf16 v[106:109], v[138:141], v[194:197], v[106:109]
	v_mfma_f32_16x16x32_bf16 v[94:97], v[130:133], v[202:205], v[94:97]
	v_mfma_f32_16x16x32_bf16 v[90:93], v[138:141], v[202:205], v[90:93]
	v_mfma_f32_16x16x32_bf16 v[78:81], v[130:133], v[210:213], v[78:81]
	v_mfma_f32_16x16x32_bf16 v[74:77], v[138:141], v[210:213], v[74:77]
	v_mfma_f32_16x16x32_bf16 v[126:129], v[134:137], v[190:193], v[126:129]
	v_mfma_f32_16x16x32_bf16 v[122:125], v[158:161], v[190:193], v[122:125]
	v_mfma_f32_16x16x32_bf16 v[110:113], v[134:137], v[198:201], v[110:113]
	v_mfma_f32_16x16x32_bf16 v[106:109], v[158:161], v[198:201], v[106:109]
	v_mfma_f32_16x16x32_bf16 v[94:97], v[134:137], v[206:209], v[94:97]
	v_mfma_f32_16x16x32_bf16 v[90:93], v[158:161], v[206:209], v[90:93]
	v_mfma_f32_16x16x32_bf16 v[78:81], v[134:137], v[218:221], v[78:81]
	v_mfma_f32_16x16x32_bf16 v[74:77], v[158:161], v[218:221], v[74:77]
	s_setprio 0
	s_setprio 1
	v_mfma_f32_16x16x32_bf16 v[118:121], v[162:165], v[186:189], v[118:121]
	v_mfma_f32_16x16x32_bf16 v[114:117], v[178:181], v[186:189], v[114:117]
	v_mfma_f32_16x16x32_bf16 v[102:105], v[162:165], v[194:197], v[102:105]
	v_mfma_f32_16x16x32_bf16 v[98:101], v[178:181], v[194:197], v[98:101]
	v_mfma_f32_16x16x32_bf16 v[86:89], v[162:165], v[202:205], v[86:89]
	v_mfma_f32_16x16x32_bf16 v[82:85], v[178:181], v[202:205], v[82:85]
	v_mfma_f32_16x16x32_bf16 v[70:73], v[162:165], v[210:213], v[70:73]
	v_mfma_f32_16x16x32_bf16 v[66:69], v[178:181], v[210:213], v[66:69]
	v_mfma_f32_16x16x32_bf16 v[118:121], v[166:169], v[190:193], v[118:121]
	v_mfma_f32_16x16x32_bf16 v[114:117], v[182:185], v[190:193], v[114:117]
	v_mfma_f32_16x16x32_bf16 v[102:105], v[166:169], v[198:201], v[102:105]
	v_mfma_f32_16x16x32_bf16 v[98:101], v[182:185], v[198:201], v[98:101]
	v_mfma_f32_16x16x32_bf16 v[86:89], v[166:169], v[206:209], v[86:89]
	v_mfma_f32_16x16x32_bf16 v[82:85], v[182:185], v[206:209], v[82:85]
	v_mfma_f32_16x16x32_bf16 v[70:73], v[166:169], v[218:221], v[70:73]
	v_mfma_f32_16x16x32_bf16 v[66:69], v[182:185], v[218:221], v[66:69]
	s_setprio 0
	s_barrier
	s_add_i32 s42, s61, s31
	v_lshl_add_u64 v[170:171], v[170:171], 0, s[24:25]
	s_mov_b32 m0, s42
	ds_read_b128 v[186:189], v176 offset:49152
	ds_read_b128 v[190:193], v176 offset:50176
	ds_read_b128 v[194:197], v176 offset:51200
	ds_read_b128 v[198:201], v176 offset:52224
	ds_read_b128 v[202:205], v176 offset:53248
	ds_read_b128 v[206:209], v176 offset:54272
	ds_read_b128 v[210:213], v176 offset:55296
	ds_read_b128 v[218:221], v176 offset:56320
	global_load_lds_dwordx4 v[170:171], off
	s_add_i32 m0, s42, 0x2000
	s_add_u32 s34, s34, 0x160080
	v_lshl_add_u64 v[170:171], v[214:215], 0, s[24:25]
	s_addc_u32 s35, s35, 0
	s_add_i32 s42, s62, s31
	global_load_lds_dwordx4 v[170:171], off
	v_lshl_add_u64 v[170:171], s[34:35], 0, v[144:145]
	s_mov_b32 m0, s42
	s_nop 0
	global_load_lds_dwordx4 v[170:171], off
	v_lshl_add_u64 v[170:171], s[34:35], 0, v[148:149]
	s_add_i32 m0, s42, 0x2000
	s_nop 0
	global_load_lds_dwordx4 v[170:171], off
	v_lshl_add_u64 v[170:171], v[222:223], 0, s[24:25]
	s_mov_b32 m0, s48
	s_nop 0
	global_load_lds_dwordx4 v[170:171], off
	v_lshl_add_u64 v[170:171], v[224:225], 0, s[24:25]
	s_mov_b32 m0, s49
	s_nop 0
	global_load_lds_dwordx4 v[170:171], off
	s_waitcnt vmcnt(8)
	s_waitcnt lgkmcnt(0)
	s_barrier
	s_setprio 1
	s_waitcnt lgkmcnt(0)
	v_mfma_f32_16x16x32_bf16 v[62:65], v[130:133], v[186:189], v[62:65]
	v_mfma_f32_16x16x32_bf16 v[58:61], v[138:141], v[186:189], v[58:61]
	v_mfma_f32_16x16x32_bf16 v[50:53], v[130:133], v[194:197], v[50:53]
	v_mfma_f32_16x16x32_bf16 v[42:45], v[138:141], v[194:197], v[42:45]
	v_mfma_f32_16x16x32_bf16 v[38:41], v[130:133], v[202:205], v[38:41]
	v_mfma_f32_16x16x32_bf16 v[34:37], v[138:141], v[202:205], v[34:37]
	v_mfma_f32_16x16x32_bf16 v[14:17], v[130:133], v[210:213], v[14:17]
	v_mfma_f32_16x16x32_bf16 v[10:13], v[138:141], v[210:213], v[10:13]
	v_mfma_f32_16x16x32_bf16 v[62:65], v[134:137], v[190:193], v[62:65]
	v_mfma_f32_16x16x32_bf16 v[58:61], v[158:161], v[190:193], v[58:61]
	v_mfma_f32_16x16x32_bf16 v[50:53], v[134:137], v[198:201], v[50:53]
	v_mfma_f32_16x16x32_bf16 v[42:45], v[158:161], v[198:201], v[42:45]
	v_mfma_f32_16x16x32_bf16 v[38:41], v[134:137], v[206:209], v[38:41]
	v_mfma_f32_16x16x32_bf16 v[34:37], v[158:161], v[206:209], v[34:37]
	v_mfma_f32_16x16x32_bf16 v[14:17], v[134:137], v[218:221], v[14:17]
	v_mfma_f32_16x16x32_bf16 v[10:13], v[158:161], v[218:221], v[10:13]
	s_setprio 0
	s_setprio 1
	v_mfma_f32_16x16x32_bf16 v[54:57], v[162:165], v[186:189], v[54:57]
	v_mfma_f32_16x16x32_bf16 v[46:49], v[178:181], v[186:189], v[46:49]
	v_mfma_f32_16x16x32_bf16 v[30:33], v[162:165], v[194:197], v[30:33]
	v_mfma_f32_16x16x32_bf16 v[26:29], v[178:181], v[194:197], v[26:29]
	v_mfma_f32_16x16x32_bf16 v[22:25], v[162:165], v[202:205], v[22:25]
	v_mfma_f32_16x16x32_bf16 v[18:21], v[178:181], v[202:205], v[18:21]
	v_mfma_f32_16x16x32_bf16 v[6:9], v[162:165], v[210:213], v[6:9]
	v_mfma_f32_16x16x32_bf16 v[2:5], v[178:181], v[210:213], v[2:5]
	v_mfma_f32_16x16x32_bf16 v[54:57], v[166:169], v[190:193], v[54:57]
	v_mfma_f32_16x16x32_bf16 v[46:49], v[182:185], v[190:193], v[46:49]
	v_mfma_f32_16x16x32_bf16 v[30:33], v[166:169], v[198:201], v[30:33]
	v_mfma_f32_16x16x32_bf16 v[26:29], v[182:185], v[198:201], v[26:29]
	v_mfma_f32_16x16x32_bf16 v[22:25], v[166:169], v[206:209], v[22:25]
	v_mfma_f32_16x16x32_bf16 v[18:21], v[182:185], v[206:209], v[18:21]
	v_mfma_f32_16x16x32_bf16 v[6:9], v[166:169], v[218:221], v[6:9]
	v_mfma_f32_16x16x32_bf16 v[2:5], v[182:185], v[218:221], v[2:5]
	s_setprio 0
	s_barrier
	s_add_i32 s60, s60, 2
	s_add_u32 s40, s40, 0x100
	s_addc_u32 s41, s41, 0
	s_add_u32 s0, s0, 0x100
	s_addc_u32 s1, s1, 0
	s_cmpk_gt_u32 s60, 0x55
	s_cbranch_scc0 .LBB0_3180
	v_lshl_or_b32 v130, s59, 8, v173
	v_lshl_add_u32 v158, s58, 8, v1
	v_ashrrev_i32_e32 v131, 31, v130
	v_lshlrev_b64 v[160:161], 1, v[130:131]
	v_or_b32_e32 v130, 16, v158
	v_ashrrev_i32_e32 v159, 31, v158
	v_ashrrev_i32_e32 v131, 31, v130
	v_lshlrev_b64 v[132:133], 12, v[158:159]
	v_lshlrev_b64 v[130:131], 12, v[130:131]
	v_lshl_add_u64 v[132:133], s[64:65], 0, v[132:133]
	v_lshl_add_u64 v[130:131], s[64:65], 0, v[130:131]
	v_lshl_add_u64 v[170:171], v[132:133], 0, v[160:161]
	v_lshl_add_u64 v[168:169], v[130:131], 0, v[160:161]
	v_mov_b32_e32 v209, 0
	v_mov_b32_e32 v208, 0x10000
	v_lshl_add_u64 v[194:195], v[208:209], 0, v[170:171]
	v_mov_b32_e32 v208, 0x20000
	v_lshl_add_u64 v[196:197], v[208:209], 0, v[170:171]
	v_mov_b32_e32 v208, 0x30000
	v_lshl_add_u64 v[198:199], v[208:209], 0, v[170:171]
	v_mov_b32_e32 v208, 0x80000
	v_lshl_add_u64 v[200:201], v[208:209], 0, v[170:171]
	v_mov_b32_e32 v208, 0x90000
	v_lshl_add_u64 v[202:203], v[208:209], 0, v[170:171]
	v_mov_b32_e32 v208, 0xa0000
	v_lshl_add_u64 v[204:205], v[208:209], 0, v[170:171]
	v_mov_b32_e32 v208, 0xb0000
	v_lshl_add_u64 v[206:207], v[208:209], 0, v[170:171]
	global_load_dwordx4 v[130:133], v[170:171], off
	global_load_dwordx4 v[134:137], v[170:171], off offset:64
	global_load_dwordx4 v[138:141], v[194:195], off
	global_load_dwordx4 v[158:161], v[194:195], off offset:64
	global_load_dwordx4 v[162:165], v[196:197], off
	global_load_dwordx4 v[166:169], v[196:197], off offset:64
	global_load_dwordx4 v[178:181], v[198:199], off
	global_load_dwordx4 v[182:185], v[198:199], off offset:64
	s_and_b64 vcc, exec, s[26:27]
	s_cbranch_vccz .LBB0_3183
	s_barrier
.LBB0_3183:
	s_waitcnt vmcnt(7)
	v_cvt_f32_f16_e32 v186, v130
	v_cvt_f32_f16_sdwa v187, v130 dst_sel:DWORD dst_unused:UNUSED_PAD src0_sel:WORD_1
	v_cvt_f32_f16_e32 v188, v131
	v_cvt_f32_f16_sdwa v189, v131 dst_sel:DWORD dst_unused:UNUSED_PAD src0_sel:WORD_1
	v_cvt_f32_f16_e32 v190, v132
	v_cvt_f32_f16_sdwa v191, v132 dst_sel:DWORD dst_unused:UNUSED_PAD src0_sel:WORD_1
	v_cvt_f32_f16_e32 v192, v133
	v_cvt_f32_f16_sdwa v193, v133 dst_sel:DWORD dst_unused:UNUSED_PAD src0_sel:WORD_1
	global_load_dwordx4 v[130:133], v[200:201], off
	v_pk_fma_f32 v[126:127], v[126:127], 0.5, v[186:187] op_sel_hi:[1,0,1]
	v_pk_fma_f32 v[128:129], v[128:129], 0.5, v[188:189] op_sel_hi:[1,0,1]
	v_pk_fma_f32 v[122:123], v[122:123], 0.5, v[190:191] op_sel_hi:[1,0,1]
	v_pk_fma_f32 v[124:125], v[124:125], 0.5, v[192:193] op_sel_hi:[1,0,1]
	v_cvt_pk_f16_f32 v125, v124, v125
	v_cvt_pk_f16_f32 v124, v122, v123
	v_cvt_pk_f16_f32 v123, v128, v129
	v_cvt_pk_f16_f32 v122, v126, v127
	global_store_dwordx4 v[170:171], v[122:125], off
	s_waitcnt vmcnt(8)
	v_cvt_f32_f16_e32 v186, v134
	v_cvt_f32_f16_sdwa v187, v134 dst_sel:DWORD dst_unused:UNUSED_PAD src0_sel:WORD_1
	v_cvt_f32_f16_e32 v188, v135
	v_cvt_f32_f16_sdwa v189, v135 dst_sel:DWORD dst_unused:UNUSED_PAD src0_sel:WORD_1
	v_cvt_f32_f16_e32 v190, v136
	v_cvt_f32_f16_sdwa v191, v136 dst_sel:DWORD dst_unused:UNUSED_PAD src0_sel:WORD_1
	v_cvt_f32_f16_e32 v192, v137
	v_cvt_f32_f16_sdwa v193, v137 dst_sel:DWORD dst_unused:UNUSED_PAD src0_sel:WORD_1
	global_load_dwordx4 v[134:137], v[200:201], off offset:64
	v_pk_fma_f32 v[118:119], v[118:119], 0.5, v[186:187] op_sel_hi:[1,0,1]
	v_pk_fma_f32 v[120:121], v[120:121], 0.5, v[188:189] op_sel_hi:[1,0,1]
	v_pk_fma_f32 v[114:115], v[114:115], 0.5, v[190:191] op_sel_hi:[1,0,1]
	v_pk_fma_f32 v[116:117], v[116:117], 0.5, v[192:193] op_sel_hi:[1,0,1]
	v_cvt_pk_f16_f32 v117, v116, v117
	v_cvt_pk_f16_f32 v116, v114, v115
	v_cvt_pk_f16_f32 v115, v120, v121
	v_cvt_pk_f16_f32 v114, v118, v119
	global_store_dwordx4 v[170:171], v[114:117], off offset:64
	s_waitcnt vmcnt(9)
	v_cvt_f32_f16_e32 v186, v138
	v_cvt_f32_f16_sdwa v187, v138 dst_sel:DWORD dst_unused:UNUSED_PAD src0_sel:WORD_1
	v_cvt_f32_f16_e32 v188, v139
	v_cvt_f32_f16_sdwa v189, v139 dst_sel:DWORD dst_unused:UNUSED_PAD src0_sel:WORD_1
	v_cvt_f32_f16_e32 v190, v140
	v_cvt_f32_f16_sdwa v191, v140 dst_sel:DWORD dst_unused:UNUSED_PAD src0_sel:WORD_1
	v_cvt_f32_f16_e32 v192, v141
	v_cvt_f32_f16_sdwa v193, v141 dst_sel:DWORD dst_unused:UNUSED_PAD src0_sel:WORD_1
	global_load_dwordx4 v[138:141], v[202:203], off
	v_pk_fma_f32 v[110:111], v[110:111], 0.5, v[186:187] op_sel_hi:[1,0,1]
	v_pk_fma_f32 v[112:113], v[112:113], 0.5, v[188:189] op_sel_hi:[1,0,1]
	v_pk_fma_f32 v[106:107], v[106:107], 0.5, v[190:191] op_sel_hi:[1,0,1]
	v_pk_fma_f32 v[108:109], v[108:109], 0.5, v[192:193] op_sel_hi:[1,0,1]
	v_cvt_pk_f16_f32 v109, v108, v109
	v_cvt_pk_f16_f32 v108, v106, v107
	v_cvt_pk_f16_f32 v107, v112, v113
	v_cvt_pk_f16_f32 v106, v110, v111
	global_store_dwordx4 v[194:195], v[106:109], off
	s_waitcnt vmcnt(10)
	v_cvt_f32_f16_e32 v186, v158
	v_cvt_f32_f16_sdwa v187, v158 dst_sel:DWORD dst_unused:UNUSED_PAD src0_sel:WORD_1
	v_cvt_f32_f16_e32 v188, v159
	v_cvt_f32_f16_sdwa v189, v159 dst_sel:DWORD dst_unused:UNUSED_PAD src0_sel:WORD_1
	v_cvt_f32_f16_e32 v190, v160
	v_cvt_f32_f16_sdwa v191, v160 dst_sel:DWORD dst_unused:UNUSED_PAD src0_sel:WORD_1
	v_cvt_f32_f16_e32 v192, v161
	v_cvt_f32_f16_sdwa v193, v161 dst_sel:DWORD dst_unused:UNUSED_PAD src0_sel:WORD_1
	global_load_dwordx4 v[158:161], v[202:203], off offset:64
	v_pk_fma_f32 v[102:103], v[102:103], 0.5, v[186:187] op_sel_hi:[1,0,1]
	v_pk_fma_f32 v[104:105], v[104:105], 0.5, v[188:189] op_sel_hi:[1,0,1]
	v_pk_fma_f32 v[98:99], v[98:99], 0.5, v[190:191] op_sel_hi:[1,0,1]
	v_pk_fma_f32 v[100:101], v[100:101], 0.5, v[192:193] op_sel_hi:[1,0,1]
	v_cvt_pk_f16_f32 v101, v100, v101
	v_cvt_pk_f16_f32 v100, v98, v99
	v_cvt_pk_f16_f32 v99, v104, v105
	v_cvt_pk_f16_f32 v98, v102, v103
	global_store_dwordx4 v[194:195], v[98:101], off offset:64
	s_waitcnt vmcnt(11)
	v_cvt_f32_f16_e32 v186, v162
	v_cvt_f32_f16_sdwa v187, v162 dst_sel:DWORD dst_unused:UNUSED_PAD src0_sel:WORD_1
	v_cvt_f32_f16_e32 v188, v163
	v_cvt_f32_f16_sdwa v189, v163 dst_sel:DWORD dst_unused:UNUSED_PAD src0_sel:WORD_1
	v_cvt_f32_f16_e32 v190, v164
	v_cvt_f32_f16_sdwa v191, v164 dst_sel:DWORD dst_unused:UNUSED_PAD src0_sel:WORD_1
	v_cvt_f32_f16_e32 v192, v165
	v_cvt_f32_f16_sdwa v193, v165 dst_sel:DWORD dst_unused:UNUSED_PAD src0_sel:WORD_1
	global_load_dwordx4 v[162:165], v[204:205], off
	v_pk_fma_f32 v[94:95], v[94:95], 0.5, v[186:187] op_sel_hi:[1,0,1]
	v_pk_fma_f32 v[96:97], v[96:97], 0.5, v[188:189] op_sel_hi:[1,0,1]
	v_pk_fma_f32 v[90:91], v[90:91], 0.5, v[190:191] op_sel_hi:[1,0,1]
	v_pk_fma_f32 v[92:93], v[92:93], 0.5, v[192:193] op_sel_hi:[1,0,1]
	v_cvt_pk_f16_f32 v93, v92, v93
	v_cvt_pk_f16_f32 v92, v90, v91
	v_cvt_pk_f16_f32 v91, v96, v97
	v_cvt_pk_f16_f32 v90, v94, v95
	global_store_dwordx4 v[196:197], v[90:93], off
	s_waitcnt vmcnt(12)
	v_cvt_f32_f16_e32 v186, v166
	v_cvt_f32_f16_sdwa v187, v166 dst_sel:DWORD dst_unused:UNUSED_PAD src0_sel:WORD_1
	v_cvt_f32_f16_e32 v188, v167
	v_cvt_f32_f16_sdwa v189, v167 dst_sel:DWORD dst_unused:UNUSED_PAD src0_sel:WORD_1
	v_cvt_f32_f16_e32 v190, v168
	v_cvt_f32_f16_sdwa v191, v168 dst_sel:DWORD dst_unused:UNUSED_PAD src0_sel:WORD_1
	v_cvt_f32_f16_e32 v192, v169
	v_cvt_f32_f16_sdwa v193, v169 dst_sel:DWORD dst_unused:UNUSED_PAD src0_sel:WORD_1
	global_load_dwordx4 v[166:169], v[204:205], off offset:64
	v_pk_fma_f32 v[86:87], v[86:87], 0.5, v[186:187] op_sel_hi:[1,0,1]
	v_pk_fma_f32 v[88:89], v[88:89], 0.5, v[188:189] op_sel_hi:[1,0,1]
	v_pk_fma_f32 v[82:83], v[82:83], 0.5, v[190:191] op_sel_hi:[1,0,1]
	v_pk_fma_f32 v[84:85], v[84:85], 0.5, v[192:193] op_sel_hi:[1,0,1]
	v_cvt_pk_f16_f32 v85, v84, v85
	v_cvt_pk_f16_f32 v84, v82, v83
	v_cvt_pk_f16_f32 v83, v88, v89
	v_cvt_pk_f16_f32 v82, v86, v87
	global_store_dwordx4 v[196:197], v[82:85], off offset:64
	s_waitcnt vmcnt(13)
	v_cvt_f32_f16_e32 v186, v178
	v_cvt_f32_f16_sdwa v187, v178 dst_sel:DWORD dst_unused:UNUSED_PAD src0_sel:WORD_1
	v_cvt_f32_f16_e32 v188, v179
	v_cvt_f32_f16_sdwa v189, v179 dst_sel:DWORD dst_unused:UNUSED_PAD src0_sel:WORD_1
	v_cvt_f32_f16_e32 v190, v180
	v_cvt_f32_f16_sdwa v191, v180 dst_sel:DWORD dst_unused:UNUSED_PAD src0_sel:WORD_1
	v_cvt_f32_f16_e32 v192, v181
	v_cvt_f32_f16_sdwa v193, v181 dst_sel:DWORD dst_unused:UNUSED_PAD src0_sel:WORD_1
	global_load_dwordx4 v[178:181], v[206:207], off
	v_pk_fma_f32 v[78:79], v[78:79], 0.5, v[186:187] op_sel_hi:[1,0,1]
	v_pk_fma_f32 v[80:81], v[80:81], 0.5, v[188:189] op_sel_hi:[1,0,1]
	v_pk_fma_f32 v[74:75], v[74:75], 0.5, v[190:191] op_sel_hi:[1,0,1]
	v_pk_fma_f32 v[76:77], v[76:77], 0.5, v[192:193] op_sel_hi:[1,0,1]
	v_cvt_pk_f16_f32 v77, v76, v77
	v_cvt_pk_f16_f32 v76, v74, v75
	v_cvt_pk_f16_f32 v75, v80, v81
	v_cvt_pk_f16_f32 v74, v78, v79
	global_store_dwordx4 v[198:199], v[74:77], off
	s_waitcnt vmcnt(14)
	v_cvt_f32_f16_e32 v186, v182
	v_cvt_f32_f16_sdwa v187, v182 dst_sel:DWORD dst_unused:UNUSED_PAD src0_sel:WORD_1
	v_cvt_f32_f16_e32 v188, v183
	v_cvt_f32_f16_sdwa v189, v183 dst_sel:DWORD dst_unused:UNUSED_PAD src0_sel:WORD_1
	v_cvt_f32_f16_e32 v190, v184
	v_cvt_f32_f16_sdwa v191, v184 dst_sel:DWORD dst_unused:UNUSED_PAD src0_sel:WORD_1
	v_cvt_f32_f16_e32 v192, v185
	v_cvt_f32_f16_sdwa v193, v185 dst_sel:DWORD dst_unused:UNUSED_PAD src0_sel:WORD_1
	global_load_dwordx4 v[182:185], v[206:207], off offset:64
	v_pk_fma_f32 v[70:71], v[70:71], 0.5, v[186:187] op_sel_hi:[1,0,1]
	v_pk_fma_f32 v[72:73], v[72:73], 0.5, v[188:189] op_sel_hi:[1,0,1]
	v_pk_fma_f32 v[66:67], v[66:67], 0.5, v[190:191] op_sel_hi:[1,0,1]
	v_pk_fma_f32 v[68:69], v[68:69], 0.5, v[192:193] op_sel_hi:[1,0,1]
	v_cvt_pk_f16_f32 v69, v68, v69
	v_cvt_pk_f16_f32 v68, v66, v67
	v_cvt_pk_f16_f32 v67, v72, v73
	v_cvt_pk_f16_f32 v66, v70, v71
	global_store_dwordx4 v[198:199], v[66:69], off offset:64
	s_waitcnt vmcnt(15)
	v_cvt_f32_f16_e32 v186, v130
	v_cvt_f32_f16_sdwa v187, v130 dst_sel:DWORD dst_unused:UNUSED_PAD src0_sel:WORD_1
	v_cvt_f32_f16_e32 v188, v131
	v_cvt_f32_f16_sdwa v189, v131 dst_sel:DWORD dst_unused:UNUSED_PAD src0_sel:WORD_1
	v_cvt_f32_f16_e32 v190, v132
	v_cvt_f32_f16_sdwa v191, v132 dst_sel:DWORD dst_unused:UNUSED_PAD src0_sel:WORD_1
	v_cvt_f32_f16_e32 v192, v133
	v_cvt_f32_f16_sdwa v193, v133 dst_sel:DWORD dst_unused:UNUSED_PAD src0_sel:WORD_1
	v_pk_fma_f32 v[62:63], v[62:63], 0.5, v[186:187] op_sel_hi:[1,0,1]
	v_pk_fma_f32 v[64:65], v[64:65], 0.5, v[188:189] op_sel_hi:[1,0,1]
	v_pk_fma_f32 v[58:59], v[58:59], 0.5, v[190:191] op_sel_hi:[1,0,1]
	v_pk_fma_f32 v[60:61], v[60:61], 0.5, v[192:193] op_sel_hi:[1,0,1]
	v_cvt_pk_f16_f32 v61, v60, v61
	v_cvt_pk_f16_f32 v60, v58, v59
	v_cvt_pk_f16_f32 v59, v64, v65
	v_cvt_pk_f16_f32 v58, v62, v63
	global_store_dwordx4 v[200:201], v[58:61], off
	s_waitcnt vmcnt(14)
	v_cvt_f32_f16_e32 v186, v134
	v_cvt_f32_f16_sdwa v187, v134 dst_sel:DWORD dst_unused:UNUSED_PAD src0_sel:WORD_1
	v_cvt_f32_f16_e32 v188, v135
	v_cvt_f32_f16_sdwa v189, v135 dst_sel:DWORD dst_unused:UNUSED_PAD src0_sel:WORD_1
	v_cvt_f32_f16_e32 v190, v136
	v_cvt_f32_f16_sdwa v191, v136 dst_sel:DWORD dst_unused:UNUSED_PAD src0_sel:WORD_1
	v_cvt_f32_f16_e32 v192, v137
	v_cvt_f32_f16_sdwa v193, v137 dst_sel:DWORD dst_unused:UNUSED_PAD src0_sel:WORD_1
	v_pk_fma_f32 v[54:55], v[54:55], 0.5, v[186:187] op_sel_hi:[1,0,1]
	v_pk_fma_f32 v[56:57], v[56:57], 0.5, v[188:189] op_sel_hi:[1,0,1]
	v_pk_fma_f32 v[46:47], v[46:47], 0.5, v[190:191] op_sel_hi:[1,0,1]
	v_pk_fma_f32 v[48:49], v[48:49], 0.5, v[192:193] op_sel_hi:[1,0,1]
	v_cvt_pk_f16_f32 v49, v48, v49
	v_cvt_pk_f16_f32 v48, v46, v47
	v_cvt_pk_f16_f32 v47, v56, v57
	v_cvt_pk_f16_f32 v46, v54, v55
	global_store_dwordx4 v[200:201], v[46:49], off offset:64
	s_waitcnt vmcnt(13)
	v_cvt_f32_f16_e32 v186, v138
	v_cvt_f32_f16_sdwa v187, v138 dst_sel:DWORD dst_unused:UNUSED_PAD src0_sel:WORD_1
	v_cvt_f32_f16_e32 v188, v139
	v_cvt_f32_f16_sdwa v189, v139 dst_sel:DWORD dst_unused:UNUSED_PAD src0_sel:WORD_1
	v_cvt_f32_f16_e32 v190, v140
	v_cvt_f32_f16_sdwa v191, v140 dst_sel:DWORD dst_unused:UNUSED_PAD src0_sel:WORD_1
	v_cvt_f32_f16_e32 v192, v141
	v_cvt_f32_f16_sdwa v193, v141 dst_sel:DWORD dst_unused:UNUSED_PAD src0_sel:WORD_1
	v_pk_fma_f32 v[50:51], v[50:51], 0.5, v[186:187] op_sel_hi:[1,0,1]
	v_pk_fma_f32 v[52:53], v[52:53], 0.5, v[188:189] op_sel_hi:[1,0,1]
	v_pk_fma_f32 v[42:43], v[42:43], 0.5, v[190:191] op_sel_hi:[1,0,1]
	v_pk_fma_f32 v[44:45], v[44:45], 0.5, v[192:193] op_sel_hi:[1,0,1]
	v_cvt_pk_f16_f32 v45, v44, v45
	v_cvt_pk_f16_f32 v44, v42, v43
	v_cvt_pk_f16_f32 v43, v52, v53
	v_cvt_pk_f16_f32 v42, v50, v51
	global_store_dwordx4 v[202:203], v[42:45], off
	s_waitcnt vmcnt(12)
	v_cvt_f32_f16_e32 v186, v158
	v_cvt_f32_f16_sdwa v187, v158 dst_sel:DWORD dst_unused:UNUSED_PAD src0_sel:WORD_1
	v_cvt_f32_f16_e32 v188, v159
	v_cvt_f32_f16_sdwa v189, v159 dst_sel:DWORD dst_unused:UNUSED_PAD src0_sel:WORD_1
	v_cvt_f32_f16_e32 v190, v160
	v_cvt_f32_f16_sdwa v191, v160 dst_sel:DWORD dst_unused:UNUSED_PAD src0_sel:WORD_1
	v_cvt_f32_f16_e32 v192, v161
	v_cvt_f32_f16_sdwa v193, v161 dst_sel:DWORD dst_unused:UNUSED_PAD src0_sel:WORD_1
	v_pk_fma_f32 v[30:31], v[30:31], 0.5, v[186:187] op_sel_hi:[1,0,1]
	v_pk_fma_f32 v[32:33], v[32:33], 0.5, v[188:189] op_sel_hi:[1,0,1]
	v_pk_fma_f32 v[26:27], v[26:27], 0.5, v[190:191] op_sel_hi:[1,0,1]
	v_pk_fma_f32 v[28:29], v[28:29], 0.5, v[192:193] op_sel_hi:[1,0,1]
	v_cvt_pk_f16_f32 v29, v28, v29
	v_cvt_pk_f16_f32 v28, v26, v27
	v_cvt_pk_f16_f32 v27, v32, v33
	v_cvt_pk_f16_f32 v26, v30, v31
	global_store_dwordx4 v[202:203], v[26:29], off offset:64
	s_waitcnt vmcnt(11)
	v_cvt_f32_f16_e32 v186, v162
	v_cvt_f32_f16_sdwa v187, v162 dst_sel:DWORD dst_unused:UNUSED_PAD src0_sel:WORD_1
	v_cvt_f32_f16_e32 v188, v163
	v_cvt_f32_f16_sdwa v189, v163 dst_sel:DWORD dst_unused:UNUSED_PAD src0_sel:WORD_1
	v_cvt_f32_f16_e32 v190, v164
	v_cvt_f32_f16_sdwa v191, v164 dst_sel:DWORD dst_unused:UNUSED_PAD src0_sel:WORD_1
	v_cvt_f32_f16_e32 v192, v165
	v_cvt_f32_f16_sdwa v193, v165 dst_sel:DWORD dst_unused:UNUSED_PAD src0_sel:WORD_1
	v_pk_fma_f32 v[38:39], v[38:39], 0.5, v[186:187] op_sel_hi:[1,0,1]
	v_pk_fma_f32 v[40:41], v[40:41], 0.5, v[188:189] op_sel_hi:[1,0,1]
	v_pk_fma_f32 v[34:35], v[34:35], 0.5, v[190:191] op_sel_hi:[1,0,1]
	v_pk_fma_f32 v[36:37], v[36:37], 0.5, v[192:193] op_sel_hi:[1,0,1]
	v_cvt_pk_f16_f32 v37, v36, v37
	v_cvt_pk_f16_f32 v36, v34, v35
	v_cvt_pk_f16_f32 v35, v40, v41
	v_cvt_pk_f16_f32 v34, v38, v39
	global_store_dwordx4 v[204:205], v[34:37], off
	s_waitcnt vmcnt(10)
	v_cvt_f32_f16_e32 v186, v166
	v_cvt_f32_f16_sdwa v187, v166 dst_sel:DWORD dst_unused:UNUSED_PAD src0_sel:WORD_1
	v_cvt_f32_f16_e32 v188, v167
	v_cvt_f32_f16_sdwa v189, v167 dst_sel:DWORD dst_unused:UNUSED_PAD src0_sel:WORD_1
	v_cvt_f32_f16_e32 v190, v168
	v_cvt_f32_f16_sdwa v191, v168 dst_sel:DWORD dst_unused:UNUSED_PAD src0_sel:WORD_1
	v_cvt_f32_f16_e32 v192, v169
	v_cvt_f32_f16_sdwa v193, v169 dst_sel:DWORD dst_unused:UNUSED_PAD src0_sel:WORD_1
	v_pk_fma_f32 v[22:23], v[22:23], 0.5, v[186:187] op_sel_hi:[1,0,1]
	v_pk_fma_f32 v[24:25], v[24:25], 0.5, v[188:189] op_sel_hi:[1,0,1]
	v_pk_fma_f32 v[18:19], v[18:19], 0.5, v[190:191] op_sel_hi:[1,0,1]
	v_pk_fma_f32 v[20:21], v[20:21], 0.5, v[192:193] op_sel_hi:[1,0,1]
	v_cvt_pk_f16_f32 v21, v20, v21
	v_cvt_pk_f16_f32 v20, v18, v19
	v_cvt_pk_f16_f32 v19, v24, v25
	v_cvt_pk_f16_f32 v18, v22, v23
	global_store_dwordx4 v[204:205], v[18:21], off offset:64
	s_waitcnt vmcnt(9)
	v_cvt_f32_f16_e32 v186, v178
	v_cvt_f32_f16_sdwa v187, v178 dst_sel:DWORD dst_unused:UNUSED_PAD src0_sel:WORD_1
	v_cvt_f32_f16_e32 v188, v179
	v_cvt_f32_f16_sdwa v189, v179 dst_sel:DWORD dst_unused:UNUSED_PAD src0_sel:WORD_1
	v_cvt_f32_f16_e32 v190, v180
	v_cvt_f32_f16_sdwa v191, v180 dst_sel:DWORD dst_unused:UNUSED_PAD src0_sel:WORD_1
	v_cvt_f32_f16_e32 v192, v181
	v_cvt_f32_f16_sdwa v193, v181 dst_sel:DWORD dst_unused:UNUSED_PAD src0_sel:WORD_1
	v_pk_fma_f32 v[14:15], v[14:15], 0.5, v[186:187] op_sel_hi:[1,0,1]
	v_pk_fma_f32 v[16:17], v[16:17], 0.5, v[188:189] op_sel_hi:[1,0,1]
	v_pk_fma_f32 v[10:11], v[10:11], 0.5, v[190:191] op_sel_hi:[1,0,1]
	v_pk_fma_f32 v[12:13], v[12:13], 0.5, v[192:193] op_sel_hi:[1,0,1]
	v_cvt_pk_f16_f32 v13, v12, v13
	v_cvt_pk_f16_f32 v12, v10, v11
	v_cvt_pk_f16_f32 v11, v16, v17
	v_cvt_pk_f16_f32 v10, v14, v15
	global_store_dwordx4 v[206:207], v[10:13], off
	s_waitcnt vmcnt(8)
	v_cvt_f32_f16_e32 v186, v182
	v_cvt_f32_f16_sdwa v187, v182 dst_sel:DWORD dst_unused:UNUSED_PAD src0_sel:WORD_1
	v_cvt_f32_f16_e32 v188, v183
	v_cvt_f32_f16_sdwa v189, v183 dst_sel:DWORD dst_unused:UNUSED_PAD src0_sel:WORD_1
	v_cvt_f32_f16_e32 v190, v184
	v_cvt_f32_f16_sdwa v191, v184 dst_sel:DWORD dst_unused:UNUSED_PAD src0_sel:WORD_1
	v_cvt_f32_f16_e32 v192, v185
	v_cvt_f32_f16_sdwa v193, v185 dst_sel:DWORD dst_unused:UNUSED_PAD src0_sel:WORD_1
	v_pk_fma_f32 v[6:7], v[6:7], 0.5, v[186:187] op_sel_hi:[1,0,1]
	v_pk_fma_f32 v[8:9], v[8:9], 0.5, v[188:189] op_sel_hi:[1,0,1]
	v_pk_fma_f32 v[2:3], v[2:3], 0.5, v[190:191] op_sel_hi:[1,0,1]
	v_pk_fma_f32 v[4:5], v[4:5], 0.5, v[192:193] op_sel_hi:[1,0,1]
	v_cvt_pk_f16_f32 v5, v4, v5
	v_cvt_pk_f16_f32 v4, v2, v3
	v_cvt_pk_f16_f32 v3, v8, v9
	v_cvt_pk_f16_f32 v2, v6, v7
	global_store_dwordx4 v[206:207], v[2:5], off offset:64
	s_mov_b64 s[0:1], -1
	s_and_b64 vcc, exec, s[2:3]
	s_cbranch_vccnz .LBB0_3168
	s_andn2_b64 vcc, exec, s[8:9]
	s_cbranch_vccnz .LBB0_3167
	s_barrier
	s_branch .LBB0_3167

.LBB0_3706:
	ds_read_b128 v[130:133], v174
	ds_read_b128 v[134:137], v174 offset:1024
	ds_read_b128 v[138:141], v174 offset:2048
	ds_read_b128 v[158:161], v174 offset:3072
	ds_read_b128 v[162:165], v175
	ds_read_b128 v[166:169], v175 offset:1024
	ds_read_b128 v[178:181], v175 offset:2048
	ds_read_b128 v[182:185], v175 offset:3072
	s_add_u32 s34, s42, 0xfff80080
	s_addc_u32 s35, s43, -1
	s_cmp_eq_u32 s60, 28
	s_cselect_b32 s45, s0, s35
	s_cselect_b32 s44, s1, s34
	s_cselect_b32 s35, s25, s59
	s_cselect_b32 s34, s27, s58
	v_lshl_add_u64 v[170:171], s[42:43], 0, v[150:151]
	s_add_i32 m0, s41, 0xc000
	ds_read_b128 v[186:189], v176
	ds_read_b128 v[190:193], v176 offset:1024
	ds_read_b128 v[194:197], v176 offset:2048
	ds_read_b128 v[198:201], v176 offset:3072
	ds_read_b128 v[202:205], v176 offset:4096
	ds_read_b128 v[206:209], v176 offset:5120
	ds_read_b128 v[210:213], v176 offset:6144
	ds_read_b128 v[218:221], v176 offset:7168
	global_load_lds_dwordx4 v[170:171], off
	v_lshl_add_u64 v[170:171], s[42:43], 0, v[152:153]
	s_add_i32 m0, s41, 0xe000
	s_nop 0
	global_load_lds_dwordx4 v[170:171], off
	s_waitcnt vmcnt(8)
	s_waitcnt lgkmcnt(0)
	s_barrier
	s_setprio 1
	s_waitcnt lgkmcnt(0)
	v_mfma_f32_16x16x32_bf16 v[126:129], v[130:133], v[186:189], v[126:129]
	v_mfma_f32_16x16x32_bf16 v[122:125], v[138:141], v[186:189], v[122:125]
	v_mfma_f32_16x16x32_bf16 v[110:113], v[130:133], v[194:197], v[110:113]
	v_mfma_f32_16x16x32_bf16 v[106:109], v[138:141], v[194:197], v[106:109]
	v_mfma_f32_16x16x32_bf16 v[94:97], v[130:133], v[202:205], v[94:97]
	v_mfma_f32_16x16x32_bf16 v[90:93], v[138:141], v[202:205], v[90:93]
	v_mfma_f32_16x16x32_bf16 v[78:81], v[130:133], v[210:213], v[78:81]
	v_mfma_f32_16x16x32_bf16 v[74:77], v[138:141], v[210:213], v[74:77]
	v_mfma_f32_16x16x32_bf16 v[126:129], v[134:137], v[190:193], v[126:129]
	v_mfma_f32_16x16x32_bf16 v[122:125], v[158:161], v[190:193], v[122:125]
	v_mfma_f32_16x16x32_bf16 v[110:113], v[134:137], v[198:201], v[110:113]
	v_mfma_f32_16x16x32_bf16 v[106:109], v[158:161], v[198:201], v[106:109]
	v_mfma_f32_16x16x32_bf16 v[94:97], v[134:137], v[206:209], v[94:97]
	v_mfma_f32_16x16x32_bf16 v[90:93], v[158:161], v[206:209], v[90:93]
	v_mfma_f32_16x16x32_bf16 v[78:81], v[134:137], v[218:221], v[78:81]
	v_mfma_f32_16x16x32_bf16 v[74:77], v[158:161], v[218:221], v[74:77]
	s_setprio 0
	s_setprio 1
	v_mfma_f32_16x16x32_bf16 v[118:121], v[162:165], v[186:189], v[118:121]
	v_mfma_f32_16x16x32_bf16 v[114:117], v[178:181], v[186:189], v[114:117]
	v_mfma_f32_16x16x32_bf16 v[102:105], v[162:165], v[194:197], v[102:105]
	v_mfma_f32_16x16x32_bf16 v[98:101], v[178:181], v[194:197], v[98:101]
	v_mfma_f32_16x16x32_bf16 v[86:89], v[162:165], v[202:205], v[86:89]
	v_mfma_f32_16x16x32_bf16 v[82:85], v[178:181], v[202:205], v[82:85]
	v_mfma_f32_16x16x32_bf16 v[70:73], v[162:165], v[210:213], v[70:73]
	v_mfma_f32_16x16x32_bf16 v[66:69], v[178:181], v[210:213], v[66:69]
	v_mfma_f32_16x16x32_bf16 v[118:121], v[166:169], v[190:193], v[118:121]
	v_mfma_f32_16x16x32_bf16 v[114:117], v[182:185], v[190:193], v[114:117]
	v_mfma_f32_16x16x32_bf16 v[102:105], v[166:169], v[198:201], v[102:105]
	v_mfma_f32_16x16x32_bf16 v[98:101], v[182:185], v[198:201], v[98:101]
	v_mfma_f32_16x16x32_bf16 v[86:89], v[166:169], v[206:209], v[86:89]
	v_mfma_f32_16x16x32_bf16 v[82:85], v[182:185], v[206:209], v[82:85]
	v_mfma_f32_16x16x32_bf16 v[70:73], v[166:169], v[218:221], v[70:73]
	v_mfma_f32_16x16x32_bf16 v[66:69], v[182:185], v[218:221], v[66:69]
	s_setprio 0
	s_barrier
	s_add_i32 s61, s54, s46
	v_lshl_add_u64 v[170:171], s[34:35], 0, v[144:145]
	s_mov_b32 m0, s61
	ds_read_b128 v[186:189], v176 offset:16384
	ds_read_b128 v[190:193], v176 offset:17408
	ds_read_b128 v[194:197], v176 offset:18432
	ds_read_b128 v[198:201], v176 offset:19456
	ds_read_b128 v[202:205], v176 offset:20480
	ds_read_b128 v[206:209], v176 offset:21504
	ds_read_b128 v[210:213], v176 offset:22528
	ds_read_b128 v[218:221], v176 offset:23552
	global_load_lds_dwordx4 v[170:171], off
	s_add_i32 m0, s61, 0x2000
	s_add_u32 s62, s34, 0x80000
	v_lshl_add_u64 v[214:215], s[34:35], 0, v[148:149]
	s_addc_u32 s63, s35, 0
	s_add_i32 s61, s55, s46
	global_load_lds_dwordx4 v[214:215], off
	v_lshl_add_u64 v[222:223], s[62:63], 0, v[144:145]
	s_mov_b32 m0, s61
	v_lshl_add_u64 v[224:225], s[44:45], 0, v[146:147]
	global_load_lds_dwordx4 v[222:223], off
	v_lshl_add_u64 v[222:223], s[62:63], 0, v[148:149]
	s_add_i32 m0, s61, 0x2000
	s_nop 0
	global_load_lds_dwordx4 v[222:223], off
	v_lshl_add_u64 v[222:223], s[44:45], 0, v[142:143]
	s_mov_b32 m0, s41
	s_nop 0
	global_load_lds_dwordx4 v[222:223], off
	s_mov_b32 m0, s47
	s_nop 0
	global_load_lds_dwordx4 v[224:225], off
	s_waitcnt vmcnt(8)
	s_waitcnt lgkmcnt(0)
	s_barrier
	s_setprio 1
	s_waitcnt lgkmcnt(0)
	v_mfma_f32_16x16x32_bf16 v[62:65], v[130:133], v[186:189], v[62:65]
	v_mfma_f32_16x16x32_bf16 v[58:61], v[138:141], v[186:189], v[58:61]
	v_mfma_f32_16x16x32_bf16 v[50:53], v[130:133], v[194:197], v[50:53]
	v_mfma_f32_16x16x32_bf16 v[42:45], v[138:141], v[194:197], v[42:45]
	v_mfma_f32_16x16x32_bf16 v[38:41], v[130:133], v[202:205], v[38:41]
	v_mfma_f32_16x16x32_bf16 v[34:37], v[138:141], v[202:205], v[34:37]
	v_mfma_f32_16x16x32_bf16 v[14:17], v[130:133], v[210:213], v[14:17]
	v_mfma_f32_16x16x32_bf16 v[10:13], v[138:141], v[210:213], v[10:13]
	v_mfma_f32_16x16x32_bf16 v[62:65], v[134:137], v[190:193], v[62:65]
	v_mfma_f32_16x16x32_bf16 v[58:61], v[158:161], v[190:193], v[58:61]
	v_mfma_f32_16x16x32_bf16 v[50:53], v[134:137], v[198:201], v[50:53]
	v_mfma_f32_16x16x32_bf16 v[42:45], v[158:161], v[198:201], v[42:45]
	v_mfma_f32_16x16x32_bf16 v[38:41], v[134:137], v[206:209], v[38:41]
	v_mfma_f32_16x16x32_bf16 v[34:37], v[158:161], v[206:209], v[34:37]
	v_mfma_f32_16x16x32_bf16 v[14:17], v[134:137], v[218:221], v[14:17]
	v_mfma_f32_16x16x32_bf16 v[10:13], v[158:161], v[218:221], v[10:13]
	s_setprio 0
	s_setprio 1
	v_mfma_f32_16x16x32_bf16 v[54:57], v[162:165], v[186:189], v[54:57]
	v_mfma_f32_16x16x32_bf16 v[46:49], v[178:181], v[186:189], v[46:49]
	v_mfma_f32_16x16x32_bf16 v[30:33], v[162:165], v[194:197], v[30:33]
	v_mfma_f32_16x16x32_bf16 v[26:29], v[178:181], v[194:197], v[26:29]
	v_mfma_f32_16x16x32_bf16 v[22:25], v[162:165], v[202:205], v[22:25]
	v_mfma_f32_16x16x32_bf16 v[18:21], v[178:181], v[202:205], v[18:21]
	v_mfma_f32_16x16x32_bf16 v[6:9], v[162:165], v[210:213], v[6:9]
	v_mfma_f32_16x16x32_bf16 v[2:5], v[178:181], v[210:213], v[2:5]
	v_mfma_f32_16x16x32_bf16 v[54:57], v[166:169], v[190:193], v[54:57]
	v_mfma_f32_16x16x32_bf16 v[46:49], v[182:185], v[190:193], v[46:49]
	v_mfma_f32_16x16x32_bf16 v[30:33], v[166:169], v[198:201], v[30:33]
	v_mfma_f32_16x16x32_bf16 v[26:29], v[182:185], v[198:201], v[26:29]
	v_mfma_f32_16x16x32_bf16 v[22:25], v[166:169], v[206:209], v[22:25]
	v_mfma_f32_16x16x32_bf16 v[18:21], v[182:185], v[206:209], v[18:21]
	v_mfma_f32_16x16x32_bf16 v[6:9], v[166:169], v[218:221], v[6:9]
	v_mfma_f32_16x16x32_bf16 v[2:5], v[182:185], v[218:221], v[2:5]
	s_setprio 0
	s_barrier
	s_add_i32 s61, 0, 0x18000
	s_add_i32 s62, 0, 0x1c000
	v_add_u32_e32 v158, s61, v172
	v_add_u32_e32 v177, 0x19000, v172
	ds_read_b128 v[130:133], v158
	ds_read_b128 v[134:137], v158 offset:1024
	ds_read_b128 v[138:141], v158 offset:2048
	ds_read_b128 v[158:161], v158 offset:3072
	ds_read_b128 v[162:165], v177
	ds_read_b128 v[166:169], v177 offset:1024
	ds_read_b128 v[178:181], v177 offset:2048
	ds_read_b128 v[182:185], v177 offset:3072
	s_add_u32 s44, s44, 0x80000
	s_addc_u32 s45, s45, 0
	s_mov_b32 m0, s48
	v_lshl_add_u64 v[226:227], s[44:45], 0, v[142:143]
	ds_read_b128 v[186:189], v176 offset:32768
	ds_read_b128 v[190:193], v176 offset:33792
	ds_read_b128 v[194:197], v176 offset:34816
	ds_read_b128 v[198:201], v176 offset:35840
	ds_read_b128 v[202:205], v176 offset:36864
	ds_read_b128 v[206:209], v176 offset:37888
	ds_read_b128 v[210:213], v176 offset:38912
	ds_read_b128 v[218:221], v176 offset:39936
	global_load_lds_dwordx4 v[226:227], off
	v_lshl_add_u64 v[226:227], s[44:45], 0, v[146:147]
	s_mov_b32 m0, s49
	s_nop 0
	global_load_lds_dwordx4 v[226:227], off
	s_waitcnt vmcnt(8)
	s_waitcnt lgkmcnt(0)
	s_barrier
	s_setprio 1
	s_waitcnt lgkmcnt(0)
	v_mfma_f32_16x16x32_bf16 v[126:129], v[130:133], v[186:189], v[126:129]
	v_mfma_f32_16x16x32_bf16 v[122:125], v[138:141], v[186:189], v[122:125]
	v_mfma_f32_16x16x32_bf16 v[110:113], v[130:133], v[194:197], v[110:113]
	v_mfma_f32_16x16x32_bf16 v[106:109], v[138:141], v[194:197], v[106:109]
	v_mfma_f32_16x16x32_bf16 v[94:97], v[130:133], v[202:205], v[94:97]
	v_mfma_f32_16x16x32_bf16 v[90:93], v[138:141], v[202:205], v[90:93]
	v_mfma_f32_16x16x32_bf16 v[78:81], v[130:133], v[210:213], v[78:81]
	v_mfma_f32_16x16x32_bf16 v[74:77], v[138:141], v[210:213], v[74:77]
	v_mfma_f32_16x16x32_bf16 v[126:129], v[134:137], v[190:193], v[126:129]
	v_mfma_f32_16x16x32_bf16 v[122:125], v[158:161], v[190:193], v[122:125]
	v_mfma_f32_16x16x32_bf16 v[110:113], v[134:137], v[198:201], v[110:113]
	v_mfma_f32_16x16x32_bf16 v[106:109], v[158:161], v[198:201], v[106:109]
	v_mfma_f32_16x16x32_bf16 v[94:97], v[134:137], v[206:209], v[94:97]
	v_mfma_f32_16x16x32_bf16 v[90:93], v[158:161], v[206:209], v[90:93]
	v_mfma_f32_16x16x32_bf16 v[78:81], v[134:137], v[218:221], v[78:81]
	v_mfma_f32_16x16x32_bf16 v[74:77], v[158:161], v[218:221], v[74:77]
	s_setprio 0
	s_setprio 1
	v_mfma_f32_16x16x32_bf16 v[118:121], v[162:165], v[186:189], v[118:121]
	v_mfma_f32_16x16x32_bf16 v[114:117], v[178:181], v[186:189], v[114:117]
	v_mfma_f32_16x16x32_bf16 v[102:105], v[162:165], v[194:197], v[102:105]
	v_mfma_f32_16x16x32_bf16 v[98:101], v[178:181], v[194:197], v[98:101]
	v_mfma_f32_16x16x32_bf16 v[86:89], v[162:165], v[202:205], v[86:89]
	v_mfma_f32_16x16x32_bf16 v[82:85], v[178:181], v[202:205], v[82:85]
	v_mfma_f32_16x16x32_bf16 v[70:73], v[162:165], v[210:213], v[70:73]
	v_mfma_f32_16x16x32_bf16 v[66:69], v[178:181], v[210:213], v[66:69]
	v_mfma_f32_16x16x32_bf16 v[118:121], v[166:169], v[190:193], v[118:121]
	v_mfma_f32_16x16x32_bf16 v[114:117], v[182:185], v[190:193], v[114:117]
	v_mfma_f32_16x16x32_bf16 v[102:105], v[166:169], v[198:201], v[102:105]
	v_mfma_f32_16x16x32_bf16 v[98:101], v[182:185], v[198:201], v[98:101]
	v_mfma_f32_16x16x32_bf16 v[86:89], v[166:169], v[206:209], v[86:89]
	v_mfma_f32_16x16x32_bf16 v[82:85], v[182:185], v[206:209], v[82:85]
	v_mfma_f32_16x16x32_bf16 v[70:73], v[166:169], v[218:221], v[70:73]
	v_mfma_f32_16x16x32_bf16 v[66:69], v[182:185], v[218:221], v[66:69]
	s_setprio 0
	s_barrier
	s_add_i32 s44, s61, s46
	v_lshl_add_u64 v[170:171], v[170:171], 0, s[12:13]
	s_mov_b32 m0, s44
	ds_read_b128 v[186:189], v176 offset:49152
	ds_read_b128 v[190:193], v176 offset:50176
	ds_read_b128 v[194:197], v176 offset:51200
	ds_read_b128 v[198:201], v176 offset:52224
	ds_read_b128 v[202:205], v176 offset:53248
	ds_read_b128 v[206:209], v176 offset:54272
	ds_read_b128 v[210:213], v176 offset:55296
	ds_read_b128 v[218:221], v176 offset:56320
	global_load_lds_dwordx4 v[170:171], off
	s_add_i32 m0, s44, 0x2000
	s_add_u32 s34, s34, 0x80080
	v_lshl_add_u64 v[170:171], v[214:215], 0, s[12:13]
	s_addc_u32 s35, s35, 0
	s_add_i32 s44, s62, s46
	global_load_lds_dwordx4 v[170:171], off
	v_lshl_add_u64 v[170:171], s[34:35], 0, v[144:145]
	s_mov_b32 m0, s44
	s_nop 0
	global_load_lds_dwordx4 v[170:171], off
	v_lshl_add_u64 v[170:171], s[34:35], 0, v[148:149]
	s_add_i32 m0, s44, 0x2000
	s_nop 0
	global_load_lds_dwordx4 v[170:171], off
	v_lshl_add_u64 v[170:171], v[222:223], 0, s[12:13]
	s_mov_b32 m0, s51
	s_nop 0
	global_load_lds_dwordx4 v[170:171], off
	v_lshl_add_u64 v[170:171], v[224:225], 0, s[12:13]
	s_mov_b32 m0, s52
	s_nop 0
	global_load_lds_dwordx4 v[170:171], off
	s_waitcnt vmcnt(8)
	s_waitcnt lgkmcnt(0)
	s_barrier
	s_setprio 1
	s_waitcnt lgkmcnt(0)
	v_mfma_f32_16x16x32_bf16 v[62:65], v[130:133], v[186:189], v[62:65]
	v_mfma_f32_16x16x32_bf16 v[58:61], v[138:141], v[186:189], v[58:61]
	v_mfma_f32_16x16x32_bf16 v[50:53], v[130:133], v[194:197], v[50:53]
	v_mfma_f32_16x16x32_bf16 v[42:45], v[138:141], v[194:197], v[42:45]
	v_mfma_f32_16x16x32_bf16 v[38:41], v[130:133], v[202:205], v[38:41]
	v_mfma_f32_16x16x32_bf16 v[34:37], v[138:141], v[202:205], v[34:37]
	v_mfma_f32_16x16x32_bf16 v[14:17], v[130:133], v[210:213], v[14:17]
	v_mfma_f32_16x16x32_bf16 v[10:13], v[138:141], v[210:213], v[10:13]
	v_mfma_f32_16x16x32_bf16 v[62:65], v[134:137], v[190:193], v[62:65]
	v_mfma_f32_16x16x32_bf16 v[58:61], v[158:161], v[190:193], v[58:61]
	v_mfma_f32_16x16x32_bf16 v[50:53], v[134:137], v[198:201], v[50:53]
	v_mfma_f32_16x16x32_bf16 v[42:45], v[158:161], v[198:201], v[42:45]
	v_mfma_f32_16x16x32_bf16 v[38:41], v[134:137], v[206:209], v[38:41]
	v_mfma_f32_16x16x32_bf16 v[34:37], v[158:161], v[206:209], v[34:37]
	v_mfma_f32_16x16x32_bf16 v[14:17], v[134:137], v[218:221], v[14:17]
	v_mfma_f32_16x16x32_bf16 v[10:13], v[158:161], v[218:221], v[10:13]
	s_setprio 0
	s_setprio 1
	v_mfma_f32_16x16x32_bf16 v[54:57], v[162:165], v[186:189], v[54:57]
	v_mfma_f32_16x16x32_bf16 v[46:49], v[178:181], v[186:189], v[46:49]
	v_mfma_f32_16x16x32_bf16 v[30:33], v[162:165], v[194:197], v[30:33]
	v_mfma_f32_16x16x32_bf16 v[26:29], v[178:181], v[194:197], v[26:29]
	v_mfma_f32_16x16x32_bf16 v[22:25], v[162:165], v[202:205], v[22:25]
	v_mfma_f32_16x16x32_bf16 v[18:21], v[178:181], v[202:205], v[18:21]
	v_mfma_f32_16x16x32_bf16 v[6:9], v[162:165], v[210:213], v[6:9]
	v_mfma_f32_16x16x32_bf16 v[2:5], v[178:181], v[210:213], v[2:5]
	v_mfma_f32_16x16x32_bf16 v[54:57], v[166:169], v[190:193], v[54:57]
	v_mfma_f32_16x16x32_bf16 v[46:49], v[182:185], v[190:193], v[46:49]
	v_mfma_f32_16x16x32_bf16 v[30:33], v[166:169], v[198:201], v[30:33]
	v_mfma_f32_16x16x32_bf16 v[26:29], v[182:185], v[198:201], v[26:29]
	v_mfma_f32_16x16x32_bf16 v[22:25], v[166:169], v[206:209], v[22:25]
	v_mfma_f32_16x16x32_bf16 v[18:21], v[182:185], v[206:209], v[18:21]
	v_mfma_f32_16x16x32_bf16 v[6:9], v[166:169], v[218:221], v[6:9]
	v_mfma_f32_16x16x32_bf16 v[2:5], v[182:185], v[218:221], v[2:5]
	s_setprio 0
	s_barrier
	s_add_i32 s60, s60, 2
	s_add_u32 s42, s42, 0x100
	s_addc_u32 s43, s43, 0
	s_add_u32 s58, s58, 0x100
	s_addc_u32 s59, s59, 0
	s_cmp_gt_u32 s60, 29
	s_cbranch_scc0 .LBB0_3706
	v_lshl_or_b32 v130, s57, 8, v173
	v_lshl_add_u32 v158, s40, 8, v1
	v_ashrrev_i32_e32 v131, 31, v130
	v_lshlrev_b64 v[160:161], 1, v[130:131]
	v_or_b32_e32 v130, 16, v158
	v_ashrrev_i32_e32 v159, 31, v158
	v_ashrrev_i32_e32 v131, 31, v130
	v_lshlrev_b64 v[132:133], 12, v[158:159]
	v_lshlrev_b64 v[130:131], 12, v[130:131]
	v_lshl_add_u64 v[132:133], s[64:65], 0, v[132:133]
	v_lshl_add_u64 v[130:131], s[64:65], 0, v[130:131]
	v_lshl_add_u64 v[170:171], v[132:133], 0, v[160:161]
	v_lshl_add_u64 v[168:169], v[130:131], 0, v[160:161]
	v_mov_b32_e32 v209, 0
	v_mov_b32_e32 v208, 0x10000
	v_lshl_add_u64 v[194:195], v[208:209], 0, v[170:171]
	v_mov_b32_e32 v208, 0x20000
	v_lshl_add_u64 v[196:197], v[208:209], 0, v[170:171]
	v_mov_b32_e32 v208, 0x30000
	v_lshl_add_u64 v[198:199], v[208:209], 0, v[170:171]
	v_mov_b32_e32 v208, 0x80000
	v_lshl_add_u64 v[200:201], v[208:209], 0, v[170:171]
	v_mov_b32_e32 v208, 0x90000
	v_lshl_add_u64 v[202:203], v[208:209], 0, v[170:171]
	v_mov_b32_e32 v208, 0xa0000
	v_lshl_add_u64 v[204:205], v[208:209], 0, v[170:171]
	v_mov_b32_e32 v208, 0xb0000
	v_lshl_add_u64 v[206:207], v[208:209], 0, v[170:171]
	global_load_dwordx4 v[130:133], v[170:171], off
	global_load_dwordx4 v[134:137], v[170:171], off offset:64
	global_load_dwordx4 v[138:141], v[194:195], off
	global_load_dwordx4 v[158:161], v[194:195], off offset:64
	global_load_dwordx4 v[162:165], v[196:197], off
	global_load_dwordx4 v[166:169], v[196:197], off offset:64
	global_load_dwordx4 v[178:181], v[198:199], off
	global_load_dwordx4 v[182:185], v[198:199], off offset:64
	s_and_b64 vcc, exec, s[14:15]
	s_cbranch_vccz .LBB0_3709
	s_barrier
